# back-edge rotation on the 5 GEMM K loops (loop-carried SALU + test moved before the loop-back barrier, barrier is loop head)
# speedup vs baseline: 1.0028x; 1.0028x over previous
; #define PG8_STAGE(bufoff, gbase, voff) do { _Pragma("unroll") for (int _i = 0; _i < 2; ++_i) \
;         __builtin_amdgcn_global_load_lds((const unsigned*)((const char*)(gbase) + (voff)[_i]), (PG8_LAS unsigned*)(lds + (bufoff) + ldsw + _i * 8192), 16, 0, 0); } while (0)
; #define PG8_LDA(dst, b, h) do { _Pragma("unroll") for (int m = 0; m < 4; ++m) _Pragma("unroll") for (int k = 0; k < 2; ++k) dst[m][k] = *(const PG8_LAS bf16x8*)(lds + PG8_SA(b, h) + aoff + m * 2048 + k * 1024); } while (0)
; #define PG8_LDB(dst, b, h) do { _Pragma("unroll") for (int n = 0; n < 2; ++n) _Pragma("unroll") for (int k = 0; k < 2; ++k) dst[n][k] = *(const PG8_LAS bf16x8*)(lds + PG8_SB(b, h) + boff + n * 2048 + k * 1024); } while (0)
; #define PG8_MMA(ai, bj, At, Bt) do { __builtin_amdgcn_s_setprio(1); _Pragma("unroll") for (int m = 0; m < 4; ++m) _Pragma("unroll") for (int n = 0; n < 2; ++n) _Pragma("unroll") for (int k = 0; k < 2; ++k) \
;         acc[ai][bj][m][n] = __builtin_amdgcn_mfma_f32_16x16x32_bf16(Bt[n][k], At[m][k], acc[ai][bj][m][n], 0, 0, 0); __builtin_amdgcn_s_setprio(0); } while (0)
; #define PG8_WAIT_V(n) asm volatile("s_waitcnt vmcnt(" #n ")" ::: "memory")
; template <class Epi, class Sched, bool ALIGN_EPI = false, bool SP2 = false>
; __device__ __forceinline__ void gemm_phase(PG8_LAS unsigned char* lds, const Gemm g, const Sched& S, const Epi& E) {
;     ...
;         const char* nA = has_next ? (const char*)g.A + (size_t)nxt.pm * tstep : cA; const char* nB = has_next ? (const char*)g.Bt + (size_t)nxt.pn * tstep : cB;
;         for (int t = 0; t < nt; t += 2) {
;             const bool last = (t == nt - 2);
;             const char* a1 = cA + (size_t)(t + 1) * kstep;
;             const char* a2 = last ? nA : cA + (size_t)(t + 2) * kstep; const char* b2 = last ? nB : cB + (size_t)(t + 2) * kstep;
;             const char* a3 = a2 + kstep; const char* b3 = b2 + kstep;
;             if (last && has_next) S.a_ready(nxt);
;             if constexpr (SP2) {
;             PG8_LDB(B0, 0, 0); PG8_LDB(B1, 0, 1); PG8_SCHED; PG8_LDA(At, 0, 0); PG8_STAGE(PG8_SA(1, 1), a1 + hstep, voffA);
;             PG8_WAIT_V(8); PG8_WAIT_L(0); PG8_BAR; PG8_MMA(0, 0, At, B0); PG8_MMA(0, 1, At, B1); PG8_BAR; PG8_SCHED;
;             PG8_LDA(At, 0, 1); PG8_STAGE(PG8_SB(0, 0), b2, voffB); PG8_STAGE(PG8_SB(0, 1), b2 + hstep, voffB); PG8_STAGE(PG8_SA(0, 0), a2, voffA);
.LBB0_204:
	s_ashr_i32 s21, s20, 31
	s_lshl_b64 s[24:25], s[20:21], 20
	v_readlane_b32 s26, v236, 50
	v_readlane_b32 s27, v236, 51
	s_add_u32 s24, s26, s24
	s_addc_u32 s25, s27, s25
	s_and_b64 s[26:27], s[8:9], exec
	s_cselect_b32 s1, s25, s5
	s_cselect_b32 s3, s24, s4
	s_ashr_i32 s23, s22, 31
	s_lshl_b64 s[26:27], s[22:23], 20
	s_add_u32 s26, s10, s26
	s_addc_u32 s27, s11, s27
	s_and_b64 s[28:29], s[8:9], exec
	s_cselect_b32 s21, s27, s7
	s_cselect_b32 s23, s26, s6
	s_add_u32 s4, s4, 0x80080
	s_addc_u32 s5, s5, 0
	s_add_u32 s33, s6, 0x100
	s_addc_u32 s50, s7, 0
	s_mov_b32 s51, -2
	s_waitcnt vmcnt(0)
	ds_read_b128 v[128:131], v190
	ds_read_b128 v[132:135], v190 offset:1024
	ds_read_b128 v[136:139], v190 offset:2048
	ds_read_b128 v[140:143], v190 offset:3072
	ds_read_b128 v[144:147], v191
	ds_read_b128 v[148:151], v191 offset:1024
	ds_read_b128 v[152:155], v191 offset:2048
	ds_read_b128 v[156:159], v191 offset:3072
	s_add_u32 s6, s4, 0xfff80080
	s_addc_u32 s7, s5, -1
	s_cmp_eq_u32 s51, 28
	s_cselect_b32 s29, s1, s7
	s_cselect_b32 s28, s3, s6
	s_cselect_b32 s7, s21, s50
	s_cselect_b32 s6, s23, s33
	v_lshl_add_u64 v[184:185], s[4:5], 0, v[172:173]
	s_add_i32 m0, s31, 0xc000
	ds_read_b128 v[180:183], v192
	ds_read_b128 v[194:197], v192 offset:1024
	ds_read_b128 v[198:201], v192 offset:2048
	ds_read_b128 v[202:205], v192 offset:3072
	ds_read_b128 v[206:209], v192 offset:4096
	ds_read_b128 v[210:213], v192 offset:5120
	ds_read_b128 v[214:217], v192 offset:6144
	ds_read_b128 v[218:221], v192 offset:7168
	global_load_lds_dwordx4 v[184:185], off
	v_lshl_add_u64 v[184:185], s[4:5], 0, v[174:175]
	s_add_i32 m0, s31, 0xe000
	s_nop 0
	global_load_lds_dwordx4 v[184:185], off
	s_waitcnt vmcnt(8)
	s_waitcnt lgkmcnt(0)
	s_barrier
	s_setprio 1
	s_waitcnt lgkmcnt(0)
	v_mfma_f32_16x16x32_bf16 v[124:127], v[128:131], v[180:183], 0
	v_mfma_f32_16x16x32_bf16 v[120:123], v[136:139], v[180:183], 0
	v_mfma_f32_16x16x32_bf16 v[108:111], v[128:131], v[198:201], 0
	v_mfma_f32_16x16x32_bf16 v[104:107], v[136:139], v[198:201], 0
	v_mfma_f32_16x16x32_bf16 v[92:95], v[128:131], v[206:209], 0
	v_mfma_f32_16x16x32_bf16 v[88:91], v[136:139], v[206:209], 0
	v_mfma_f32_16x16x32_bf16 v[76:79], v[128:131], v[214:217], 0
	v_mfma_f32_16x16x32_bf16 v[72:75], v[136:139], v[214:217], 0
	v_mfma_f32_16x16x32_bf16 v[124:127], v[132:135], v[194:197], v[124:127]
	v_mfma_f32_16x16x32_bf16 v[120:123], v[140:143], v[194:197], v[120:123]
	v_mfma_f32_16x16x32_bf16 v[108:111], v[132:135], v[202:205], v[108:111]
	v_mfma_f32_16x16x32_bf16 v[104:107], v[140:143], v[202:205], v[104:107]
	v_mfma_f32_16x16x32_bf16 v[92:95], v[132:135], v[210:213], v[92:95]
	v_mfma_f32_16x16x32_bf16 v[88:91], v[140:143], v[210:213], v[88:91]
	v_mfma_f32_16x16x32_bf16 v[76:79], v[132:135], v[218:221], v[76:79]
	v_mfma_f32_16x16x32_bf16 v[72:75], v[140:143], v[218:221], v[72:75]
	s_setprio 0
	s_setprio 1
	v_mfma_f32_16x16x32_bf16 v[116:119], v[144:147], v[180:183], 0
	v_mfma_f32_16x16x32_bf16 v[112:115], v[152:155], v[180:183], 0
	v_mfma_f32_16x16x32_bf16 v[100:103], v[144:147], v[198:201], 0
	v_mfma_f32_16x16x32_bf16 v[96:99], v[152:155], v[198:201], 0
	v_mfma_f32_16x16x32_bf16 v[84:87], v[144:147], v[206:209], 0
	v_mfma_f32_16x16x32_bf16 v[80:83], v[152:155], v[206:209], 0
	v_mfma_f32_16x16x32_bf16 v[68:71], v[144:147], v[214:217], 0
	v_mfma_f32_16x16x32_bf16 v[64:67], v[152:155], v[214:217], 0
	v_mfma_f32_16x16x32_bf16 v[116:119], v[148:151], v[194:197], v[116:119]
	v_mfma_f32_16x16x32_bf16 v[112:115], v[156:159], v[194:197], v[112:115]
	v_mfma_f32_16x16x32_bf16 v[100:103], v[148:151], v[202:205], v[100:103]
	v_mfma_f32_16x16x32_bf16 v[96:99], v[156:159], v[202:205], v[96:99]
	v_mfma_f32_16x16x32_bf16 v[84:87], v[148:151], v[210:213], v[84:87]
	v_mfma_f32_16x16x32_bf16 v[80:83], v[156:159], v[210:213], v[80:83]
	v_mfma_f32_16x16x32_bf16 v[68:71], v[148:151], v[218:221], v[68:71]
	v_mfma_f32_16x16x32_bf16 v[64:67], v[156:159], v[218:221], v[64:67]
	s_setprio 0
	s_barrier
	s_add_i32 s52, s43, s30
	v_lshl_add_u64 v[184:185], s[6:7], 0, v[164:165]
	s_mov_b32 m0, s52
	ds_read_b128 v[180:183], v192 offset:16384
	ds_read_b128 v[194:197], v192 offset:17408
	ds_read_b128 v[198:201], v192 offset:18432
	ds_read_b128 v[202:205], v192 offset:19456
	ds_read_b128 v[206:209], v192 offset:20480
	ds_read_b128 v[210:213], v192 offset:21504
	ds_read_b128 v[214:217], v192 offset:22528
	ds_read_b128 v[218:221], v192 offset:23552
	global_load_lds_dwordx4 v[184:185], off
	s_add_i32 m0, s52, 0x2000
	s_add_u32 s52, s6, 0x80000
	v_lshl_add_u64 v[222:223], s[6:7], 0, v[168:169]
	s_addc_u32 s53, s7, 0
	s_add_i32 s54, s44, s30
	global_load_lds_dwordx4 v[222:223], off
	v_lshl_add_u64 v[224:225], s[52:53], 0, v[164:165]
	s_mov_b32 m0, s54
	v_lshl_add_u64 v[226:227], s[28:29], 0, v[166:167]
	global_load_lds_dwordx4 v[224:225], off
	v_lshl_add_u64 v[224:225], s[52:53], 0, v[168:169]
	s_add_i32 m0, s54, 0x2000
	s_nop 0
	global_load_lds_dwordx4 v[224:225], off
	v_lshl_add_u64 v[224:225], s[28:29], 0, v[162:163]
	s_mov_b32 m0, s31
	s_nop 0
	global_load_lds_dwordx4 v[224:225], off
	s_mov_b32 m0, s34
	s_nop 0
	global_load_lds_dwordx4 v[226:227], off
	s_waitcnt vmcnt(8)
	s_waitcnt lgkmcnt(0)
	s_barrier
; #define PG8_STAGE(bufoff, gbase, voff) do { _Pragma("unroll") for (int _i = 0; _i < 2; ++_i) \
;         __builtin_amdgcn_global_load_lds((const unsigned*)((const char*)(gbase) + (voff)[_i]), (PG8_LAS unsigned*)(lds + (bufoff) + ldsw + _i * 8192), 16, 0, 0); } while (0)
; #define PG8_LDA(dst, b, h) do { _Pragma("unroll") for (int m = 0; m < 4; ++m) _Pragma("unroll") for (int k = 0; k < 2; ++k) dst[m][k] = *(const PG8_LAS bf16x8*)(lds + PG8_SA(b, h) + aoff + m * 2048 + k * 1024); } while (0)
; #define PG8_LDB(dst, b, h) do { _Pragma("unroll") for (int n = 0; n < 2; ++n) _Pragma("unroll") for (int k = 0; k < 2; ++k) dst[n][k] = *(const PG8_LAS bf16x8*)(lds + PG8_SB(b, h) + boff + n * 2048 + k * 1024); } while (0)
; #define PG8_MMA(ai, bj, At, Bt) do { __builtin_amdgcn_s_setprio(1); _Pragma("unroll") for (int m = 0; m < 4; ++m) _Pragma("unroll") for (int n = 0; n < 2; ++n) _Pragma("unroll") for (int k = 0; k < 2; ++k) \
;         acc[ai][bj][m][n] = __builtin_amdgcn_mfma_f32_16x16x32_bf16(Bt[n][k], At[m][k], acc[ai][bj][m][n], 0, 0, 0); __builtin_amdgcn_s_setprio(0); } while (0)
; #define PG8_WAIT_V(n) asm volatile("s_waitcnt vmcnt(" #n ")" ::: "memory")
; #define PG8_WAIT_L(n) asm volatile("s_waitcnt lgkmcnt(" #n ")" ::: "memory")
; #define PG8_BAR __builtin_amdgcn_s_barrier()
; #define PG8_SCHED __builtin_amdgcn_sched_barrier(0)
; template <class Epi, class Sched, bool ALIGN_EPI = false, bool SP2 = false>
; __device__ __forceinline__ void gemm_phase(PG8_LAS unsigned char* lds, const Gemm g, const Sched& S, const Epi& E) {
;     ...
;             PG8_WAIT_V(8); PG8_WAIT_L(0); PG8_BAR; PG8_MMA(1, 0, At, B0); PG8_MMA(1, 1, At, B1); PG8_BAR; PG8_SCHED;
;             PG8_LDB(B0, 1, 0); PG8_LDB(B1, 1, 1); PG8_SCHED; PG8_LDA(At, 1, 0); PG8_STAGE(PG8_SA(0, 1), a2 + hstep, voffA);
;             PG8_WAIT_V(8); PG8_WAIT_L(0); PG8_BAR; PG8_MMA(0, 0, At, B0); PG8_MMA(0, 1, At, B1); PG8_BAR; PG8_SCHED;
	s_setprio 1
	s_waitcnt lgkmcnt(0)
	v_mfma_f32_16x16x32_bf16 v[60:63], v[128:131], v[180:183], 0
	v_mfma_f32_16x16x32_bf16 v[56:59], v[136:139], v[180:183], 0
	v_mfma_f32_16x16x32_bf16 v[44:47], v[128:131], v[198:201], 0
	v_mfma_f32_16x16x32_bf16 v[40:43], v[136:139], v[198:201], 0
	v_mfma_f32_16x16x32_bf16 v[28:31], v[128:131], v[206:209], 0
	v_mfma_f32_16x16x32_bf16 v[24:27], v[136:139], v[206:209], 0
	v_mfma_f32_16x16x32_bf16 v[12:15], v[128:131], v[214:217], 0
	v_mfma_f32_16x16x32_bf16 v[8:11], v[136:139], v[214:217], 0
	v_mfma_f32_16x16x32_bf16 v[60:63], v[132:135], v[194:197], v[60:63]
	v_mfma_f32_16x16x32_bf16 v[56:59], v[140:143], v[194:197], v[56:59]
	v_mfma_f32_16x16x32_bf16 v[44:47], v[132:135], v[202:205], v[44:47]
	v_mfma_f32_16x16x32_bf16 v[40:43], v[140:143], v[202:205], v[40:43]
	v_mfma_f32_16x16x32_bf16 v[28:31], v[132:135], v[210:213], v[28:31]
	v_mfma_f32_16x16x32_bf16 v[24:27], v[140:143], v[210:213], v[24:27]
	v_mfma_f32_16x16x32_bf16 v[12:15], v[132:135], v[218:221], v[12:15]
	v_mfma_f32_16x16x32_bf16 v[8:11], v[140:143], v[218:221], v[8:11]
	s_setprio 0
	s_setprio 1
	v_mfma_f32_16x16x32_bf16 v[52:55], v[144:147], v[180:183], 0
	v_mfma_f32_16x16x32_bf16 v[48:51], v[152:155], v[180:183], 0
	v_mfma_f32_16x16x32_bf16 v[36:39], v[144:147], v[198:201], 0
	v_mfma_f32_16x16x32_bf16 v[32:35], v[152:155], v[198:201], 0
	v_mfma_f32_16x16x32_bf16 v[20:23], v[144:147], v[206:209], 0
	v_mfma_f32_16x16x32_bf16 v[16:19], v[152:155], v[206:209], 0
	v_mfma_f32_16x16x32_bf16 v[4:7], v[144:147], v[214:217], 0
	v_mfma_f32_16x16x32_bf16 v[0:3], v[152:155], v[214:217], 0
	v_mfma_f32_16x16x32_bf16 v[52:55], v[148:151], v[194:197], v[52:55]
	v_mfma_f32_16x16x32_bf16 v[48:51], v[156:159], v[194:197], v[48:51]
	v_mfma_f32_16x16x32_bf16 v[36:39], v[148:151], v[202:205], v[36:39]
	v_mfma_f32_16x16x32_bf16 v[32:35], v[156:159], v[202:205], v[32:35]
	v_mfma_f32_16x16x32_bf16 v[20:23], v[148:151], v[210:213], v[20:23]
	v_mfma_f32_16x16x32_bf16 v[16:19], v[156:159], v[210:213], v[16:19]
	v_mfma_f32_16x16x32_bf16 v[4:7], v[148:151], v[218:221], v[4:7]
	v_mfma_f32_16x16x32_bf16 v[0:3], v[156:159], v[218:221], v[0:3]
	s_setprio 0
	s_barrier
	s_add_i32 s52, 0, 0x18000
	s_add_i32 s53, 0, 0x1c000
	v_add_u32_e32 v140, s52, v188
	v_add_u32_e32 v156, s53, v188
	ds_read_b128 v[128:131], v140
	ds_read_b128 v[132:135], v140 offset:1024
	ds_read_b128 v[136:139], v140 offset:2048
	ds_read_b128 v[140:143], v140 offset:3072
	ds_read_b128 v[144:147], v156
	ds_read_b128 v[148:151], v156 offset:1024
	ds_read_b128 v[152:155], v156 offset:2048
	ds_read_b128 v[156:159], v156 offset:3072
	s_add_u32 s28, s28, 0x80000
	s_addc_u32 s29, s29, 0
	s_mov_b32 m0, s35
	v_lshl_add_u64 v[228:229], s[28:29], 0, v[162:163]
	ds_read_b128 v[180:183], v192 offset:32768
	ds_read_b128 v[194:197], v192 offset:33792
	ds_read_b128 v[198:201], v192 offset:34816
	ds_read_b128 v[202:205], v192 offset:35840
	ds_read_b128 v[206:209], v192 offset:36864
	ds_read_b128 v[210:213], v192 offset:37888
	ds_read_b128 v[214:217], v192 offset:38912
	ds_read_b128 v[218:221], v192 offset:39936
	global_load_lds_dwordx4 v[228:229], off
	v_lshl_add_u64 v[228:229], s[28:29], 0, v[166:167]
	s_mov_b32 m0, s36
	s_nop 0
	global_load_lds_dwordx4 v[228:229], off
	s_waitcnt vmcnt(8)
	s_waitcnt lgkmcnt(0)
	s_barrier
	s_setprio 1
	s_waitcnt lgkmcnt(0)
	v_mfma_f32_16x16x32_bf16 v[124:127], v[128:131], v[180:183], v[124:127]
	v_mfma_f32_16x16x32_bf16 v[120:123], v[136:139], v[180:183], v[120:123]
	v_mfma_f32_16x16x32_bf16 v[108:111], v[128:131], v[198:201], v[108:111]
	v_mfma_f32_16x16x32_bf16 v[104:107], v[136:139], v[198:201], v[104:107]
	v_mfma_f32_16x16x32_bf16 v[92:95], v[128:131], v[206:209], v[92:95]
	v_mfma_f32_16x16x32_bf16 v[88:91], v[136:139], v[206:209], v[88:91]
	v_mfma_f32_16x16x32_bf16 v[76:79], v[128:131], v[214:217], v[76:79]
	v_mfma_f32_16x16x32_bf16 v[72:75], v[136:139], v[214:217], v[72:75]
	v_mfma_f32_16x16x32_bf16 v[124:127], v[132:135], v[194:197], v[124:127]
	v_mfma_f32_16x16x32_bf16 v[120:123], v[140:143], v[194:197], v[120:123]
	v_mfma_f32_16x16x32_bf16 v[108:111], v[132:135], v[202:205], v[108:111]
	v_mfma_f32_16x16x32_bf16 v[104:107], v[140:143], v[202:205], v[104:107]
	v_mfma_f32_16x16x32_bf16 v[92:95], v[132:135], v[210:213], v[92:95]
	v_mfma_f32_16x16x32_bf16 v[88:91], v[140:143], v[210:213], v[88:91]
	v_mfma_f32_16x16x32_bf16 v[76:79], v[132:135], v[218:221], v[76:79]
	v_mfma_f32_16x16x32_bf16 v[72:75], v[140:143], v[218:221], v[72:75]
	s_setprio 0
	s_setprio 1
	v_mfma_f32_16x16x32_bf16 v[116:119], v[144:147], v[180:183], v[116:119]
	v_mfma_f32_16x16x32_bf16 v[112:115], v[152:155], v[180:183], v[112:115]
	v_mfma_f32_16x16x32_bf16 v[100:103], v[144:147], v[198:201], v[100:103]
	v_mfma_f32_16x16x32_bf16 v[96:99], v[152:155], v[198:201], v[96:99]
	v_mfma_f32_16x16x32_bf16 v[84:87], v[144:147], v[206:209], v[84:87]
	v_mfma_f32_16x16x32_bf16 v[80:83], v[152:155], v[206:209], v[80:83]
	v_mfma_f32_16x16x32_bf16 v[68:71], v[144:147], v[214:217], v[68:71]
	v_mfma_f32_16x16x32_bf16 v[64:67], v[152:155], v[214:217], v[64:67]
	v_mfma_f32_16x16x32_bf16 v[116:119], v[148:151], v[194:197], v[116:119]
	v_mfma_f32_16x16x32_bf16 v[112:115], v[156:159], v[194:197], v[112:115]
	v_mfma_f32_16x16x32_bf16 v[100:103], v[148:151], v[202:205], v[100:103]
	v_mfma_f32_16x16x32_bf16 v[96:99], v[156:159], v[202:205], v[96:99]
	v_mfma_f32_16x16x32_bf16 v[84:87], v[148:151], v[210:213], v[84:87]
	v_mfma_f32_16x16x32_bf16 v[80:83], v[156:159], v[210:213], v[80:83]
	v_mfma_f32_16x16x32_bf16 v[68:71], v[148:151], v[218:221], v[68:71]
	v_mfma_f32_16x16x32_bf16 v[64:67], v[156:159], v[218:221], v[64:67]
	s_setprio 0
	s_barrier
; #define PG8_STAGE(bufoff, gbase, voff) do { _Pragma("unroll") for (int _i = 0; _i < 2; ++_i) \
;         __builtin_amdgcn_global_load_lds((const unsigned*)((const char*)(gbase) + (voff)[_i]), (PG8_LAS unsigned*)(lds + (bufoff) + ldsw + _i * 8192), 16, 0, 0); } while (0)
; #define PG8_LDA(dst, b, h) do { _Pragma("unroll") for (int m = 0; m < 4; ++m) _Pragma("unroll") for (int k = 0; k < 2; ++k) dst[m][k] = *(const PG8_LAS bf16x8*)(lds + PG8_SA(b, h) + aoff + m * 2048 + k * 1024); } while (0)
; #define PG8_MMA(ai, bj, At, Bt) do { __builtin_amdgcn_s_setprio(1); _Pragma("unroll") for (int m = 0; m < 4; ++m) _Pragma("unroll") for (int n = 0; n < 2; ++n) _Pragma("unroll") for (int k = 0; k < 2; ++k) \
;         acc[ai][bj][m][n] = __builtin_amdgcn_mfma_f32_16x16x32_bf16(Bt[n][k], At[m][k], acc[ai][bj][m][n], 0, 0, 0); __builtin_amdgcn_s_setprio(0); } while (0)
; #define PG8_WAIT_V(n) asm volatile("s_waitcnt vmcnt(" #n ")" ::: "memory")
; #define PG8_WAIT_L(n) asm volatile("s_waitcnt lgkmcnt(" #n ")" ::: "memory")
; #define PG8_BAR __builtin_amdgcn_s_barrier()
; #define PG8_SCHED __builtin_amdgcn_sched_barrier(0)
; template <class Epi, class Sched, bool ALIGN_EPI = false, bool SP2 = false>
; __device__ __forceinline__ void gemm_phase(PG8_LAS unsigned char* lds, const Gemm g, const Sched& S, const Epi& E) {
;     ...
;         for (int t = 0; t < nt; t += 2) {
;             const bool last = (t == nt - 2);
;             const char* a1 = cA + (size_t)(t + 1) * kstep;
;             const char* a2 = last ? nA : cA + (size_t)(t + 2) * kstep; const char* b2 = last ? nB : cB + (size_t)(t + 2) * kstep;
;     ...
;             PG8_LDA(At, 1, 1); PG8_STAGE(PG8_SB(1, 0), b3, voffB); PG8_STAGE(PG8_SB(1, 1), b3 + hstep, voffB); PG8_STAGE(PG8_SA(1, 0), a3, voffA);
;             PG8_WAIT_V(8); PG8_WAIT_L(0); PG8_BAR; PG8_MMA(1, 0, At, B0); PG8_MMA(1, 1, At, B1); PG8_BAR; PG8_SCHED;
	s_add_i32 s28, s52, s30
	v_lshl_add_u64 v[184:185], v[184:185], 0, s[16:17]
	s_mov_b32 m0, s28
	ds_read_b128 v[180:183], v192 offset:49152
	ds_read_b128 v[194:197], v192 offset:50176
	ds_read_b128 v[198:201], v192 offset:51200
	ds_read_b128 v[202:205], v192 offset:52224
	ds_read_b128 v[206:209], v192 offset:53248
	ds_read_b128 v[210:213], v192 offset:54272
	ds_read_b128 v[214:217], v192 offset:55296
	ds_read_b128 v[218:221], v192 offset:56320
	global_load_lds_dwordx4 v[184:185], off
	s_add_i32 m0, s28, 0x2000
	s_add_u32 s6, s6, 0x80080
	v_lshl_add_u64 v[184:185], v[222:223], 0, s[16:17]
	s_addc_u32 s7, s7, 0
	s_add_i32 s28, s53, s30
	global_load_lds_dwordx4 v[184:185], off
	v_lshl_add_u64 v[184:185], s[6:7], 0, v[164:165]
	s_mov_b32 m0, s28
	s_nop 0
	global_load_lds_dwordx4 v[184:185], off
	v_lshl_add_u64 v[184:185], s[6:7], 0, v[168:169]
	s_add_i32 m0, s28, 0x2000
	s_nop 0
	global_load_lds_dwordx4 v[184:185], off
	v_lshl_add_u64 v[184:185], v[224:225], 0, s[16:17]
	s_mov_b32 m0, s38
	s_nop 0
	global_load_lds_dwordx4 v[184:185], off
	v_lshl_add_u64 v[184:185], v[226:227], 0, s[16:17]
	s_mov_b32 m0, s39
	s_nop 0
	global_load_lds_dwordx4 v[184:185], off
	s_waitcnt vmcnt(8)
	s_waitcnt lgkmcnt(0)
	s_barrier
	s_setprio 1
	s_waitcnt lgkmcnt(0)
	v_mfma_f32_16x16x32_bf16 v[60:63], v[128:131], v[180:183], v[60:63]
	v_mfma_f32_16x16x32_bf16 v[56:59], v[136:139], v[180:183], v[56:59]
	v_mfma_f32_16x16x32_bf16 v[44:47], v[128:131], v[198:201], v[44:47]
	v_mfma_f32_16x16x32_bf16 v[40:43], v[136:139], v[198:201], v[40:43]
	v_mfma_f32_16x16x32_bf16 v[28:31], v[128:131], v[206:209], v[28:31]
	v_mfma_f32_16x16x32_bf16 v[24:27], v[136:139], v[206:209], v[24:27]
	v_mfma_f32_16x16x32_bf16 v[12:15], v[128:131], v[214:217], v[12:15]
	v_mfma_f32_16x16x32_bf16 v[8:11], v[136:139], v[214:217], v[8:11]
	v_mfma_f32_16x16x32_bf16 v[60:63], v[132:135], v[194:197], v[60:63]
	v_mfma_f32_16x16x32_bf16 v[56:59], v[140:143], v[194:197], v[56:59]
	v_mfma_f32_16x16x32_bf16 v[44:47], v[132:135], v[202:205], v[44:47]
	v_mfma_f32_16x16x32_bf16 v[40:43], v[140:143], v[202:205], v[40:43]
	v_mfma_f32_16x16x32_bf16 v[28:31], v[132:135], v[210:213], v[28:31]
	v_mfma_f32_16x16x32_bf16 v[24:27], v[140:143], v[210:213], v[24:27]
	v_mfma_f32_16x16x32_bf16 v[12:15], v[132:135], v[218:221], v[12:15]
	v_mfma_f32_16x16x32_bf16 v[8:11], v[140:143], v[218:221], v[8:11]
	s_setprio 0
	s_setprio 1
	v_mfma_f32_16x16x32_bf16 v[52:55], v[144:147], v[180:183], v[52:55]
	v_mfma_f32_16x16x32_bf16 v[48:51], v[152:155], v[180:183], v[48:51]
	v_mfma_f32_16x16x32_bf16 v[36:39], v[144:147], v[198:201], v[36:39]
	v_mfma_f32_16x16x32_bf16 v[32:35], v[152:155], v[198:201], v[32:35]
	v_mfma_f32_16x16x32_bf16 v[20:23], v[144:147], v[206:209], v[20:23]
	v_mfma_f32_16x16x32_bf16 v[16:19], v[152:155], v[206:209], v[16:19]
	v_mfma_f32_16x16x32_bf16 v[4:7], v[144:147], v[214:217], v[4:7]
	v_mfma_f32_16x16x32_bf16 v[0:3], v[152:155], v[214:217], v[0:3]
	v_mfma_f32_16x16x32_bf16 v[52:55], v[148:151], v[194:197], v[52:55]
	v_mfma_f32_16x16x32_bf16 v[48:51], v[156:159], v[194:197], v[48:51]
	v_mfma_f32_16x16x32_bf16 v[36:39], v[148:151], v[202:205], v[36:39]
	v_mfma_f32_16x16x32_bf16 v[32:35], v[156:159], v[202:205], v[32:35]
	v_mfma_f32_16x16x32_bf16 v[20:23], v[148:151], v[210:213], v[20:23]
	v_mfma_f32_16x16x32_bf16 v[16:19], v[156:159], v[210:213], v[16:19]
	v_mfma_f32_16x16x32_bf16 v[4:7], v[148:151], v[218:221], v[4:7]
	v_mfma_f32_16x16x32_bf16 v[0:3], v[156:159], v[218:221], v[0:3]
	s_setprio 0
	s_add_i32 s51, s51, 2
	s_add_u32 s4, s4, 0x100
	s_addc_u32 s5, s5, 0
	s_add_u32 s33, s33, 0x100
	s_addc_u32 s50, s50, 0
	s_cmp_gt_u32 s51, 29

; #define PG8_STAGE(bufoff, gbase, voff) do { _Pragma("unroll") for (int _i = 0; _i < 2; ++_i) \
;         __builtin_amdgcn_global_load_lds((const unsigned*)((const char*)(gbase) + (voff)[_i]), (PG8_LAS unsigned*)(lds + (bufoff) + ldsw + _i * 8192), 16, 0, 0); } while (0)
; #define PG8_LDA(dst, b, h) do { _Pragma("unroll") for (int m = 0; m < 4; ++m) _Pragma("unroll") for (int k = 0; k < 2; ++k) dst[m][k] = *(const PG8_LAS bf16x8*)(lds + PG8_SA(b, h) + aoff + m * 2048 + k * 1024); } while (0)
; #define PG8_LDB(dst, b, h) do { _Pragma("unroll") for (int n = 0; n < 2; ++n) _Pragma("unroll") for (int k = 0; k < 2; ++k) dst[n][k] = *(const PG8_LAS bf16x8*)(lds + PG8_SB(b, h) + boff + n * 2048 + k * 1024); } while (0)
; #define PG8_MMA(ai, bj, At, Bt) do { __builtin_amdgcn_s_setprio(1); _Pragma("unroll") for (int m = 0; m < 4; ++m) _Pragma("unroll") for (int n = 0; n < 2; ++n) _Pragma("unroll") for (int k = 0; k < 2; ++k) \
;         acc[ai][bj][m][n] = __builtin_amdgcn_mfma_f32_16x16x32_bf16(Bt[n][k], At[m][k], acc[ai][bj][m][n], 0, 0, 0); __builtin_amdgcn_s_setprio(0); } while (0)
; #define PG8_WAIT_V(n) asm volatile("s_waitcnt vmcnt(" #n ")" ::: "memory")
; #define PG8_BAR __builtin_amdgcn_s_barrier()
; template <class Epi, class Sched, bool ALIGN_EPI = false, bool SP2 = false>
; __device__ __forceinline__ void gemm_phase(PG8_LAS unsigned char* lds, const Gemm g, const Sched& S, const Epi& E) {
;     ...
;         for (int t = 0; t < nt; t += 2) {
;             const bool last = (t == nt - 2);
;             const char* a1 = cA + (size_t)(t + 1) * kstep;
;             const char* a2 = last ? nA : cA + (size_t)(t + 2) * kstep; const char* b2 = last ? nB : cB + (size_t)(t + 2) * kstep;
;             const char* a3 = a2 + kstep; const char* b3 = b2 + kstep;
;             if (last && has_next) S.a_ready(nxt);
;             if constexpr (SP2) {
;             PG8_LDB(B0, 0, 0); PG8_LDB(B1, 0, 1); PG8_SCHED; PG8_LDA(At, 0, 0); PG8_STAGE(PG8_SA(1, 1), a1 + hstep, voffA);
;             PG8_WAIT_V(8); PG8_WAIT_L(0); PG8_BAR; PG8_MMA(0, 0, At, B0); PG8_MMA(0, 1, At, B1); PG8_BAR; PG8_SCHED;
;             PG8_LDA(At, 0, 1); PG8_STAGE(PG8_SB(0, 0), b2, voffB); PG8_STAGE(PG8_SB(0, 1), b2 + hstep, voffB); PG8_STAGE(PG8_SA(0, 0), a2, voffA);
;             PG8_WAIT_V(8); PG8_WAIT_L(0); PG8_BAR; PG8_MMA(1, 0, At, B0); PG8_MMA(1, 1, At, B1); PG8_BAR; PG8_SCHED;
.LBB0_205:
	ds_read_b128 v[128:131], v190
	ds_read_b128 v[132:135], v190 offset:1024
	ds_read_b128 v[136:139], v190 offset:2048
	ds_read_b128 v[140:143], v190 offset:3072
	ds_read_b128 v[144:147], v191
	ds_read_b128 v[148:151], v191 offset:1024
	ds_read_b128 v[152:155], v191 offset:2048
	ds_read_b128 v[156:159], v191 offset:3072
	s_add_u32 s6, s4, 0xfff80080
	s_addc_u32 s7, s5, -1
	s_cmp_eq_u32 s51, 28
	s_cselect_b32 s29, s1, s7
	s_cselect_b32 s28, s3, s6
	s_cselect_b32 s7, s21, s50
	s_cselect_b32 s6, s23, s33
	v_lshl_add_u64 v[184:185], s[4:5], 0, v[172:173]
	s_add_i32 m0, s31, 0xc000
	ds_read_b128 v[180:183], v192
	ds_read_b128 v[194:197], v192 offset:1024
	ds_read_b128 v[198:201], v192 offset:2048
	ds_read_b128 v[202:205], v192 offset:3072
	ds_read_b128 v[206:209], v192 offset:4096
	ds_read_b128 v[210:213], v192 offset:5120
	ds_read_b128 v[214:217], v192 offset:6144
	ds_read_b128 v[218:221], v192 offset:7168
	global_load_lds_dwordx4 v[184:185], off
	v_lshl_add_u64 v[184:185], s[4:5], 0, v[174:175]
	s_add_i32 m0, s31, 0xe000
	s_nop 0
	global_load_lds_dwordx4 v[184:185], off
	s_waitcnt vmcnt(8)
	s_waitcnt lgkmcnt(0)
	s_barrier
	s_setprio 1
	s_waitcnt lgkmcnt(0)
	v_mfma_f32_16x16x32_bf16 v[124:127], v[128:131], v[180:183], v[124:127]
	v_mfma_f32_16x16x32_bf16 v[120:123], v[136:139], v[180:183], v[120:123]
	v_mfma_f32_16x16x32_bf16 v[108:111], v[128:131], v[198:201], v[108:111]
	v_mfma_f32_16x16x32_bf16 v[104:107], v[136:139], v[198:201], v[104:107]
	v_mfma_f32_16x16x32_bf16 v[92:95], v[128:131], v[206:209], v[92:95]
	v_mfma_f32_16x16x32_bf16 v[88:91], v[136:139], v[206:209], v[88:91]
	v_mfma_f32_16x16x32_bf16 v[76:79], v[128:131], v[214:217], v[76:79]
	v_mfma_f32_16x16x32_bf16 v[72:75], v[136:139], v[214:217], v[72:75]
	v_mfma_f32_16x16x32_bf16 v[124:127], v[132:135], v[194:197], v[124:127]
	v_mfma_f32_16x16x32_bf16 v[120:123], v[140:143], v[194:197], v[120:123]
	v_mfma_f32_16x16x32_bf16 v[108:111], v[132:135], v[202:205], v[108:111]
	v_mfma_f32_16x16x32_bf16 v[104:107], v[140:143], v[202:205], v[104:107]
	v_mfma_f32_16x16x32_bf16 v[92:95], v[132:135], v[210:213], v[92:95]
	v_mfma_f32_16x16x32_bf16 v[88:91], v[140:143], v[210:213], v[88:91]
	v_mfma_f32_16x16x32_bf16 v[76:79], v[132:135], v[218:221], v[76:79]
	v_mfma_f32_16x16x32_bf16 v[72:75], v[140:143], v[218:221], v[72:75]
	s_setprio 0
	s_setprio 1
	v_mfma_f32_16x16x32_bf16 v[116:119], v[144:147], v[180:183], v[116:119]
	v_mfma_f32_16x16x32_bf16 v[112:115], v[152:155], v[180:183], v[112:115]
	v_mfma_f32_16x16x32_bf16 v[100:103], v[144:147], v[198:201], v[100:103]
	v_mfma_f32_16x16x32_bf16 v[96:99], v[152:155], v[198:201], v[96:99]
	v_mfma_f32_16x16x32_bf16 v[84:87], v[144:147], v[206:209], v[84:87]
	v_mfma_f32_16x16x32_bf16 v[80:83], v[152:155], v[206:209], v[80:83]
	v_mfma_f32_16x16x32_bf16 v[68:71], v[144:147], v[214:217], v[68:71]
	v_mfma_f32_16x16x32_bf16 v[64:67], v[152:155], v[214:217], v[64:67]
	v_mfma_f32_16x16x32_bf16 v[116:119], v[148:151], v[194:197], v[116:119]
	v_mfma_f32_16x16x32_bf16 v[112:115], v[156:159], v[194:197], v[112:115]
	v_mfma_f32_16x16x32_bf16 v[100:103], v[148:151], v[202:205], v[100:103]
	v_mfma_f32_16x16x32_bf16 v[96:99], v[156:159], v[202:205], v[96:99]
	v_mfma_f32_16x16x32_bf16 v[84:87], v[148:151], v[210:213], v[84:87]
	v_mfma_f32_16x16x32_bf16 v[80:83], v[156:159], v[210:213], v[80:83]
	v_mfma_f32_16x16x32_bf16 v[68:71], v[148:151], v[218:221], v[68:71]
	v_mfma_f32_16x16x32_bf16 v[64:67], v[156:159], v[218:221], v[64:67]
	s_setprio 0
	s_barrier
	s_add_i32 s52, s43, s30
	v_lshl_add_u64 v[184:185], s[6:7], 0, v[164:165]
	s_mov_b32 m0, s52
	ds_read_b128 v[180:183], v192 offset:16384
	ds_read_b128 v[194:197], v192 offset:17408
	ds_read_b128 v[198:201], v192 offset:18432
	ds_read_b128 v[202:205], v192 offset:19456
	ds_read_b128 v[206:209], v192 offset:20480
	ds_read_b128 v[210:213], v192 offset:21504
	ds_read_b128 v[214:217], v192 offset:22528
	ds_read_b128 v[218:221], v192 offset:23552
	global_load_lds_dwordx4 v[184:185], off
	s_add_i32 m0, s52, 0x2000
	s_add_u32 s52, s6, 0x80000
	v_lshl_add_u64 v[222:223], s[6:7], 0, v[168:169]
	s_addc_u32 s53, s7, 0
	s_add_i32 s54, s44, s30
	global_load_lds_dwordx4 v[222:223], off
	v_lshl_add_u64 v[224:225], s[52:53], 0, v[164:165]
	s_mov_b32 m0, s54
	v_lshl_add_u64 v[226:227], s[28:29], 0, v[166:167]
	global_load_lds_dwordx4 v[224:225], off
	v_lshl_add_u64 v[224:225], s[52:53], 0, v[168:169]
	s_add_i32 m0, s54, 0x2000
	s_nop 0
	global_load_lds_dwordx4 v[224:225], off
	v_lshl_add_u64 v[224:225], s[28:29], 0, v[162:163]
	s_mov_b32 m0, s31
	s_nop 0
	global_load_lds_dwordx4 v[224:225], off
	s_mov_b32 m0, s34
	s_nop 0
	global_load_lds_dwordx4 v[226:227], off
	s_waitcnt vmcnt(8)
	s_waitcnt lgkmcnt(0)
	s_barrier
; #define PG8_STAGE(bufoff, gbase, voff) do { _Pragma("unroll") for (int _i = 0; _i < 2; ++_i) \
;         __builtin_amdgcn_global_load_lds((const unsigned*)((const char*)(gbase) + (voff)[_i]), (PG8_LAS unsigned*)(lds + (bufoff) + ldsw + _i * 8192), 16, 0, 0); } while (0)
; #define PG8_LDA(dst, b, h) do { _Pragma("unroll") for (int m = 0; m < 4; ++m) _Pragma("unroll") for (int k = 0; k < 2; ++k) dst[m][k] = *(const PG8_LAS bf16x8*)(lds + PG8_SA(b, h) + aoff + m * 2048 + k * 1024); } while (0)
; #define PG8_LDB(dst, b, h) do { _Pragma("unroll") for (int n = 0; n < 2; ++n) _Pragma("unroll") for (int k = 0; k < 2; ++k) dst[n][k] = *(const PG8_LAS bf16x8*)(lds + PG8_SB(b, h) + boff + n * 2048 + k * 1024); } while (0)
; #define PG8_MMA(ai, bj, At, Bt) do { __builtin_amdgcn_s_setprio(1); _Pragma("unroll") for (int m = 0; m < 4; ++m) _Pragma("unroll") for (int n = 0; n < 2; ++n) _Pragma("unroll") for (int k = 0; k < 2; ++k) \
;         acc[ai][bj][m][n] = __builtin_amdgcn_mfma_f32_16x16x32_bf16(Bt[n][k], At[m][k], acc[ai][bj][m][n], 0, 0, 0); __builtin_amdgcn_s_setprio(0); } while (0)
; #define PG8_WAIT_V(n) asm volatile("s_waitcnt vmcnt(" #n ")" ::: "memory")
; #define PG8_WAIT_L(n) asm volatile("s_waitcnt lgkmcnt(" #n ")" ::: "memory")
; #define PG8_BAR __builtin_amdgcn_s_barrier()
; #define PG8_SCHED __builtin_amdgcn_sched_barrier(0)
; template <class Epi, class Sched, bool ALIGN_EPI = false, bool SP2 = false>
; __device__ __forceinline__ void gemm_phase(PG8_LAS unsigned char* lds, const Gemm g, const Sched& S, const Epi& E) {
;     ...
;             PG8_WAIT_V(8); PG8_WAIT_L(0); PG8_BAR; PG8_MMA(1, 0, At, B0); PG8_MMA(1, 1, At, B1); PG8_BAR; PG8_SCHED;
;             PG8_LDB(B0, 1, 0); PG8_LDB(B1, 1, 1); PG8_SCHED; PG8_LDA(At, 1, 0); PG8_STAGE(PG8_SA(0, 1), a2 + hstep, voffA);
;             PG8_WAIT_V(8); PG8_WAIT_L(0); PG8_BAR; PG8_MMA(0, 0, At, B0); PG8_MMA(0, 1, At, B1); PG8_BAR; PG8_SCHED;
	s_setprio 1
	s_waitcnt lgkmcnt(0)
	v_mfma_f32_16x16x32_bf16 v[60:63], v[128:131], v[180:183], v[60:63]
	v_mfma_f32_16x16x32_bf16 v[56:59], v[136:139], v[180:183], v[56:59]
	v_mfma_f32_16x16x32_bf16 v[44:47], v[128:131], v[198:201], v[44:47]
	v_mfma_f32_16x16x32_bf16 v[40:43], v[136:139], v[198:201], v[40:43]
	v_mfma_f32_16x16x32_bf16 v[28:31], v[128:131], v[206:209], v[28:31]
	v_mfma_f32_16x16x32_bf16 v[24:27], v[136:139], v[206:209], v[24:27]
	v_mfma_f32_16x16x32_bf16 v[12:15], v[128:131], v[214:217], v[12:15]
	v_mfma_f32_16x16x32_bf16 v[8:11], v[136:139], v[214:217], v[8:11]
	v_mfma_f32_16x16x32_bf16 v[60:63], v[132:135], v[194:197], v[60:63]
	v_mfma_f32_16x16x32_bf16 v[56:59], v[140:143], v[194:197], v[56:59]
	v_mfma_f32_16x16x32_bf16 v[44:47], v[132:135], v[202:205], v[44:47]
	v_mfma_f32_16x16x32_bf16 v[40:43], v[140:143], v[202:205], v[40:43]
	v_mfma_f32_16x16x32_bf16 v[28:31], v[132:135], v[210:213], v[28:31]
	v_mfma_f32_16x16x32_bf16 v[24:27], v[140:143], v[210:213], v[24:27]
	v_mfma_f32_16x16x32_bf16 v[12:15], v[132:135], v[218:221], v[12:15]
	v_mfma_f32_16x16x32_bf16 v[8:11], v[140:143], v[218:221], v[8:11]
	s_setprio 0
	s_setprio 1
	v_mfma_f32_16x16x32_bf16 v[52:55], v[144:147], v[180:183], v[52:55]
	v_mfma_f32_16x16x32_bf16 v[48:51], v[152:155], v[180:183], v[48:51]
	v_mfma_f32_16x16x32_bf16 v[36:39], v[144:147], v[198:201], v[36:39]
	v_mfma_f32_16x16x32_bf16 v[32:35], v[152:155], v[198:201], v[32:35]
	v_mfma_f32_16x16x32_bf16 v[20:23], v[144:147], v[206:209], v[20:23]
	v_mfma_f32_16x16x32_bf16 v[16:19], v[152:155], v[206:209], v[16:19]
	v_mfma_f32_16x16x32_bf16 v[4:7], v[144:147], v[214:217], v[4:7]
	v_mfma_f32_16x16x32_bf16 v[0:3], v[152:155], v[214:217], v[0:3]
	v_mfma_f32_16x16x32_bf16 v[52:55], v[148:151], v[194:197], v[52:55]
	v_mfma_f32_16x16x32_bf16 v[48:51], v[156:159], v[194:197], v[48:51]
	v_mfma_f32_16x16x32_bf16 v[36:39], v[148:151], v[202:205], v[36:39]
	v_mfma_f32_16x16x32_bf16 v[32:35], v[156:159], v[202:205], v[32:35]
	v_mfma_f32_16x16x32_bf16 v[20:23], v[148:151], v[210:213], v[20:23]
	v_mfma_f32_16x16x32_bf16 v[16:19], v[156:159], v[210:213], v[16:19]
	v_mfma_f32_16x16x32_bf16 v[4:7], v[148:151], v[218:221], v[4:7]
	v_mfma_f32_16x16x32_bf16 v[0:3], v[156:159], v[218:221], v[0:3]
	s_setprio 0
	s_barrier
	s_add_i32 s52, 0, 0x18000
	s_add_i32 s53, 0, 0x1c000
	v_add_u32_e32 v140, s52, v188
	v_add_u32_e32 v156, s53, v188
	ds_read_b128 v[128:131], v140
	ds_read_b128 v[132:135], v140 offset:1024
	ds_read_b128 v[136:139], v140 offset:2048
	ds_read_b128 v[140:143], v140 offset:3072
	ds_read_b128 v[144:147], v156
	ds_read_b128 v[148:151], v156 offset:1024
	ds_read_b128 v[152:155], v156 offset:2048
	ds_read_b128 v[156:159], v156 offset:3072
	s_add_u32 s28, s28, 0x80000
	s_addc_u32 s29, s29, 0
	s_mov_b32 m0, s35
	v_lshl_add_u64 v[228:229], s[28:29], 0, v[162:163]
	ds_read_b128 v[180:183], v192 offset:32768
	ds_read_b128 v[194:197], v192 offset:33792
	ds_read_b128 v[198:201], v192 offset:34816
	ds_read_b128 v[202:205], v192 offset:35840
	ds_read_b128 v[206:209], v192 offset:36864
	ds_read_b128 v[210:213], v192 offset:37888
	ds_read_b128 v[214:217], v192 offset:38912
	ds_read_b128 v[218:221], v192 offset:39936
	global_load_lds_dwordx4 v[228:229], off
	v_lshl_add_u64 v[228:229], s[28:29], 0, v[166:167]
	s_mov_b32 m0, s36
	s_nop 0
	global_load_lds_dwordx4 v[228:229], off
	s_waitcnt vmcnt(8)
	s_waitcnt lgkmcnt(0)
	s_barrier
	s_setprio 1
	s_waitcnt lgkmcnt(0)
	v_mfma_f32_16x16x32_bf16 v[124:127], v[128:131], v[180:183], v[124:127]
	v_mfma_f32_16x16x32_bf16 v[120:123], v[136:139], v[180:183], v[120:123]
	v_mfma_f32_16x16x32_bf16 v[108:111], v[128:131], v[198:201], v[108:111]
	v_mfma_f32_16x16x32_bf16 v[104:107], v[136:139], v[198:201], v[104:107]
	v_mfma_f32_16x16x32_bf16 v[92:95], v[128:131], v[206:209], v[92:95]
	v_mfma_f32_16x16x32_bf16 v[88:91], v[136:139], v[206:209], v[88:91]
	v_mfma_f32_16x16x32_bf16 v[76:79], v[128:131], v[214:217], v[76:79]
	v_mfma_f32_16x16x32_bf16 v[72:75], v[136:139], v[214:217], v[72:75]
	v_mfma_f32_16x16x32_bf16 v[124:127], v[132:135], v[194:197], v[124:127]
	v_mfma_f32_16x16x32_bf16 v[120:123], v[140:143], v[194:197], v[120:123]
	v_mfma_f32_16x16x32_bf16 v[108:111], v[132:135], v[202:205], v[108:111]
	v_mfma_f32_16x16x32_bf16 v[104:107], v[140:143], v[202:205], v[104:107]
	v_mfma_f32_16x16x32_bf16 v[92:95], v[132:135], v[210:213], v[92:95]
	v_mfma_f32_16x16x32_bf16 v[88:91], v[140:143], v[210:213], v[88:91]
	v_mfma_f32_16x16x32_bf16 v[76:79], v[132:135], v[218:221], v[76:79]
	v_mfma_f32_16x16x32_bf16 v[72:75], v[140:143], v[218:221], v[72:75]
	s_setprio 0
	s_setprio 1
	v_mfma_f32_16x16x32_bf16 v[116:119], v[144:147], v[180:183], v[116:119]
	v_mfma_f32_16x16x32_bf16 v[112:115], v[152:155], v[180:183], v[112:115]
	v_mfma_f32_16x16x32_bf16 v[100:103], v[144:147], v[198:201], v[100:103]
	v_mfma_f32_16x16x32_bf16 v[96:99], v[152:155], v[198:201], v[96:99]
	v_mfma_f32_16x16x32_bf16 v[84:87], v[144:147], v[206:209], v[84:87]
	v_mfma_f32_16x16x32_bf16 v[80:83], v[152:155], v[206:209], v[80:83]
	v_mfma_f32_16x16x32_bf16 v[68:71], v[144:147], v[214:217], v[68:71]
	v_mfma_f32_16x16x32_bf16 v[64:67], v[152:155], v[214:217], v[64:67]
	v_mfma_f32_16x16x32_bf16 v[116:119], v[148:151], v[194:197], v[116:119]
	v_mfma_f32_16x16x32_bf16 v[112:115], v[156:159], v[194:197], v[112:115]
	v_mfma_f32_16x16x32_bf16 v[100:103], v[148:151], v[202:205], v[100:103]
	v_mfma_f32_16x16x32_bf16 v[96:99], v[156:159], v[202:205], v[96:99]
	v_mfma_f32_16x16x32_bf16 v[84:87], v[148:151], v[210:213], v[84:87]
	v_mfma_f32_16x16x32_bf16 v[80:83], v[156:159], v[210:213], v[80:83]
	v_mfma_f32_16x16x32_bf16 v[68:71], v[148:151], v[218:221], v[68:71]
	v_mfma_f32_16x16x32_bf16 v[64:67], v[156:159], v[218:221], v[64:67]
	s_setprio 0
	s_barrier
; #define PG8_STAGE(bufoff, gbase, voff) do { _Pragma("unroll") for (int _i = 0; _i < 2; ++_i) \
;         __builtin_amdgcn_global_load_lds((const unsigned*)((const char*)(gbase) + (voff)[_i]), (PG8_LAS unsigned*)(lds + (bufoff) + ldsw + _i * 8192), 16, 0, 0); } while (0)
; #define PG8_LDA(dst, b, h) do { _Pragma("unroll") for (int m = 0; m < 4; ++m) _Pragma("unroll") for (int k = 0; k < 2; ++k) dst[m][k] = *(const PG8_LAS bf16x8*)(lds + PG8_SA(b, h) + aoff + m * 2048 + k * 1024); } while (0)
; #define PG8_MMA(ai, bj, At, Bt) do { __builtin_amdgcn_s_setprio(1); _Pragma("unroll") for (int m = 0; m < 4; ++m) _Pragma("unroll") for (int n = 0; n < 2; ++n) _Pragma("unroll") for (int k = 0; k < 2; ++k) \
;         acc[ai][bj][m][n] = __builtin_amdgcn_mfma_f32_16x16x32_bf16(Bt[n][k], At[m][k], acc[ai][bj][m][n], 0, 0, 0); __builtin_amdgcn_s_setprio(0); } while (0)
; #define PG8_WAIT_V(n) asm volatile("s_waitcnt vmcnt(" #n ")" ::: "memory")
; #define PG8_WAIT_L(n) asm volatile("s_waitcnt lgkmcnt(" #n ")" ::: "memory")
; #define PG8_BAR __builtin_amdgcn_s_barrier()
; #define PG8_SCHED __builtin_amdgcn_sched_barrier(0)
; template <class Epi, class Sched, bool ALIGN_EPI = false, bool SP2 = false>
; __device__ __forceinline__ void gemm_phase(PG8_LAS unsigned char* lds, const Gemm g, const Sched& S, const Epi& E) {
;     ...
;         for (int t = 0; t < nt; t += 2) {
;     ...
;             PG8_LDA(At, 1, 1); PG8_STAGE(PG8_SB(1, 0), b3, voffB); PG8_STAGE(PG8_SB(1, 1), b3 + hstep, voffB); PG8_STAGE(PG8_SA(1, 0), a3, voffA);
;             PG8_WAIT_V(8); PG8_WAIT_L(0); PG8_BAR; PG8_MMA(1, 0, At, B0); PG8_MMA(1, 1, At, B1); PG8_BAR; PG8_SCHED;
;     ...
;         if constexpr (ALIGN_EPI) { if (wr == 0) PG8_BAR; }
	s_add_i32 s28, s52, s30
	v_lshl_add_u64 v[184:185], v[184:185], 0, s[16:17]
	s_mov_b32 m0, s28
	ds_read_b128 v[180:183], v192 offset:49152
	ds_read_b128 v[194:197], v192 offset:50176
	ds_read_b128 v[198:201], v192 offset:51200
	ds_read_b128 v[202:205], v192 offset:52224
	ds_read_b128 v[206:209], v192 offset:53248
	ds_read_b128 v[210:213], v192 offset:54272
	ds_read_b128 v[214:217], v192 offset:55296
	ds_read_b128 v[218:221], v192 offset:56320
	global_load_lds_dwordx4 v[184:185], off
	s_add_i32 m0, s28, 0x2000
	s_add_u32 s6, s6, 0x80080
	v_lshl_add_u64 v[184:185], v[222:223], 0, s[16:17]
	s_addc_u32 s7, s7, 0
	s_add_i32 s28, s53, s30
	global_load_lds_dwordx4 v[184:185], off
	v_lshl_add_u64 v[184:185], s[6:7], 0, v[164:165]
	s_mov_b32 m0, s28
	s_nop 0
	global_load_lds_dwordx4 v[184:185], off
	v_lshl_add_u64 v[184:185], s[6:7], 0, v[168:169]
	s_add_i32 m0, s28, 0x2000
	s_nop 0
	global_load_lds_dwordx4 v[184:185], off
	v_lshl_add_u64 v[184:185], v[224:225], 0, s[16:17]
	s_mov_b32 m0, s38
	s_nop 0
	global_load_lds_dwordx4 v[184:185], off
	v_lshl_add_u64 v[184:185], v[226:227], 0, s[16:17]
	s_mov_b32 m0, s39
	s_nop 0
	global_load_lds_dwordx4 v[184:185], off
	s_waitcnt vmcnt(8)
	s_waitcnt lgkmcnt(0)
	s_barrier
	s_setprio 1
	s_waitcnt lgkmcnt(0)
	v_mfma_f32_16x16x32_bf16 v[60:63], v[128:131], v[180:183], v[60:63]
	v_mfma_f32_16x16x32_bf16 v[56:59], v[136:139], v[180:183], v[56:59]
	v_mfma_f32_16x16x32_bf16 v[44:47], v[128:131], v[198:201], v[44:47]
	v_mfma_f32_16x16x32_bf16 v[40:43], v[136:139], v[198:201], v[40:43]
	v_mfma_f32_16x16x32_bf16 v[28:31], v[128:131], v[206:209], v[28:31]
	v_mfma_f32_16x16x32_bf16 v[24:27], v[136:139], v[206:209], v[24:27]
	v_mfma_f32_16x16x32_bf16 v[12:15], v[128:131], v[214:217], v[12:15]
	v_mfma_f32_16x16x32_bf16 v[8:11], v[136:139], v[214:217], v[8:11]
	v_mfma_f32_16x16x32_bf16 v[60:63], v[132:135], v[194:197], v[60:63]
	v_mfma_f32_16x16x32_bf16 v[56:59], v[140:143], v[194:197], v[56:59]
	v_mfma_f32_16x16x32_bf16 v[44:47], v[132:135], v[202:205], v[44:47]
	v_mfma_f32_16x16x32_bf16 v[40:43], v[140:143], v[202:205], v[40:43]
	v_mfma_f32_16x16x32_bf16 v[28:31], v[132:135], v[210:213], v[28:31]
	v_mfma_f32_16x16x32_bf16 v[24:27], v[140:143], v[210:213], v[24:27]
	v_mfma_f32_16x16x32_bf16 v[12:15], v[132:135], v[218:221], v[12:15]
	v_mfma_f32_16x16x32_bf16 v[8:11], v[140:143], v[218:221], v[8:11]
	s_setprio 0
	s_setprio 1
	v_mfma_f32_16x16x32_bf16 v[52:55], v[144:147], v[180:183], v[52:55]
	v_mfma_f32_16x16x32_bf16 v[48:51], v[152:155], v[180:183], v[48:51]
	v_mfma_f32_16x16x32_bf16 v[36:39], v[144:147], v[198:201], v[36:39]
	v_mfma_f32_16x16x32_bf16 v[32:35], v[152:155], v[198:201], v[32:35]
	v_mfma_f32_16x16x32_bf16 v[20:23], v[144:147], v[206:209], v[20:23]
	v_mfma_f32_16x16x32_bf16 v[16:19], v[152:155], v[206:209], v[16:19]
	v_mfma_f32_16x16x32_bf16 v[4:7], v[144:147], v[214:217], v[4:7]
	v_mfma_f32_16x16x32_bf16 v[0:3], v[152:155], v[214:217], v[0:3]
	v_mfma_f32_16x16x32_bf16 v[52:55], v[148:151], v[194:197], v[52:55]
	v_mfma_f32_16x16x32_bf16 v[48:51], v[156:159], v[194:197], v[48:51]
	v_mfma_f32_16x16x32_bf16 v[36:39], v[148:151], v[202:205], v[36:39]
	v_mfma_f32_16x16x32_bf16 v[32:35], v[156:159], v[202:205], v[32:35]
	v_mfma_f32_16x16x32_bf16 v[20:23], v[148:151], v[210:213], v[20:23]
	v_mfma_f32_16x16x32_bf16 v[16:19], v[156:159], v[210:213], v[16:19]
	v_mfma_f32_16x16x32_bf16 v[4:7], v[148:151], v[218:221], v[4:7]
	v_mfma_f32_16x16x32_bf16 v[0:3], v[156:159], v[218:221], v[0:3]
	s_setprio 0
	s_add_i32 s51, s51, 2
	s_add_u32 s4, s4, 0x100
	s_addc_u32 s5, s5, 0
	s_add_u32 s33, s33, 0x100
	s_addc_u32 s50, s50, 0
	s_cmp_gt_u32 s51, 29
	s_cbranch_scc0 .Lrot_205
	s_barrier
	s_and_b64 vcc, exec, s[18:19]
	s_cbranch_vccz .LBB0_208
	s_barrier

;     __device__ __forceinline__ bool next(int i, Unit& u) const { if (!base.next(i >> 1, u)) return false; if (i & 1) { u.pm += 64; u.pn += 8; } return true; }
; #define PG8_STAGE(bufoff, gbase, voff) do { _Pragma("unroll") for (int _i = 0; _i < 2; ++_i) \
;         __builtin_amdgcn_global_load_lds((const unsigned*)((const char*)(gbase) + (voff)[_i]), (PG8_LAS unsigned*)(lds + (bufoff) + ldsw + _i * 8192), 16, 0, 0); } while (0)
; #define PG8_LDA(dst, b, h) do { _Pragma("unroll") for (int m = 0; m < 4; ++m) _Pragma("unroll") for (int k = 0; k < 2; ++k) dst[m][k] = *(const PG8_LAS bf16x8*)(lds + PG8_SA(b, h) + aoff + m * 2048 + k * 1024); } while (0)
; #define PG8_LDB(dst, b, h) do { _Pragma("unroll") for (int n = 0; n < 2; ++n) _Pragma("unroll") for (int k = 0; k < 2; ++k) dst[n][k] = *(const PG8_LAS bf16x8*)(lds + PG8_SB(b, h) + boff + n * 2048 + k * 1024); } while (0)
; #define PG8_WAIT_V(n) asm volatile("s_waitcnt vmcnt(" #n ")" ::: "memory")
; #define PG8_WAIT_L(n) asm volatile("s_waitcnt lgkmcnt(" #n ")" ::: "memory")
; #define PG8_BAR __builtin_amdgcn_s_barrier()
; #define PG8_SCHED __builtin_amdgcn_sched_barrier(0)
; template <class Epi, class Sched, bool ALIGN_EPI = false, bool SP2 = false>
; __device__ __forceinline__ void gemm_phase(PG8_LAS unsigned char* lds, const Gemm g, const Sched& S, const Epi& E) {
;     ...
;         const bool has_next = S.next(ui + 1, nxt);
;         const char* nA = has_next ? (const char*)g.A + (size_t)nxt.pm * tstep : cA; const char* nB = has_next ? (const char*)g.Bt + (size_t)nxt.pn * tstep : cB;
;         for (int t = 0; t < nt; t += 2) {
;             const bool last = (t == nt - 2);
;             const char* a1 = cA + (size_t)(t + 1) * kstep;
;             const char* a2 = last ? nA : cA + (size_t)(t + 2) * kstep; const char* b2 = last ? nB : cB + (size_t)(t + 2) * kstep;
;             const char* a3 = a2 + kstep; const char* b3 = b2 + kstep;
;             if (last && has_next) S.a_ready(nxt);
;             if constexpr (SP2) {
;             PG8_LDB(B0, 0, 0); PG8_LDB(B1, 0, 1); PG8_SCHED; PG8_LDA(At, 0, 0); PG8_STAGE(PG8_SA(1, 1), a1 + hstep, voffA);
;             PG8_WAIT_V(8); PG8_WAIT_L(0); PG8_BAR; PG8_MMA(0, 0, At, B0); PG8_MMA(0, 1, At, B1); PG8_BAR; PG8_SCHED;
;             PG8_LDA(At, 0, 1); PG8_STAGE(PG8_SB(0, 0), b2, voffB); PG8_STAGE(PG8_SB(0, 1), b2 + hstep, voffB); PG8_STAGE(PG8_SA(0, 0), a2, voffA);
.LBB0_571:
	s_bitcmp0_b32 s7, 0
	s_cselect_b64 s[16:17], -1, 0
	s_and_b64 s[16:17], s[16:17], s[4:5]
	s_add_i32 s7, s14, 64
	s_add_i32 s13, s12, 8
	s_and_b64 s[16:17], s[16:17], exec
	s_cselect_b32 s14, s7, s14
	s_cselect_b32 s12, s13, s12
	s_ashr_i32 s15, s14, 31
	s_lshl_b64 s[16:17], s[14:15], 19
	s_add_u32 s16, s29, s16
	s_addc_u32 s17, s30, s17
	s_and_b64 s[18:19], s[4:5], exec
	s_cselect_b32 s7, s17, s23
	s_cselect_b32 s15, s16, s22
	s_ashr_i32 s13, s12, 31
	s_lshl_b64 s[18:19], s[12:13], 19
	v_readlane_b32 s26, v236, 41
	v_readlane_b32 s27, v236, 42
	s_add_u32 s18, s26, s18
	s_addc_u32 s19, s27, s19
	s_and_b64 s[26:27], s[4:5], exec
	s_cselect_b32 s13, s19, s25
	s_cselect_b32 s21, s18, s24
	s_add_u32 s22, s22, 0x40080
	s_addc_u32 s23, s23, 0
	s_add_u32 s44, s24, 0x100
	s_addc_u32 s45, s25, 0
	s_mov_b32 s46, -2
	ds_read_b128 v[146:149], v159
	ds_read_b128 v[150:153], v159 offset:1024
	ds_read_b128 v[164:167], v159 offset:2048
	ds_read_b128 v[168:171], v159 offset:3072
	ds_read_b128 v[172:175], v161
	ds_read_b128 v[176:179], v161 offset:1024
	ds_read_b128 v[180:183], v161 offset:2048
	ds_read_b128 v[188:191], v161 offset:3072
	s_add_u32 s24, s22, 0xfffc0080
	s_addc_u32 s25, s23, -1
	s_cmp_eq_u32 s46, 12
	s_cselect_b32 s27, s7, s25
	s_cselect_b32 s26, s15, s24
	s_cselect_b32 s25, s13, s45
	s_cselect_b32 s24, s21, s44
	v_lshl_add_u64 v[154:155], s[22:23], 0, v[138:139]
	s_add_i32 m0, s31, 0xc000
	ds_read_b128 v[192:195], v162
	ds_read_b128 v[196:199], v162 offset:1024
	ds_read_b128 v[200:203], v162 offset:2048
	ds_read_b128 v[204:207], v162 offset:3072
	ds_read_b128 v[208:211], v162 offset:4096
	ds_read_b128 v[212:215], v162 offset:5120
	ds_read_b128 v[216:219], v162 offset:6144
	ds_read_b128 v[220:223], v162 offset:7168
	global_load_lds_dwordx4 v[154:155], off
	v_lshl_add_u64 v[154:155], s[22:23], 0, v[140:141]
	s_add_i32 m0, s31, 0xe000
	s_nop 0
	global_load_lds_dwordx4 v[154:155], off
	s_waitcnt vmcnt(8)
	s_waitcnt lgkmcnt(0)
	s_barrier
	s_setprio 1
	s_waitcnt lgkmcnt(0)
	v_mfma_f32_16x16x32_bf16 v[124:127], v[146:149], v[192:195], 0
	v_mfma_f32_16x16x32_bf16 v[120:123], v[164:167], v[192:195], 0
	v_mfma_f32_16x16x32_bf16 v[108:111], v[146:149], v[200:203], 0
	v_mfma_f32_16x16x32_bf16 v[104:107], v[164:167], v[200:203], 0
	v_mfma_f32_16x16x32_bf16 v[92:95], v[146:149], v[208:211], 0
	v_mfma_f32_16x16x32_bf16 v[88:91], v[164:167], v[208:211], 0
	v_mfma_f32_16x16x32_bf16 v[76:79], v[146:149], v[216:219], 0
	v_mfma_f32_16x16x32_bf16 v[72:75], v[164:167], v[216:219], 0
	v_mfma_f32_16x16x32_bf16 v[124:127], v[150:153], v[196:199], v[124:127]
	v_mfma_f32_16x16x32_bf16 v[120:123], v[168:171], v[196:199], v[120:123]
	v_mfma_f32_16x16x32_bf16 v[108:111], v[150:153], v[204:207], v[108:111]
	v_mfma_f32_16x16x32_bf16 v[104:107], v[168:171], v[204:207], v[104:107]
	v_mfma_f32_16x16x32_bf16 v[92:95], v[150:153], v[212:215], v[92:95]
	v_mfma_f32_16x16x32_bf16 v[88:91], v[168:171], v[212:215], v[88:91]
	v_mfma_f32_16x16x32_bf16 v[76:79], v[150:153], v[220:223], v[76:79]
	v_mfma_f32_16x16x32_bf16 v[72:75], v[168:171], v[220:223], v[72:75]
	s_setprio 0
	s_setprio 1
	v_mfma_f32_16x16x32_bf16 v[116:119], v[172:175], v[192:195], 0
	v_mfma_f32_16x16x32_bf16 v[112:115], v[180:183], v[192:195], 0
	v_mfma_f32_16x16x32_bf16 v[100:103], v[172:175], v[200:203], 0
	v_mfma_f32_16x16x32_bf16 v[96:99], v[180:183], v[200:203], 0
	v_mfma_f32_16x16x32_bf16 v[84:87], v[172:175], v[208:211], 0
	v_mfma_f32_16x16x32_bf16 v[80:83], v[180:183], v[208:211], 0
	v_mfma_f32_16x16x32_bf16 v[68:71], v[172:175], v[216:219], 0
	v_mfma_f32_16x16x32_bf16 v[64:67], v[180:183], v[216:219], 0
	v_mfma_f32_16x16x32_bf16 v[116:119], v[176:179], v[196:199], v[116:119]
	v_mfma_f32_16x16x32_bf16 v[112:115], v[188:191], v[196:199], v[112:115]
	v_mfma_f32_16x16x32_bf16 v[100:103], v[176:179], v[204:207], v[100:103]
	v_mfma_f32_16x16x32_bf16 v[96:99], v[188:191], v[204:207], v[96:99]
	v_mfma_f32_16x16x32_bf16 v[84:87], v[176:179], v[212:215], v[84:87]
	v_mfma_f32_16x16x32_bf16 v[80:83], v[188:191], v[212:215], v[80:83]
	v_mfma_f32_16x16x32_bf16 v[68:71], v[176:179], v[220:223], v[68:71]
	v_mfma_f32_16x16x32_bf16 v[64:67], v[188:191], v[220:223], v[64:67]
	s_setprio 0
	s_barrier
	s_add_i32 s47, s39, s28
	v_lshl_add_u64 v[154:155], s[24:25], 0, v[130:131]
	s_mov_b32 m0, s47
	ds_read_b128 v[192:195], v162 offset:16384
	ds_read_b128 v[196:199], v162 offset:17408
	ds_read_b128 v[200:203], v162 offset:18432
	ds_read_b128 v[204:207], v162 offset:19456
	ds_read_b128 v[208:211], v162 offset:20480
	ds_read_b128 v[212:215], v162 offset:21504
	ds_read_b128 v[216:219], v162 offset:22528
	ds_read_b128 v[220:223], v162 offset:23552
	global_load_lds_dwordx4 v[154:155], off
	s_add_i32 m0, s47, 0x2000
	s_add_u32 s48, s24, 0x40000
	v_lshl_add_u64 v[184:185], s[24:25], 0, v[134:135]
	s_addc_u32 s49, s25, 0
	s_add_i32 s47, s40, s28
	global_load_lds_dwordx4 v[184:185], off
	v_lshl_add_u64 v[224:225], s[48:49], 0, v[130:131]
	s_mov_b32 m0, s47
	v_lshl_add_u64 v[226:227], s[26:27], 0, v[132:133]
	global_load_lds_dwordx4 v[224:225], off
	v_lshl_add_u64 v[224:225], s[48:49], 0, v[134:135]
	s_add_i32 m0, s47, 0x2000
	s_nop 0
	global_load_lds_dwordx4 v[224:225], off
	v_lshl_add_u64 v[224:225], s[26:27], 0, v[128:129]
	s_mov_b32 m0, s31
	s_nop 0
	global_load_lds_dwordx4 v[224:225], off
	s_mov_b32 m0, s33
	s_nop 0
	global_load_lds_dwordx4 v[226:227], off
	s_waitcnt vmcnt(8)
	s_waitcnt lgkmcnt(0)
	s_barrier
; #define PG8_STAGE(bufoff, gbase, voff) do { _Pragma("unroll") for (int _i = 0; _i < 2; ++_i) \
;         __builtin_amdgcn_global_load_lds((const unsigned*)((const char*)(gbase) + (voff)[_i]), (PG8_LAS unsigned*)(lds + (bufoff) + ldsw + _i * 8192), 16, 0, 0); } while (0)
; #define PG8_LDA(dst, b, h) do { _Pragma("unroll") for (int m = 0; m < 4; ++m) _Pragma("unroll") for (int k = 0; k < 2; ++k) dst[m][k] = *(const PG8_LAS bf16x8*)(lds + PG8_SA(b, h) + aoff + m * 2048 + k * 1024); } while (0)
; #define PG8_LDB(dst, b, h) do { _Pragma("unroll") for (int n = 0; n < 2; ++n) _Pragma("unroll") for (int k = 0; k < 2; ++k) dst[n][k] = *(const PG8_LAS bf16x8*)(lds + PG8_SB(b, h) + boff + n * 2048 + k * 1024); } while (0)
; #define PG8_MMA(ai, bj, At, Bt) do { __builtin_amdgcn_s_setprio(1); _Pragma("unroll") for (int m = 0; m < 4; ++m) _Pragma("unroll") for (int n = 0; n < 2; ++n) _Pragma("unroll") for (int k = 0; k < 2; ++k) \
;         acc[ai][bj][m][n] = __builtin_amdgcn_mfma_f32_16x16x32_bf16(Bt[n][k], At[m][k], acc[ai][bj][m][n], 0, 0, 0); __builtin_amdgcn_s_setprio(0); } while (0)
; #define PG8_WAIT_V(n) asm volatile("s_waitcnt vmcnt(" #n ")" ::: "memory")
; #define PG8_WAIT_L(n) asm volatile("s_waitcnt lgkmcnt(" #n ")" ::: "memory")
; #define PG8_BAR __builtin_amdgcn_s_barrier()
; #define PG8_SCHED __builtin_amdgcn_sched_barrier(0)
; template <class Epi, class Sched, bool ALIGN_EPI = false, bool SP2 = false>
; __device__ __forceinline__ void gemm_phase(PG8_LAS unsigned char* lds, const Gemm g, const Sched& S, const Epi& E) {
;     ...
;             PG8_WAIT_V(8); PG8_WAIT_L(0); PG8_BAR; PG8_MMA(1, 0, At, B0); PG8_MMA(1, 1, At, B1); PG8_BAR; PG8_SCHED;
;             PG8_LDB(B0, 1, 0); PG8_LDB(B1, 1, 1); PG8_SCHED; PG8_LDA(At, 1, 0); PG8_STAGE(PG8_SA(0, 1), a2 + hstep, voffA);
;             PG8_WAIT_V(8); PG8_WAIT_L(0); PG8_BAR; PG8_MMA(0, 0, At, B0); PG8_MMA(0, 1, At, B1); PG8_BAR; PG8_SCHED;
	s_setprio 1
	s_waitcnt lgkmcnt(0)
	v_mfma_f32_16x16x32_bf16 v[60:63], v[146:149], v[192:195], 0
	v_mfma_f32_16x16x32_bf16 v[56:59], v[164:167], v[192:195], 0
	v_mfma_f32_16x16x32_bf16 v[44:47], v[146:149], v[200:203], 0
	v_mfma_f32_16x16x32_bf16 v[40:43], v[164:167], v[200:203], 0
	v_mfma_f32_16x16x32_bf16 v[28:31], v[146:149], v[208:211], 0
	v_mfma_f32_16x16x32_bf16 v[24:27], v[164:167], v[208:211], 0
	v_mfma_f32_16x16x32_bf16 v[12:15], v[146:149], v[216:219], 0
	v_mfma_f32_16x16x32_bf16 v[8:11], v[164:167], v[216:219], 0
	v_mfma_f32_16x16x32_bf16 v[60:63], v[150:153], v[196:199], v[60:63]
	v_mfma_f32_16x16x32_bf16 v[56:59], v[168:171], v[196:199], v[56:59]
	v_mfma_f32_16x16x32_bf16 v[44:47], v[150:153], v[204:207], v[44:47]
	v_mfma_f32_16x16x32_bf16 v[40:43], v[168:171], v[204:207], v[40:43]
	v_mfma_f32_16x16x32_bf16 v[28:31], v[150:153], v[212:215], v[28:31]
	v_mfma_f32_16x16x32_bf16 v[24:27], v[168:171], v[212:215], v[24:27]
	v_mfma_f32_16x16x32_bf16 v[12:15], v[150:153], v[220:223], v[12:15]
	v_mfma_f32_16x16x32_bf16 v[8:11], v[168:171], v[220:223], v[8:11]
	s_setprio 0
	s_setprio 1
	v_mfma_f32_16x16x32_bf16 v[52:55], v[172:175], v[192:195], 0
	v_mfma_f32_16x16x32_bf16 v[48:51], v[180:183], v[192:195], 0
	v_mfma_f32_16x16x32_bf16 v[36:39], v[172:175], v[200:203], 0
	v_mfma_f32_16x16x32_bf16 v[32:35], v[180:183], v[200:203], 0
	v_mfma_f32_16x16x32_bf16 v[20:23], v[172:175], v[208:211], 0
	v_mfma_f32_16x16x32_bf16 v[16:19], v[180:183], v[208:211], 0
	v_mfma_f32_16x16x32_bf16 v[4:7], v[172:175], v[216:219], 0
	v_mfma_f32_16x16x32_bf16 v[0:3], v[180:183], v[216:219], 0
	v_mfma_f32_16x16x32_bf16 v[52:55], v[176:179], v[196:199], v[52:55]
	v_mfma_f32_16x16x32_bf16 v[48:51], v[188:191], v[196:199], v[48:51]
	v_mfma_f32_16x16x32_bf16 v[36:39], v[176:179], v[204:207], v[36:39]
	v_mfma_f32_16x16x32_bf16 v[32:35], v[188:191], v[204:207], v[32:35]
	v_mfma_f32_16x16x32_bf16 v[20:23], v[176:179], v[212:215], v[20:23]
	v_mfma_f32_16x16x32_bf16 v[16:19], v[188:191], v[212:215], v[16:19]
	v_mfma_f32_16x16x32_bf16 v[4:7], v[176:179], v[220:223], v[4:7]
	v_mfma_f32_16x16x32_bf16 v[0:3], v[188:191], v[220:223], v[0:3]
	s_setprio 0
	s_barrier
	s_add_i32 s47, 0, 0x18000
	v_add_u32_e32 v136, s47, v157
	s_add_i32 s48, 0, 0x1c000
	ds_read_b128 v[146:149], v136
	ds_read_b128 v[150:153], v136 offset:1024
	ds_read_b128 v[164:167], v136 offset:2048
	ds_read_b128 v[168:171], v136 offset:3072
	v_add_u32_e32 v136, s48, v157
	ds_read_b128 v[172:175], v136
	ds_read_b128 v[176:179], v136 offset:1024
	ds_read_b128 v[180:183], v136 offset:2048
	ds_read_b128 v[188:191], v136 offset:3072
	s_add_u32 s26, s26, 0x40000
	s_addc_u32 s27, s27, 0
	s_mov_b32 m0, s34
	v_lshl_add_u64 v[228:229], s[26:27], 0, v[128:129]
	ds_read_b128 v[192:195], v162 offset:32768
	ds_read_b128 v[196:199], v162 offset:33792
	ds_read_b128 v[200:203], v162 offset:34816
	ds_read_b128 v[204:207], v162 offset:35840
	ds_read_b128 v[208:211], v162 offset:36864
	ds_read_b128 v[212:215], v162 offset:37888
	ds_read_b128 v[216:219], v162 offset:38912
	ds_read_b128 v[220:223], v162 offset:39936
	global_load_lds_dwordx4 v[228:229], off
	v_lshl_add_u64 v[228:229], s[26:27], 0, v[132:133]
	s_mov_b32 m0, s35
	s_nop 0
	global_load_lds_dwordx4 v[228:229], off
	s_waitcnt vmcnt(8)
	s_waitcnt lgkmcnt(0)
	s_barrier
	s_setprio 1
	s_waitcnt lgkmcnt(0)
	v_mfma_f32_16x16x32_bf16 v[124:127], v[146:149], v[192:195], v[124:127]
	v_mfma_f32_16x16x32_bf16 v[120:123], v[164:167], v[192:195], v[120:123]
	v_mfma_f32_16x16x32_bf16 v[108:111], v[146:149], v[200:203], v[108:111]
	v_mfma_f32_16x16x32_bf16 v[104:107], v[164:167], v[200:203], v[104:107]
	v_mfma_f32_16x16x32_bf16 v[92:95], v[146:149], v[208:211], v[92:95]
	v_mfma_f32_16x16x32_bf16 v[88:91], v[164:167], v[208:211], v[88:91]
	v_mfma_f32_16x16x32_bf16 v[76:79], v[146:149], v[216:219], v[76:79]
	v_mfma_f32_16x16x32_bf16 v[72:75], v[164:167], v[216:219], v[72:75]
	v_mfma_f32_16x16x32_bf16 v[124:127], v[150:153], v[196:199], v[124:127]
	v_mfma_f32_16x16x32_bf16 v[120:123], v[168:171], v[196:199], v[120:123]
	v_mfma_f32_16x16x32_bf16 v[108:111], v[150:153], v[204:207], v[108:111]
	v_mfma_f32_16x16x32_bf16 v[104:107], v[168:171], v[204:207], v[104:107]
	v_mfma_f32_16x16x32_bf16 v[92:95], v[150:153], v[212:215], v[92:95]
	v_mfma_f32_16x16x32_bf16 v[88:91], v[168:171], v[212:215], v[88:91]
	v_mfma_f32_16x16x32_bf16 v[76:79], v[150:153], v[220:223], v[76:79]
	v_mfma_f32_16x16x32_bf16 v[72:75], v[168:171], v[220:223], v[72:75]
	s_setprio 0
	s_setprio 1
	v_mfma_f32_16x16x32_bf16 v[116:119], v[172:175], v[192:195], v[116:119]
	v_mfma_f32_16x16x32_bf16 v[112:115], v[180:183], v[192:195], v[112:115]
	v_mfma_f32_16x16x32_bf16 v[100:103], v[172:175], v[200:203], v[100:103]
	v_mfma_f32_16x16x32_bf16 v[96:99], v[180:183], v[200:203], v[96:99]
	v_mfma_f32_16x16x32_bf16 v[84:87], v[172:175], v[208:211], v[84:87]
	v_mfma_f32_16x16x32_bf16 v[80:83], v[180:183], v[208:211], v[80:83]
	v_mfma_f32_16x16x32_bf16 v[68:71], v[172:175], v[216:219], v[68:71]
	v_mfma_f32_16x16x32_bf16 v[64:67], v[180:183], v[216:219], v[64:67]
	v_mfma_f32_16x16x32_bf16 v[116:119], v[176:179], v[196:199], v[116:119]
	v_mfma_f32_16x16x32_bf16 v[112:115], v[188:191], v[196:199], v[112:115]
	v_mfma_f32_16x16x32_bf16 v[100:103], v[176:179], v[204:207], v[100:103]
	v_mfma_f32_16x16x32_bf16 v[96:99], v[188:191], v[204:207], v[96:99]
	v_mfma_f32_16x16x32_bf16 v[84:87], v[176:179], v[212:215], v[84:87]
	v_mfma_f32_16x16x32_bf16 v[80:83], v[188:191], v[212:215], v[80:83]
	v_mfma_f32_16x16x32_bf16 v[68:71], v[176:179], v[220:223], v[68:71]
	v_mfma_f32_16x16x32_bf16 v[64:67], v[188:191], v[220:223], v[64:67]
	s_setprio 0
	s_barrier
; #define PG8_STAGE(bufoff, gbase, voff) do { _Pragma("unroll") for (int _i = 0; _i < 2; ++_i) \
;         __builtin_amdgcn_global_load_lds((const unsigned*)((const char*)(gbase) + (voff)[_i]), (PG8_LAS unsigned*)(lds + (bufoff) + ldsw + _i * 8192), 16, 0, 0); } while (0)
; #define PG8_LDA(dst, b, h) do { _Pragma("unroll") for (int m = 0; m < 4; ++m) _Pragma("unroll") for (int k = 0; k < 2; ++k) dst[m][k] = *(const PG8_LAS bf16x8*)(lds + PG8_SA(b, h) + aoff + m * 2048 + k * 1024); } while (0)
; #define PG8_MMA(ai, bj, At, Bt) do { __builtin_amdgcn_s_setprio(1); _Pragma("unroll") for (int m = 0; m < 4; ++m) _Pragma("unroll") for (int n = 0; n < 2; ++n) _Pragma("unroll") for (int k = 0; k < 2; ++k) \
;         acc[ai][bj][m][n] = __builtin_amdgcn_mfma_f32_16x16x32_bf16(Bt[n][k], At[m][k], acc[ai][bj][m][n], 0, 0, 0); __builtin_amdgcn_s_setprio(0); } while (0)
; #define PG8_WAIT_V(n) asm volatile("s_waitcnt vmcnt(" #n ")" ::: "memory")
; #define PG8_WAIT_L(n) asm volatile("s_waitcnt lgkmcnt(" #n ")" ::: "memory")
; #define PG8_BAR __builtin_amdgcn_s_barrier()
; #define PG8_SCHED __builtin_amdgcn_sched_barrier(0)
; template <class Epi, class Sched, bool ALIGN_EPI = false, bool SP2 = false>
; __device__ __forceinline__ void gemm_phase(PG8_LAS unsigned char* lds, const Gemm g, const Sched& S, const Epi& E) {
;     ...
;         for (int t = 0; t < nt; t += 2) {
;             const bool last = (t == nt - 2);
;             const char* a1 = cA + (size_t)(t + 1) * kstep;
;             const char* a2 = last ? nA : cA + (size_t)(t + 2) * kstep; const char* b2 = last ? nB : cB + (size_t)(t + 2) * kstep;
;     ...
;             PG8_LDA(At, 1, 1); PG8_STAGE(PG8_SB(1, 0), b3, voffB); PG8_STAGE(PG8_SB(1, 1), b3 + hstep, voffB); PG8_STAGE(PG8_SA(1, 0), a3, voffA);
;             PG8_WAIT_V(8); PG8_WAIT_L(0); PG8_BAR; PG8_MMA(1, 0, At, B0); PG8_MMA(1, 1, At, B1); PG8_BAR; PG8_SCHED;
	s_add_i32 s26, s47, s28
	v_lshl_add_u64 v[154:155], v[154:155], 0, s[8:9]
	s_mov_b32 m0, s26
	ds_read_b128 v[192:195], v162 offset:49152
	ds_read_b128 v[196:199], v162 offset:50176
	ds_read_b128 v[200:203], v162 offset:51200
	ds_read_b128 v[204:207], v162 offset:52224
	ds_read_b128 v[208:211], v162 offset:53248
	ds_read_b128 v[212:215], v162 offset:54272
	ds_read_b128 v[216:219], v162 offset:55296
	ds_read_b128 v[220:223], v162 offset:56320
	global_load_lds_dwordx4 v[154:155], off
	s_add_i32 m0, s26, 0x2000
	s_add_u32 s24, s24, 0x40080
	v_lshl_add_u64 v[154:155], v[184:185], 0, s[8:9]
	s_addc_u32 s25, s25, 0
	s_add_i32 s26, s48, s28
	global_load_lds_dwordx4 v[154:155], off
	v_lshl_add_u64 v[154:155], s[24:25], 0, v[130:131]
	s_mov_b32 m0, s26
	s_nop 0
	global_load_lds_dwordx4 v[154:155], off
	v_lshl_add_u64 v[154:155], s[24:25], 0, v[134:135]
	s_add_i32 m0, s26, 0x2000
	s_nop 0
	global_load_lds_dwordx4 v[154:155], off
	v_lshl_add_u64 v[154:155], v[224:225], 0, s[8:9]
	s_mov_b32 m0, s36
	s_nop 0
	global_load_lds_dwordx4 v[154:155], off
	v_lshl_add_u64 v[154:155], v[226:227], 0, s[8:9]
	s_mov_b32 m0, s37
	s_nop 0
	global_load_lds_dwordx4 v[154:155], off
	s_waitcnt vmcnt(8)
	s_waitcnt lgkmcnt(0)
	s_barrier
	s_setprio 1
	s_waitcnt lgkmcnt(0)
	v_mfma_f32_16x16x32_bf16 v[60:63], v[146:149], v[192:195], v[60:63]
	v_mfma_f32_16x16x32_bf16 v[56:59], v[164:167], v[192:195], v[56:59]
	v_mfma_f32_16x16x32_bf16 v[44:47], v[146:149], v[200:203], v[44:47]
	v_mfma_f32_16x16x32_bf16 v[40:43], v[164:167], v[200:203], v[40:43]
	v_mfma_f32_16x16x32_bf16 v[28:31], v[146:149], v[208:211], v[28:31]
	v_mfma_f32_16x16x32_bf16 v[24:27], v[164:167], v[208:211], v[24:27]
	v_mfma_f32_16x16x32_bf16 v[12:15], v[146:149], v[216:219], v[12:15]
	v_mfma_f32_16x16x32_bf16 v[8:11], v[164:167], v[216:219], v[8:11]
	v_mfma_f32_16x16x32_bf16 v[60:63], v[150:153], v[196:199], v[60:63]
	v_mfma_f32_16x16x32_bf16 v[56:59], v[168:171], v[196:199], v[56:59]
	v_mfma_f32_16x16x32_bf16 v[44:47], v[150:153], v[204:207], v[44:47]
	v_mfma_f32_16x16x32_bf16 v[40:43], v[168:171], v[204:207], v[40:43]
	v_mfma_f32_16x16x32_bf16 v[28:31], v[150:153], v[212:215], v[28:31]
	v_mfma_f32_16x16x32_bf16 v[24:27], v[168:171], v[212:215], v[24:27]
	v_mfma_f32_16x16x32_bf16 v[12:15], v[150:153], v[220:223], v[12:15]
	v_mfma_f32_16x16x32_bf16 v[8:11], v[168:171], v[220:223], v[8:11]
	s_setprio 0
	s_setprio 1
	v_mfma_f32_16x16x32_bf16 v[52:55], v[172:175], v[192:195], v[52:55]
	v_mfma_f32_16x16x32_bf16 v[48:51], v[180:183], v[192:195], v[48:51]
	v_mfma_f32_16x16x32_bf16 v[36:39], v[172:175], v[200:203], v[36:39]
	v_mfma_f32_16x16x32_bf16 v[32:35], v[180:183], v[200:203], v[32:35]
	v_mfma_f32_16x16x32_bf16 v[20:23], v[172:175], v[208:211], v[20:23]
	v_mfma_f32_16x16x32_bf16 v[16:19], v[180:183], v[208:211], v[16:19]
	v_mfma_f32_16x16x32_bf16 v[4:7], v[172:175], v[216:219], v[4:7]
	v_mfma_f32_16x16x32_bf16 v[0:3], v[180:183], v[216:219], v[0:3]
	v_mfma_f32_16x16x32_bf16 v[52:55], v[176:179], v[196:199], v[52:55]
	v_mfma_f32_16x16x32_bf16 v[48:51], v[188:191], v[196:199], v[48:51]
	v_mfma_f32_16x16x32_bf16 v[36:39], v[176:179], v[204:207], v[36:39]
	v_mfma_f32_16x16x32_bf16 v[32:35], v[188:191], v[204:207], v[32:35]
	v_mfma_f32_16x16x32_bf16 v[20:23], v[176:179], v[212:215], v[20:23]
	v_mfma_f32_16x16x32_bf16 v[16:19], v[188:191], v[212:215], v[16:19]
	v_mfma_f32_16x16x32_bf16 v[4:7], v[176:179], v[220:223], v[4:7]
	v_mfma_f32_16x16x32_bf16 v[0:3], v[188:191], v[220:223], v[0:3]
	s_setprio 0
	s_add_i32 s46, s46, 2
	s_add_u32 s22, s22, 0x100
	s_addc_u32 s23, s23, 0
	s_add_u32 s44, s44, 0x100
	s_addc_u32 s45, s45, 0
	s_cmp_gt_u32 s46, 13

; #define PG8_STAGE(bufoff, gbase, voff) do { _Pragma("unroll") for (int _i = 0; _i < 2; ++_i) \
;         __builtin_amdgcn_global_load_lds((const unsigned*)((const char*)(gbase) + (voff)[_i]), (PG8_LAS unsigned*)(lds + (bufoff) + ldsw + _i * 8192), 16, 0, 0); } while (0)
; #define PG8_LDA(dst, b, h) do { _Pragma("unroll") for (int m = 0; m < 4; ++m) _Pragma("unroll") for (int k = 0; k < 2; ++k) dst[m][k] = *(const PG8_LAS bf16x8*)(lds + PG8_SA(b, h) + aoff + m * 2048 + k * 1024); } while (0)
; #define PG8_LDB(dst, b, h) do { _Pragma("unroll") for (int n = 0; n < 2; ++n) _Pragma("unroll") for (int k = 0; k < 2; ++k) dst[n][k] = *(const PG8_LAS bf16x8*)(lds + PG8_SB(b, h) + boff + n * 2048 + k * 1024); } while (0)
; #define PG8_MMA(ai, bj, At, Bt) do { __builtin_amdgcn_s_setprio(1); _Pragma("unroll") for (int m = 0; m < 4; ++m) _Pragma("unroll") for (int n = 0; n < 2; ++n) _Pragma("unroll") for (int k = 0; k < 2; ++k) \
;         acc[ai][bj][m][n] = __builtin_amdgcn_mfma_f32_16x16x32_bf16(Bt[n][k], At[m][k], acc[ai][bj][m][n], 0, 0, 0); __builtin_amdgcn_s_setprio(0); } while (0)
; #define PG8_WAIT_V(n) asm volatile("s_waitcnt vmcnt(" #n ")" ::: "memory")
; #define PG8_WAIT_L(n) asm volatile("s_waitcnt lgkmcnt(" #n ")" ::: "memory")
; #define PG8_BAR __builtin_amdgcn_s_barrier()
; #define PG8_SCHED __builtin_amdgcn_sched_barrier(0)
; template <class Epi, class Sched, bool ALIGN_EPI = false, bool SP2 = false>
; __device__ __forceinline__ void gemm_phase(PG8_LAS unsigned char* lds, const Gemm g, const Sched& S, const Epi& E) {
;     ...
;         for (int t = 0; t < nt; t += 2) {
;             const bool last = (t == nt - 2);
;             const char* a1 = cA + (size_t)(t + 1) * kstep;
;             const char* a2 = last ? nA : cA + (size_t)(t + 2) * kstep; const char* b2 = last ? nB : cB + (size_t)(t + 2) * kstep;
;             const char* a3 = a2 + kstep; const char* b3 = b2 + kstep;
;             if (last && has_next) S.a_ready(nxt);
;             if constexpr (SP2) {
;             PG8_LDB(B0, 0, 0); PG8_LDB(B1, 0, 1); PG8_SCHED; PG8_LDA(At, 0, 0); PG8_STAGE(PG8_SA(1, 1), a1 + hstep, voffA);
;             PG8_WAIT_V(8); PG8_WAIT_L(0); PG8_BAR; PG8_MMA(0, 0, At, B0); PG8_MMA(0, 1, At, B1); PG8_BAR; PG8_SCHED;
;             PG8_LDA(At, 0, 1); PG8_STAGE(PG8_SB(0, 0), b2, voffB); PG8_STAGE(PG8_SB(0, 1), b2 + hstep, voffB); PG8_STAGE(PG8_SA(0, 0), a2, voffA);
.LBB0_572:
	ds_read_b128 v[146:149], v159
	ds_read_b128 v[150:153], v159 offset:1024
	ds_read_b128 v[164:167], v159 offset:2048
	ds_read_b128 v[168:171], v159 offset:3072
	ds_read_b128 v[172:175], v161
	ds_read_b128 v[176:179], v161 offset:1024
	ds_read_b128 v[180:183], v161 offset:2048
	ds_read_b128 v[188:191], v161 offset:3072
	s_add_u32 s24, s22, 0xfffc0080
	s_addc_u32 s25, s23, -1
	s_cmp_eq_u32 s46, 12
	s_cselect_b32 s27, s7, s25
	s_cselect_b32 s26, s15, s24
	s_cselect_b32 s25, s13, s45
	s_cselect_b32 s24, s21, s44
	v_lshl_add_u64 v[154:155], s[22:23], 0, v[138:139]
	s_add_i32 m0, s31, 0xc000
	ds_read_b128 v[192:195], v162
	ds_read_b128 v[196:199], v162 offset:1024
	ds_read_b128 v[200:203], v162 offset:2048
	ds_read_b128 v[204:207], v162 offset:3072
	ds_read_b128 v[208:211], v162 offset:4096
	ds_read_b128 v[212:215], v162 offset:5120
	ds_read_b128 v[216:219], v162 offset:6144
	ds_read_b128 v[220:223], v162 offset:7168
	global_load_lds_dwordx4 v[154:155], off
	v_lshl_add_u64 v[154:155], s[22:23], 0, v[140:141]
	s_add_i32 m0, s31, 0xe000
	s_nop 0
	global_load_lds_dwordx4 v[154:155], off
	s_waitcnt vmcnt(8)
	s_waitcnt lgkmcnt(0)
	s_barrier
	s_setprio 1
	s_waitcnt lgkmcnt(0)
	v_mfma_f32_16x16x32_bf16 v[124:127], v[146:149], v[192:195], v[124:127]
	v_mfma_f32_16x16x32_bf16 v[120:123], v[164:167], v[192:195], v[120:123]
	v_mfma_f32_16x16x32_bf16 v[108:111], v[146:149], v[200:203], v[108:111]
	v_mfma_f32_16x16x32_bf16 v[104:107], v[164:167], v[200:203], v[104:107]
	v_mfma_f32_16x16x32_bf16 v[92:95], v[146:149], v[208:211], v[92:95]
	v_mfma_f32_16x16x32_bf16 v[88:91], v[164:167], v[208:211], v[88:91]
	v_mfma_f32_16x16x32_bf16 v[76:79], v[146:149], v[216:219], v[76:79]
	v_mfma_f32_16x16x32_bf16 v[72:75], v[164:167], v[216:219], v[72:75]
	v_mfma_f32_16x16x32_bf16 v[124:127], v[150:153], v[196:199], v[124:127]
	v_mfma_f32_16x16x32_bf16 v[120:123], v[168:171], v[196:199], v[120:123]
	v_mfma_f32_16x16x32_bf16 v[108:111], v[150:153], v[204:207], v[108:111]
	v_mfma_f32_16x16x32_bf16 v[104:107], v[168:171], v[204:207], v[104:107]
	v_mfma_f32_16x16x32_bf16 v[92:95], v[150:153], v[212:215], v[92:95]
	v_mfma_f32_16x16x32_bf16 v[88:91], v[168:171], v[212:215], v[88:91]
	v_mfma_f32_16x16x32_bf16 v[76:79], v[150:153], v[220:223], v[76:79]
	v_mfma_f32_16x16x32_bf16 v[72:75], v[168:171], v[220:223], v[72:75]
	s_setprio 0
	s_setprio 1
	v_mfma_f32_16x16x32_bf16 v[116:119], v[172:175], v[192:195], v[116:119]
	v_mfma_f32_16x16x32_bf16 v[112:115], v[180:183], v[192:195], v[112:115]
	v_mfma_f32_16x16x32_bf16 v[100:103], v[172:175], v[200:203], v[100:103]
	v_mfma_f32_16x16x32_bf16 v[96:99], v[180:183], v[200:203], v[96:99]
	v_mfma_f32_16x16x32_bf16 v[84:87], v[172:175], v[208:211], v[84:87]
	v_mfma_f32_16x16x32_bf16 v[80:83], v[180:183], v[208:211], v[80:83]
	v_mfma_f32_16x16x32_bf16 v[68:71], v[172:175], v[216:219], v[68:71]
	v_mfma_f32_16x16x32_bf16 v[64:67], v[180:183], v[216:219], v[64:67]
	v_mfma_f32_16x16x32_bf16 v[116:119], v[176:179], v[196:199], v[116:119]
	v_mfma_f32_16x16x32_bf16 v[112:115], v[188:191], v[196:199], v[112:115]
	v_mfma_f32_16x16x32_bf16 v[100:103], v[176:179], v[204:207], v[100:103]
	v_mfma_f32_16x16x32_bf16 v[96:99], v[188:191], v[204:207], v[96:99]
	v_mfma_f32_16x16x32_bf16 v[84:87], v[176:179], v[212:215], v[84:87]
	v_mfma_f32_16x16x32_bf16 v[80:83], v[188:191], v[212:215], v[80:83]
	v_mfma_f32_16x16x32_bf16 v[68:71], v[176:179], v[220:223], v[68:71]
	v_mfma_f32_16x16x32_bf16 v[64:67], v[188:191], v[220:223], v[64:67]
	s_setprio 0
	s_barrier
	s_add_i32 s47, s39, s28
	v_lshl_add_u64 v[154:155], s[24:25], 0, v[130:131]
	s_mov_b32 m0, s47
	ds_read_b128 v[192:195], v162 offset:16384
	ds_read_b128 v[196:199], v162 offset:17408
	ds_read_b128 v[200:203], v162 offset:18432
	ds_read_b128 v[204:207], v162 offset:19456
	ds_read_b128 v[208:211], v162 offset:20480
	ds_read_b128 v[212:215], v162 offset:21504
	ds_read_b128 v[216:219], v162 offset:22528
	ds_read_b128 v[220:223], v162 offset:23552
	global_load_lds_dwordx4 v[154:155], off
	s_add_i32 m0, s47, 0x2000
	s_add_u32 s48, s24, 0x40000
	v_lshl_add_u64 v[184:185], s[24:25], 0, v[134:135]
	s_addc_u32 s49, s25, 0
	s_add_i32 s47, s40, s28
	global_load_lds_dwordx4 v[184:185], off
	v_lshl_add_u64 v[224:225], s[48:49], 0, v[130:131]
	s_mov_b32 m0, s47
	v_lshl_add_u64 v[226:227], s[26:27], 0, v[132:133]
	global_load_lds_dwordx4 v[224:225], off
	v_lshl_add_u64 v[224:225], s[48:49], 0, v[134:135]
	s_add_i32 m0, s47, 0x2000
	s_nop 0
	global_load_lds_dwordx4 v[224:225], off
	v_lshl_add_u64 v[224:225], s[26:27], 0, v[128:129]
	s_mov_b32 m0, s31
	s_nop 0
	global_load_lds_dwordx4 v[224:225], off
	s_mov_b32 m0, s33
	s_nop 0
	global_load_lds_dwordx4 v[226:227], off
	s_waitcnt vmcnt(8)
	s_waitcnt lgkmcnt(0)
	s_barrier
; #define PG8_STAGE(bufoff, gbase, voff) do { _Pragma("unroll") for (int _i = 0; _i < 2; ++_i) \
;         __builtin_amdgcn_global_load_lds((const unsigned*)((const char*)(gbase) + (voff)[_i]), (PG8_LAS unsigned*)(lds + (bufoff) + ldsw + _i * 8192), 16, 0, 0); } while (0)
; #define PG8_LDA(dst, b, h) do { _Pragma("unroll") for (int m = 0; m < 4; ++m) _Pragma("unroll") for (int k = 0; k < 2; ++k) dst[m][k] = *(const PG8_LAS bf16x8*)(lds + PG8_SA(b, h) + aoff + m * 2048 + k * 1024); } while (0)
; #define PG8_LDB(dst, b, h) do { _Pragma("unroll") for (int n = 0; n < 2; ++n) _Pragma("unroll") for (int k = 0; k < 2; ++k) dst[n][k] = *(const PG8_LAS bf16x8*)(lds + PG8_SB(b, h) + boff + n * 2048 + k * 1024); } while (0)
; #define PG8_MMA(ai, bj, At, Bt) do { __builtin_amdgcn_s_setprio(1); _Pragma("unroll") for (int m = 0; m < 4; ++m) _Pragma("unroll") for (int n = 0; n < 2; ++n) _Pragma("unroll") for (int k = 0; k < 2; ++k) \
;         acc[ai][bj][m][n] = __builtin_amdgcn_mfma_f32_16x16x32_bf16(Bt[n][k], At[m][k], acc[ai][bj][m][n], 0, 0, 0); __builtin_amdgcn_s_setprio(0); } while (0)
; #define PG8_WAIT_V(n) asm volatile("s_waitcnt vmcnt(" #n ")" ::: "memory")
; #define PG8_WAIT_L(n) asm volatile("s_waitcnt lgkmcnt(" #n ")" ::: "memory")
; #define PG8_BAR __builtin_amdgcn_s_barrier()
; #define PG8_SCHED __builtin_amdgcn_sched_barrier(0)
; template <class Epi, class Sched, bool ALIGN_EPI = false, bool SP2 = false>
; __device__ __forceinline__ void gemm_phase(PG8_LAS unsigned char* lds, const Gemm g, const Sched& S, const Epi& E) {
;     ...
;             PG8_WAIT_V(8); PG8_WAIT_L(0); PG8_BAR; PG8_MMA(1, 0, At, B0); PG8_MMA(1, 1, At, B1); PG8_BAR; PG8_SCHED;
;             PG8_LDB(B0, 1, 0); PG8_LDB(B1, 1, 1); PG8_SCHED; PG8_LDA(At, 1, 0); PG8_STAGE(PG8_SA(0, 1), a2 + hstep, voffA);
;             PG8_WAIT_V(8); PG8_WAIT_L(0); PG8_BAR; PG8_MMA(0, 0, At, B0); PG8_MMA(0, 1, At, B1); PG8_BAR; PG8_SCHED;
	s_setprio 1
	s_waitcnt lgkmcnt(0)
	v_mfma_f32_16x16x32_bf16 v[60:63], v[146:149], v[192:195], v[60:63]
	v_mfma_f32_16x16x32_bf16 v[56:59], v[164:167], v[192:195], v[56:59]
	v_mfma_f32_16x16x32_bf16 v[44:47], v[146:149], v[200:203], v[44:47]
	v_mfma_f32_16x16x32_bf16 v[40:43], v[164:167], v[200:203], v[40:43]
	v_mfma_f32_16x16x32_bf16 v[28:31], v[146:149], v[208:211], v[28:31]
	v_mfma_f32_16x16x32_bf16 v[24:27], v[164:167], v[208:211], v[24:27]
	v_mfma_f32_16x16x32_bf16 v[12:15], v[146:149], v[216:219], v[12:15]
	v_mfma_f32_16x16x32_bf16 v[8:11], v[164:167], v[216:219], v[8:11]
	v_mfma_f32_16x16x32_bf16 v[60:63], v[150:153], v[196:199], v[60:63]
	v_mfma_f32_16x16x32_bf16 v[56:59], v[168:171], v[196:199], v[56:59]
	v_mfma_f32_16x16x32_bf16 v[44:47], v[150:153], v[204:207], v[44:47]
	v_mfma_f32_16x16x32_bf16 v[40:43], v[168:171], v[204:207], v[40:43]
	v_mfma_f32_16x16x32_bf16 v[28:31], v[150:153], v[212:215], v[28:31]
	v_mfma_f32_16x16x32_bf16 v[24:27], v[168:171], v[212:215], v[24:27]
	v_mfma_f32_16x16x32_bf16 v[12:15], v[150:153], v[220:223], v[12:15]
	v_mfma_f32_16x16x32_bf16 v[8:11], v[168:171], v[220:223], v[8:11]
	s_setprio 0
	s_setprio 1
	v_mfma_f32_16x16x32_bf16 v[52:55], v[172:175], v[192:195], v[52:55]
	v_mfma_f32_16x16x32_bf16 v[48:51], v[180:183], v[192:195], v[48:51]
	v_mfma_f32_16x16x32_bf16 v[36:39], v[172:175], v[200:203], v[36:39]
	v_mfma_f32_16x16x32_bf16 v[32:35], v[180:183], v[200:203], v[32:35]
	v_mfma_f32_16x16x32_bf16 v[20:23], v[172:175], v[208:211], v[20:23]
	v_mfma_f32_16x16x32_bf16 v[16:19], v[180:183], v[208:211], v[16:19]
	v_mfma_f32_16x16x32_bf16 v[4:7], v[172:175], v[216:219], v[4:7]
	v_mfma_f32_16x16x32_bf16 v[0:3], v[180:183], v[216:219], v[0:3]
	v_mfma_f32_16x16x32_bf16 v[52:55], v[176:179], v[196:199], v[52:55]
	v_mfma_f32_16x16x32_bf16 v[48:51], v[188:191], v[196:199], v[48:51]
	v_mfma_f32_16x16x32_bf16 v[36:39], v[176:179], v[204:207], v[36:39]
	v_mfma_f32_16x16x32_bf16 v[32:35], v[188:191], v[204:207], v[32:35]
	v_mfma_f32_16x16x32_bf16 v[20:23], v[176:179], v[212:215], v[20:23]
	v_mfma_f32_16x16x32_bf16 v[16:19], v[188:191], v[212:215], v[16:19]
	v_mfma_f32_16x16x32_bf16 v[4:7], v[176:179], v[220:223], v[4:7]
	v_mfma_f32_16x16x32_bf16 v[0:3], v[188:191], v[220:223], v[0:3]
	s_setprio 0
	s_barrier
	s_add_i32 s47, 0, 0x18000
	v_add_u32_e32 v136, s47, v157
	s_add_i32 s48, 0, 0x1c000
	ds_read_b128 v[146:149], v136
	ds_read_b128 v[150:153], v136 offset:1024
	ds_read_b128 v[164:167], v136 offset:2048
	ds_read_b128 v[168:171], v136 offset:3072
	v_add_u32_e32 v136, s48, v157
	ds_read_b128 v[172:175], v136
	ds_read_b128 v[176:179], v136 offset:1024
	ds_read_b128 v[180:183], v136 offset:2048
	ds_read_b128 v[188:191], v136 offset:3072
	s_add_u32 s26, s26, 0x40000
	s_addc_u32 s27, s27, 0
	s_mov_b32 m0, s34
	v_lshl_add_u64 v[228:229], s[26:27], 0, v[128:129]
	ds_read_b128 v[192:195], v162 offset:32768
	ds_read_b128 v[196:199], v162 offset:33792
	ds_read_b128 v[200:203], v162 offset:34816
	ds_read_b128 v[204:207], v162 offset:35840
	ds_read_b128 v[208:211], v162 offset:36864
	ds_read_b128 v[212:215], v162 offset:37888
	ds_read_b128 v[216:219], v162 offset:38912
	ds_read_b128 v[220:223], v162 offset:39936
	global_load_lds_dwordx4 v[228:229], off
	v_lshl_add_u64 v[228:229], s[26:27], 0, v[132:133]
	s_mov_b32 m0, s35
	s_nop 0
	global_load_lds_dwordx4 v[228:229], off
	s_waitcnt vmcnt(8)
	s_waitcnt lgkmcnt(0)
	s_barrier
	s_setprio 1
	s_waitcnt lgkmcnt(0)
	v_mfma_f32_16x16x32_bf16 v[124:127], v[146:149], v[192:195], v[124:127]
	v_mfma_f32_16x16x32_bf16 v[120:123], v[164:167], v[192:195], v[120:123]
	v_mfma_f32_16x16x32_bf16 v[108:111], v[146:149], v[200:203], v[108:111]
	v_mfma_f32_16x16x32_bf16 v[104:107], v[164:167], v[200:203], v[104:107]
	v_mfma_f32_16x16x32_bf16 v[92:95], v[146:149], v[208:211], v[92:95]
	v_mfma_f32_16x16x32_bf16 v[88:91], v[164:167], v[208:211], v[88:91]
	v_mfma_f32_16x16x32_bf16 v[76:79], v[146:149], v[216:219], v[76:79]
	v_mfma_f32_16x16x32_bf16 v[72:75], v[164:167], v[216:219], v[72:75]
	v_mfma_f32_16x16x32_bf16 v[124:127], v[150:153], v[196:199], v[124:127]
	v_mfma_f32_16x16x32_bf16 v[120:123], v[168:171], v[196:199], v[120:123]
	v_mfma_f32_16x16x32_bf16 v[108:111], v[150:153], v[204:207], v[108:111]
	v_mfma_f32_16x16x32_bf16 v[104:107], v[168:171], v[204:207], v[104:107]
	v_mfma_f32_16x16x32_bf16 v[92:95], v[150:153], v[212:215], v[92:95]
	v_mfma_f32_16x16x32_bf16 v[88:91], v[168:171], v[212:215], v[88:91]
	v_mfma_f32_16x16x32_bf16 v[76:79], v[150:153], v[220:223], v[76:79]
	v_mfma_f32_16x16x32_bf16 v[72:75], v[168:171], v[220:223], v[72:75]
	s_setprio 0
	s_setprio 1
	v_mfma_f32_16x16x32_bf16 v[116:119], v[172:175], v[192:195], v[116:119]
	v_mfma_f32_16x16x32_bf16 v[112:115], v[180:183], v[192:195], v[112:115]
	v_mfma_f32_16x16x32_bf16 v[100:103], v[172:175], v[200:203], v[100:103]
	v_mfma_f32_16x16x32_bf16 v[96:99], v[180:183], v[200:203], v[96:99]
	v_mfma_f32_16x16x32_bf16 v[84:87], v[172:175], v[208:211], v[84:87]
	v_mfma_f32_16x16x32_bf16 v[80:83], v[180:183], v[208:211], v[80:83]
	v_mfma_f32_16x16x32_bf16 v[68:71], v[172:175], v[216:219], v[68:71]
	v_mfma_f32_16x16x32_bf16 v[64:67], v[180:183], v[216:219], v[64:67]
	v_mfma_f32_16x16x32_bf16 v[116:119], v[176:179], v[196:199], v[116:119]
	v_mfma_f32_16x16x32_bf16 v[112:115], v[188:191], v[196:199], v[112:115]
	v_mfma_f32_16x16x32_bf16 v[100:103], v[176:179], v[204:207], v[100:103]
	v_mfma_f32_16x16x32_bf16 v[96:99], v[188:191], v[204:207], v[96:99]
	v_mfma_f32_16x16x32_bf16 v[84:87], v[176:179], v[212:215], v[84:87]
	v_mfma_f32_16x16x32_bf16 v[80:83], v[188:191], v[212:215], v[80:83]
	v_mfma_f32_16x16x32_bf16 v[68:71], v[176:179], v[220:223], v[68:71]
	v_mfma_f32_16x16x32_bf16 v[64:67], v[188:191], v[220:223], v[64:67]
	s_setprio 0
	s_barrier
; #define PG8_STAGE(bufoff, gbase, voff) do { _Pragma("unroll") for (int _i = 0; _i < 2; ++_i) \
;         __builtin_amdgcn_global_load_lds((const unsigned*)((const char*)(gbase) + (voff)[_i]), (PG8_LAS unsigned*)(lds + (bufoff) + ldsw + _i * 8192), 16, 0, 0); } while (0)
; #define PG8_LDA(dst, b, h) do { _Pragma("unroll") for (int m = 0; m < 4; ++m) _Pragma("unroll") for (int k = 0; k < 2; ++k) dst[m][k] = *(const PG8_LAS bf16x8*)(lds + PG8_SA(b, h) + aoff + m * 2048 + k * 1024); } while (0)
; #define PG8_MMA(ai, bj, At, Bt) do { __builtin_amdgcn_s_setprio(1); _Pragma("unroll") for (int m = 0; m < 4; ++m) _Pragma("unroll") for (int n = 0; n < 2; ++n) _Pragma("unroll") for (int k = 0; k < 2; ++k) \
;         acc[ai][bj][m][n] = __builtin_amdgcn_mfma_f32_16x16x32_bf16(Bt[n][k], At[m][k], acc[ai][bj][m][n], 0, 0, 0); __builtin_amdgcn_s_setprio(0); } while (0)
; #define PG8_WAIT_V(n) asm volatile("s_waitcnt vmcnt(" #n ")" ::: "memory")
; #define PG8_WAIT_L(n) asm volatile("s_waitcnt lgkmcnt(" #n ")" ::: "memory")
; #define PG8_BAR __builtin_amdgcn_s_barrier()
; #define PG8_SCHED __builtin_amdgcn_sched_barrier(0)
; template <class Epi, class Sched, bool ALIGN_EPI = false, bool SP2 = false>
; __device__ __forceinline__ void gemm_phase(PG8_LAS unsigned char* lds, const Gemm g, const Sched& S, const Epi& E) {
;     ...
;         for (int t = 0; t < nt; t += 2) {
;     ...
;             PG8_LDA(At, 1, 1); PG8_STAGE(PG8_SB(1, 0), b3, voffB); PG8_STAGE(PG8_SB(1, 1), b3 + hstep, voffB); PG8_STAGE(PG8_SA(1, 0), a3, voffA);
;             PG8_WAIT_V(8); PG8_WAIT_L(0); PG8_BAR; PG8_MMA(1, 0, At, B0); PG8_MMA(1, 1, At, B1); PG8_BAR; PG8_SCHED;
;     ...
;         if constexpr (ALIGN_EPI) { if (wr == 0) PG8_BAR; }
	s_add_i32 s26, s47, s28
	v_lshl_add_u64 v[154:155], v[154:155], 0, s[8:9]
	s_mov_b32 m0, s26
	ds_read_b128 v[192:195], v162 offset:49152
	ds_read_b128 v[196:199], v162 offset:50176
	ds_read_b128 v[200:203], v162 offset:51200
	ds_read_b128 v[204:207], v162 offset:52224
	ds_read_b128 v[208:211], v162 offset:53248
	ds_read_b128 v[212:215], v162 offset:54272
	ds_read_b128 v[216:219], v162 offset:55296
	ds_read_b128 v[220:223], v162 offset:56320
	global_load_lds_dwordx4 v[154:155], off
	s_add_i32 m0, s26, 0x2000
	s_add_u32 s24, s24, 0x40080
	v_lshl_add_u64 v[154:155], v[184:185], 0, s[8:9]
	s_addc_u32 s25, s25, 0
	s_add_i32 s26, s48, s28
	global_load_lds_dwordx4 v[154:155], off
	v_lshl_add_u64 v[154:155], s[24:25], 0, v[130:131]
	s_mov_b32 m0, s26
	s_nop 0
	global_load_lds_dwordx4 v[154:155], off
	v_lshl_add_u64 v[154:155], s[24:25], 0, v[134:135]
	s_add_i32 m0, s26, 0x2000
	s_nop 0
	global_load_lds_dwordx4 v[154:155], off
	v_lshl_add_u64 v[154:155], v[224:225], 0, s[8:9]
	s_mov_b32 m0, s36
	s_nop 0
	global_load_lds_dwordx4 v[154:155], off
	v_lshl_add_u64 v[154:155], v[226:227], 0, s[8:9]
	s_mov_b32 m0, s37
	s_nop 0
	global_load_lds_dwordx4 v[154:155], off
	s_waitcnt vmcnt(8)
	s_waitcnt lgkmcnt(0)
	s_barrier
	s_setprio 1
	s_waitcnt lgkmcnt(0)
	v_mfma_f32_16x16x32_bf16 v[60:63], v[146:149], v[192:195], v[60:63]
	v_mfma_f32_16x16x32_bf16 v[56:59], v[164:167], v[192:195], v[56:59]
	v_mfma_f32_16x16x32_bf16 v[44:47], v[146:149], v[200:203], v[44:47]
	v_mfma_f32_16x16x32_bf16 v[40:43], v[164:167], v[200:203], v[40:43]
	v_mfma_f32_16x16x32_bf16 v[28:31], v[146:149], v[208:211], v[28:31]
	v_mfma_f32_16x16x32_bf16 v[24:27], v[164:167], v[208:211], v[24:27]
	v_mfma_f32_16x16x32_bf16 v[12:15], v[146:149], v[216:219], v[12:15]
	v_mfma_f32_16x16x32_bf16 v[8:11], v[164:167], v[216:219], v[8:11]
	v_mfma_f32_16x16x32_bf16 v[60:63], v[150:153], v[196:199], v[60:63]
	v_mfma_f32_16x16x32_bf16 v[56:59], v[168:171], v[196:199], v[56:59]
	v_mfma_f32_16x16x32_bf16 v[44:47], v[150:153], v[204:207], v[44:47]
	v_mfma_f32_16x16x32_bf16 v[40:43], v[168:171], v[204:207], v[40:43]
	v_mfma_f32_16x16x32_bf16 v[28:31], v[150:153], v[212:215], v[28:31]
	v_mfma_f32_16x16x32_bf16 v[24:27], v[168:171], v[212:215], v[24:27]
	v_mfma_f32_16x16x32_bf16 v[12:15], v[150:153], v[220:223], v[12:15]
	v_mfma_f32_16x16x32_bf16 v[8:11], v[168:171], v[220:223], v[8:11]
	s_setprio 0
	s_setprio 1
	v_mfma_f32_16x16x32_bf16 v[52:55], v[172:175], v[192:195], v[52:55]
	v_mfma_f32_16x16x32_bf16 v[48:51], v[180:183], v[192:195], v[48:51]
	v_mfma_f32_16x16x32_bf16 v[36:39], v[172:175], v[200:203], v[36:39]
	v_mfma_f32_16x16x32_bf16 v[32:35], v[180:183], v[200:203], v[32:35]
	v_mfma_f32_16x16x32_bf16 v[20:23], v[172:175], v[208:211], v[20:23]
	v_mfma_f32_16x16x32_bf16 v[16:19], v[180:183], v[208:211], v[16:19]
	v_mfma_f32_16x16x32_bf16 v[4:7], v[172:175], v[216:219], v[4:7]
	v_mfma_f32_16x16x32_bf16 v[0:3], v[180:183], v[216:219], v[0:3]
	v_mfma_f32_16x16x32_bf16 v[52:55], v[176:179], v[196:199], v[52:55]
	v_mfma_f32_16x16x32_bf16 v[48:51], v[188:191], v[196:199], v[48:51]
	v_mfma_f32_16x16x32_bf16 v[36:39], v[176:179], v[204:207], v[36:39]
	v_mfma_f32_16x16x32_bf16 v[32:35], v[188:191], v[204:207], v[32:35]
	v_mfma_f32_16x16x32_bf16 v[20:23], v[176:179], v[212:215], v[20:23]
	v_mfma_f32_16x16x32_bf16 v[16:19], v[188:191], v[212:215], v[16:19]
	v_mfma_f32_16x16x32_bf16 v[4:7], v[176:179], v[220:223], v[4:7]
	v_mfma_f32_16x16x32_bf16 v[0:3], v[188:191], v[220:223], v[0:3]
	s_setprio 0
	s_add_i32 s46, s46, 2
	s_add_u32 s22, s22, 0x100
	s_addc_u32 s23, s23, 0
	s_add_u32 s44, s44, 0x100
	s_addc_u32 s45, s45, 0
	s_cmp_gt_u32 s46, 13
	s_cbranch_scc0 .Lrot_572
	s_barrier
	s_and_b64 vcc, exec, s[10:11]
	s_cbranch_vccz .LBB0_575
	s_barrier

;     __device__ __forceinline__ bool next(int i, Unit& u) const { if (!base.next(i >> 1, u)) return false; if (i & 1) { u.pm += 64; u.pn += 8; } return true; }
; #define PG8_STAGE(bufoff, gbase, voff) do { _Pragma("unroll") for (int _i = 0; _i < 2; ++_i) \
;         __builtin_amdgcn_global_load_lds((const unsigned*)((const char*)(gbase) + (voff)[_i]), (PG8_LAS unsigned*)(lds + (bufoff) + ldsw + _i * 8192), 16, 0, 0); } while (0)
; #define PG8_LDA(dst, b, h) do { _Pragma("unroll") for (int m = 0; m < 4; ++m) _Pragma("unroll") for (int k = 0; k < 2; ++k) dst[m][k] = *(const PG8_LAS bf16x8*)(lds + PG8_SA(b, h) + aoff + m * 2048 + k * 1024); } while (0)
; #define PG8_LDB(dst, b, h) do { _Pragma("unroll") for (int n = 0; n < 2; ++n) _Pragma("unroll") for (int k = 0; k < 2; ++k) dst[n][k] = *(const PG8_LAS bf16x8*)(lds + PG8_SB(b, h) + boff + n * 2048 + k * 1024); } while (0)
; #define PG8_WAIT_V(n) asm volatile("s_waitcnt vmcnt(" #n ")" ::: "memory")
; #define PG8_WAIT_L(n) asm volatile("s_waitcnt lgkmcnt(" #n ")" ::: "memory")
; #define PG8_BAR __builtin_amdgcn_s_barrier()
; #define PG8_SCHED __builtin_amdgcn_sched_barrier(0)
; template <class Epi, class Sched, bool ALIGN_EPI = false, bool SP2 = false>
; __device__ __forceinline__ void gemm_phase(PG8_LAS unsigned char* lds, const Gemm g, const Sched& S, const Epi& E) {
;     ...
;         const bool has_next = S.next(ui + 1, nxt);
;         const char* nA = has_next ? (const char*)g.A + (size_t)nxt.pm * tstep : cA; const char* nB = has_next ? (const char*)g.Bt + (size_t)nxt.pn * tstep : cB;
;         for (int t = 0; t < nt; t += 2) {
;             const bool last = (t == nt - 2);
;             const char* a1 = cA + (size_t)(t + 1) * kstep;
;             const char* a2 = last ? nA : cA + (size_t)(t + 2) * kstep; const char* b2 = last ? nB : cB + (size_t)(t + 2) * kstep;
;             const char* a3 = a2 + kstep; const char* b3 = b2 + kstep;
;             if (last && has_next) S.a_ready(nxt);
;             if constexpr (SP2) {
;             PG8_LDB(B0, 0, 0); PG8_LDB(B1, 0, 1); PG8_SCHED; PG8_LDA(At, 0, 0); PG8_STAGE(PG8_SA(1, 1), a1 + hstep, voffA);
;             PG8_WAIT_V(8); PG8_WAIT_L(0); PG8_BAR; PG8_MMA(0, 0, At, B0); PG8_MMA(0, 1, At, B1); PG8_BAR; PG8_SCHED;
;             PG8_LDA(At, 0, 1); PG8_STAGE(PG8_SB(0, 0), b2, voffB); PG8_STAGE(PG8_SB(0, 1), b2 + hstep, voffB); PG8_STAGE(PG8_SA(0, 0), a2, voffA);
.LBB0_893:
	s_ashr_i32 s25, s24, 31
	s_lshl_b64 s[28:29], s[24:25], 20
	v_readlane_b32 s30, v236, 50
	v_readlane_b32 s31, v236, 51
	s_add_u32 s28, s30, s28
	s_addc_u32 s29, s31, s29
	s_and_b64 s[30:31], s[6:7], exec
	s_cselect_b32 s25, s29, s39
	s_cselect_b32 s35, s28, s38
	s_ashr_i32 s27, s26, 31
	s_lshl_b64 s[30:31], s[26:27], 20
	v_readlane_b32 s42, v236, 43
	v_readlane_b32 s43, v236, 44
	s_add_u32 s30, s42, s30
	s_addc_u32 s31, s43, s31
	s_and_b64 s[42:43], s[6:7], exec
	s_cselect_b32 s27, s31, s41
	s_cselect_b32 s55, s30, s40
	s_add_u32 s38, s38, 0x80080
	s_addc_u32 s39, s39, 0
	s_add_u32 s56, s40, 0x100
	s_addc_u32 s57, s41, 0
	s_mov_b32 s58, -2
	s_waitcnt lgkmcnt(0)
	ds_read_b128 v[72:75], v169
	ds_read_b128 v[84:87], v169 offset:1024
	ds_read_b128 v[92:95], v169 offset:2048
	ds_read_b128 v[96:99], v169 offset:3072
	ds_read_b128 v[156:159], v170
	ds_read_b128 v[160:163], v170 offset:1024
	ds_read_b128 v[174:177], v170 offset:2048
	ds_read_b128 v[178:181], v170 offset:3072
	s_add_u32 s40, s38, 0xfff80080
	s_addc_u32 s41, s39, -1
	s_cmp_eq_u32 s58, 28
	s_cselect_b32 s43, s25, s41
	s_cselect_b32 s42, s35, s40
	s_cselect_b32 s41, s27, s57
	s_cselect_b32 s40, s55, s56
	v_lshl_add_u64 v[164:165], s[38:39], 0, v[148:149]
	s_add_i32 m0, s37, 0xc000
	ds_read_b128 v[182:185], v171
	ds_read_b128 v[188:191], v171 offset:1024
	ds_read_b128 v[192:195], v171 offset:2048
	ds_read_b128 v[196:199], v171 offset:3072
	ds_read_b128 v[200:203], v171 offset:4096
	ds_read_b128 v[204:207], v171 offset:5120
	ds_read_b128 v[208:211], v171 offset:6144
	ds_read_b128 v[212:215], v171 offset:7168
	global_load_lds_dwordx4 v[164:165], off
	v_lshl_add_u64 v[164:165], s[38:39], 0, v[150:151]
	s_add_i32 m0, s37, 0xe000
	s_nop 0
	global_load_lds_dwordx4 v[164:165], off
	s_waitcnt vmcnt(8)
	s_waitcnt lgkmcnt(0)
	s_barrier
	s_setprio 1
	s_waitcnt lgkmcnt(0)
	v_mfma_f32_16x16x32_bf16 v[140:143], v[72:75], v[182:185], 0
	v_mfma_f32_16x16x32_bf16 v[136:139], v[92:95], v[182:185], 0
	v_mfma_f32_16x16x32_bf16 v[124:127], v[72:75], v[192:195], 0
	v_mfma_f32_16x16x32_bf16 v[120:123], v[92:95], v[192:195], 0
	v_mfma_f32_16x16x32_bf16 v[108:111], v[72:75], v[200:203], 0
	v_mfma_f32_16x16x32_bf16 v[104:107], v[92:95], v[200:203], 0
	v_mfma_f32_16x16x32_bf16 v[80:83], v[72:75], v[208:211], 0
	v_mfma_f32_16x16x32_bf16 v[76:79], v[92:95], v[208:211], 0
	v_mfma_f32_16x16x32_bf16 v[140:143], v[84:87], v[188:191], v[140:143]
	v_mfma_f32_16x16x32_bf16 v[136:139], v[96:99], v[188:191], v[136:139]
	v_mfma_f32_16x16x32_bf16 v[124:127], v[84:87], v[196:199], v[124:127]
	v_mfma_f32_16x16x32_bf16 v[120:123], v[96:99], v[196:199], v[120:123]
	v_mfma_f32_16x16x32_bf16 v[108:111], v[84:87], v[204:207], v[108:111]
	v_mfma_f32_16x16x32_bf16 v[104:107], v[96:99], v[204:207], v[104:107]
	v_mfma_f32_16x16x32_bf16 v[80:83], v[84:87], v[212:215], v[80:83]
	v_mfma_f32_16x16x32_bf16 v[76:79], v[96:99], v[212:215], v[76:79]
	s_setprio 0
	s_setprio 1
	v_mfma_f32_16x16x32_bf16 v[132:135], v[156:159], v[182:185], 0
	v_mfma_f32_16x16x32_bf16 v[128:131], v[174:177], v[182:185], 0
	v_mfma_f32_16x16x32_bf16 v[116:119], v[156:159], v[192:195], 0
	v_mfma_f32_16x16x32_bf16 v[112:115], v[174:177], v[192:195], 0
	v_mfma_f32_16x16x32_bf16 v[100:103], v[156:159], v[200:203], 0
	v_mfma_f32_16x16x32_bf16 v[88:91], v[174:177], v[200:203], 0
	v_mfma_f32_16x16x32_bf16 v[68:71], v[156:159], v[208:211], 0
	v_mfma_f32_16x16x32_bf16 v[64:67], v[174:177], v[208:211], 0
	v_mfma_f32_16x16x32_bf16 v[132:135], v[160:163], v[188:191], v[132:135]
	v_mfma_f32_16x16x32_bf16 v[128:131], v[178:181], v[188:191], v[128:131]
	v_mfma_f32_16x16x32_bf16 v[116:119], v[160:163], v[196:199], v[116:119]
	v_mfma_f32_16x16x32_bf16 v[112:115], v[178:181], v[196:199], v[112:115]
	v_mfma_f32_16x16x32_bf16 v[100:103], v[160:163], v[204:207], v[100:103]
	v_mfma_f32_16x16x32_bf16 v[88:91], v[178:181], v[204:207], v[88:91]
	v_mfma_f32_16x16x32_bf16 v[68:71], v[160:163], v[212:215], v[68:71]
	v_mfma_f32_16x16x32_bf16 v[64:67], v[178:181], v[212:215], v[64:67]
	s_setprio 0
	s_barrier
	s_add_i32 s59, s53, s33
	v_lshl_add_u64 v[164:165], s[40:41], 0, v[144:145]
	s_mov_b32 m0, s59
	ds_read_b128 v[182:185], v171 offset:16384
	ds_read_b128 v[188:191], v171 offset:17408
	ds_read_b128 v[192:195], v171 offset:18432
	ds_read_b128 v[196:199], v171 offset:19456
	ds_read_b128 v[200:203], v171 offset:20480
	ds_read_b128 v[204:207], v171 offset:21504
	ds_read_b128 v[208:211], v171 offset:22528
	ds_read_b128 v[212:215], v171 offset:23552
	global_load_lds_dwordx4 v[164:165], off
	s_add_i32 m0, s59, 0x2000
	s_add_u32 s60, s40, 0x80000
	v_lshl_add_u64 v[216:217], s[40:41], 0, v[146:147]
	s_addc_u32 s61, s41, 0
	s_add_i32 s59, s54, s33
	global_load_lds_dwordx4 v[216:217], off
	v_lshl_add_u64 v[218:219], s[60:61], 0, v[144:145]
	s_mov_b32 m0, s59
	v_lshl_add_u64 v[220:221], s[42:43], 0, v[146:147]
	global_load_lds_dwordx4 v[218:219], off
	v_lshl_add_u64 v[218:219], s[60:61], 0, v[146:147]
	s_add_i32 m0, s59, 0x2000
	s_nop 0
	global_load_lds_dwordx4 v[218:219], off
	v_lshl_add_u64 v[218:219], s[42:43], 0, v[144:145]
	s_mov_b32 m0, s37
	s_nop 0
	global_load_lds_dwordx4 v[218:219], off
	s_mov_b32 m0, s44
	s_nop 0
	global_load_lds_dwordx4 v[220:221], off
	s_waitcnt vmcnt(8)
	s_waitcnt lgkmcnt(0)
	s_barrier
; #define PG8_STAGE(bufoff, gbase, voff) do { _Pragma("unroll") for (int _i = 0; _i < 2; ++_i) \
;         __builtin_amdgcn_global_load_lds((const unsigned*)((const char*)(gbase) + (voff)[_i]), (PG8_LAS unsigned*)(lds + (bufoff) + ldsw + _i * 8192), 16, 0, 0); } while (0)
; #define PG8_LDA(dst, b, h) do { _Pragma("unroll") for (int m = 0; m < 4; ++m) _Pragma("unroll") for (int k = 0; k < 2; ++k) dst[m][k] = *(const PG8_LAS bf16x8*)(lds + PG8_SA(b, h) + aoff + m * 2048 + k * 1024); } while (0)
; #define PG8_LDB(dst, b, h) do { _Pragma("unroll") for (int n = 0; n < 2; ++n) _Pragma("unroll") for (int k = 0; k < 2; ++k) dst[n][k] = *(const PG8_LAS bf16x8*)(lds + PG8_SB(b, h) + boff + n * 2048 + k * 1024); } while (0)
; #define PG8_MMA(ai, bj, At, Bt) do { __builtin_amdgcn_s_setprio(1); _Pragma("unroll") for (int m = 0; m < 4; ++m) _Pragma("unroll") for (int n = 0; n < 2; ++n) _Pragma("unroll") for (int k = 0; k < 2; ++k) \
;         acc[ai][bj][m][n] = __builtin_amdgcn_mfma_f32_16x16x32_bf16(Bt[n][k], At[m][k], acc[ai][bj][m][n], 0, 0, 0); __builtin_amdgcn_s_setprio(0); } while (0)
; #define PG8_WAIT_V(n) asm volatile("s_waitcnt vmcnt(" #n ")" ::: "memory")
; #define PG8_WAIT_L(n) asm volatile("s_waitcnt lgkmcnt(" #n ")" ::: "memory")
; #define PG8_BAR __builtin_amdgcn_s_barrier()
; #define PG8_SCHED __builtin_amdgcn_sched_barrier(0)
; template <class Epi, class Sched, bool ALIGN_EPI = false, bool SP2 = false>
; __device__ __forceinline__ void gemm_phase(PG8_LAS unsigned char* lds, const Gemm g, const Sched& S, const Epi& E) {
;     ...
;             PG8_WAIT_V(8); PG8_WAIT_L(0); PG8_BAR; PG8_MMA(1, 0, At, B0); PG8_MMA(1, 1, At, B1); PG8_BAR; PG8_SCHED;
;             PG8_LDB(B0, 1, 0); PG8_LDB(B1, 1, 1); PG8_SCHED; PG8_LDA(At, 1, 0); PG8_STAGE(PG8_SA(0, 1), a2 + hstep, voffA);
;             PG8_WAIT_V(8); PG8_WAIT_L(0); PG8_BAR; PG8_MMA(0, 0, At, B0); PG8_MMA(0, 1, At, B1); PG8_BAR; PG8_SCHED;
	s_setprio 1
	s_waitcnt lgkmcnt(0)
	v_mfma_f32_16x16x32_bf16 v[60:63], v[72:75], v[182:185], 0
	v_mfma_f32_16x16x32_bf16 v[56:59], v[92:95], v[182:185], 0
	v_mfma_f32_16x16x32_bf16 v[44:47], v[72:75], v[192:195], 0
	v_mfma_f32_16x16x32_bf16 v[40:43], v[92:95], v[192:195], 0
	v_mfma_f32_16x16x32_bf16 v[28:31], v[72:75], v[200:203], 0
	v_mfma_f32_16x16x32_bf16 v[24:27], v[92:95], v[200:203], 0
	v_mfma_f32_16x16x32_bf16 v[12:15], v[72:75], v[208:211], 0
	v_mfma_f32_16x16x32_bf16 v[8:11], v[92:95], v[208:211], 0
	v_mfma_f32_16x16x32_bf16 v[60:63], v[84:87], v[188:191], v[60:63]
	v_mfma_f32_16x16x32_bf16 v[56:59], v[96:99], v[188:191], v[56:59]
	v_mfma_f32_16x16x32_bf16 v[44:47], v[84:87], v[196:199], v[44:47]
	v_mfma_f32_16x16x32_bf16 v[40:43], v[96:99], v[196:199], v[40:43]
	v_mfma_f32_16x16x32_bf16 v[28:31], v[84:87], v[204:207], v[28:31]
	v_mfma_f32_16x16x32_bf16 v[24:27], v[96:99], v[204:207], v[24:27]
	v_mfma_f32_16x16x32_bf16 v[12:15], v[84:87], v[212:215], v[12:15]
	v_mfma_f32_16x16x32_bf16 v[8:11], v[96:99], v[212:215], v[8:11]
	s_setprio 0
	s_setprio 1
	v_mfma_f32_16x16x32_bf16 v[52:55], v[156:159], v[182:185], 0
	v_mfma_f32_16x16x32_bf16 v[48:51], v[174:177], v[182:185], 0
	v_mfma_f32_16x16x32_bf16 v[36:39], v[156:159], v[192:195], 0
	v_mfma_f32_16x16x32_bf16 v[32:35], v[174:177], v[192:195], 0
	v_mfma_f32_16x16x32_bf16 v[20:23], v[156:159], v[200:203], 0
	v_mfma_f32_16x16x32_bf16 v[16:19], v[174:177], v[200:203], 0
	v_mfma_f32_16x16x32_bf16 v[4:7], v[156:159], v[208:211], 0
	v_mfma_f32_16x16x32_bf16 v[0:3], v[174:177], v[208:211], 0
	v_mfma_f32_16x16x32_bf16 v[52:55], v[160:163], v[188:191], v[52:55]
	v_mfma_f32_16x16x32_bf16 v[48:51], v[178:181], v[188:191], v[48:51]
	v_mfma_f32_16x16x32_bf16 v[36:39], v[160:163], v[196:199], v[36:39]
	v_mfma_f32_16x16x32_bf16 v[32:35], v[178:181], v[196:199], v[32:35]
	v_mfma_f32_16x16x32_bf16 v[20:23], v[160:163], v[204:207], v[20:23]
	v_mfma_f32_16x16x32_bf16 v[16:19], v[178:181], v[204:207], v[16:19]
	v_mfma_f32_16x16x32_bf16 v[4:7], v[160:163], v[212:215], v[4:7]
	v_mfma_f32_16x16x32_bf16 v[0:3], v[178:181], v[212:215], v[0:3]
	s_setprio 0
	s_barrier
	s_add_i32 s59, 0, 0x18000
	s_add_i32 s60, 0, 0x1c000
	v_add_u32_e32 v96, s59, v167
	v_add_u32_e32 v173, s60, v167
	ds_read_b128 v[72:75], v96
	ds_read_b128 v[84:87], v96 offset:1024
	ds_read_b128 v[92:95], v96 offset:2048
	ds_read_b128 v[96:99], v96 offset:3072
	ds_read_b128 v[156:159], v173
	ds_read_b128 v[160:163], v173 offset:1024
	ds_read_b128 v[174:177], v173 offset:2048
	ds_read_b128 v[178:181], v173 offset:3072
	s_add_u32 s42, s42, 0x80000
	s_addc_u32 s43, s43, 0
	s_mov_b32 m0, s45
	v_lshl_add_u64 v[222:223], s[42:43], 0, v[144:145]
	ds_read_b128 v[182:185], v171 offset:32768
	ds_read_b128 v[188:191], v171 offset:33792
	ds_read_b128 v[192:195], v171 offset:34816
	ds_read_b128 v[196:199], v171 offset:35840
	ds_read_b128 v[200:203], v171 offset:36864
	ds_read_b128 v[204:207], v171 offset:37888
	ds_read_b128 v[208:211], v171 offset:38912
	ds_read_b128 v[212:215], v171 offset:39936
	global_load_lds_dwordx4 v[222:223], off
	v_lshl_add_u64 v[222:223], s[42:43], 0, v[146:147]
	s_mov_b32 m0, s46
	s_nop 0
	global_load_lds_dwordx4 v[222:223], off
	s_waitcnt vmcnt(8)
	s_waitcnt lgkmcnt(0)
	s_barrier
	s_setprio 1
	s_waitcnt lgkmcnt(0)
	v_mfma_f32_16x16x32_bf16 v[140:143], v[72:75], v[182:185], v[140:143]
	v_mfma_f32_16x16x32_bf16 v[136:139], v[92:95], v[182:185], v[136:139]
	v_mfma_f32_16x16x32_bf16 v[124:127], v[72:75], v[192:195], v[124:127]
	v_mfma_f32_16x16x32_bf16 v[120:123], v[92:95], v[192:195], v[120:123]
	v_mfma_f32_16x16x32_bf16 v[108:111], v[72:75], v[200:203], v[108:111]
	v_mfma_f32_16x16x32_bf16 v[104:107], v[92:95], v[200:203], v[104:107]
	v_mfma_f32_16x16x32_bf16 v[80:83], v[72:75], v[208:211], v[80:83]
	v_mfma_f32_16x16x32_bf16 v[76:79], v[92:95], v[208:211], v[76:79]
	v_mfma_f32_16x16x32_bf16 v[140:143], v[84:87], v[188:191], v[140:143]
	v_mfma_f32_16x16x32_bf16 v[136:139], v[96:99], v[188:191], v[136:139]
	v_mfma_f32_16x16x32_bf16 v[124:127], v[84:87], v[196:199], v[124:127]
	v_mfma_f32_16x16x32_bf16 v[120:123], v[96:99], v[196:199], v[120:123]
	v_mfma_f32_16x16x32_bf16 v[108:111], v[84:87], v[204:207], v[108:111]
	v_mfma_f32_16x16x32_bf16 v[104:107], v[96:99], v[204:207], v[104:107]
	v_mfma_f32_16x16x32_bf16 v[80:83], v[84:87], v[212:215], v[80:83]
	v_mfma_f32_16x16x32_bf16 v[76:79], v[96:99], v[212:215], v[76:79]
	s_setprio 0
	s_setprio 1
	v_mfma_f32_16x16x32_bf16 v[132:135], v[156:159], v[182:185], v[132:135]
	v_mfma_f32_16x16x32_bf16 v[128:131], v[174:177], v[182:185], v[128:131]
	v_mfma_f32_16x16x32_bf16 v[116:119], v[156:159], v[192:195], v[116:119]
	v_mfma_f32_16x16x32_bf16 v[112:115], v[174:177], v[192:195], v[112:115]
	v_mfma_f32_16x16x32_bf16 v[100:103], v[156:159], v[200:203], v[100:103]
	v_mfma_f32_16x16x32_bf16 v[88:91], v[174:177], v[200:203], v[88:91]
	v_mfma_f32_16x16x32_bf16 v[68:71], v[156:159], v[208:211], v[68:71]
	v_mfma_f32_16x16x32_bf16 v[64:67], v[174:177], v[208:211], v[64:67]
	v_mfma_f32_16x16x32_bf16 v[132:135], v[160:163], v[188:191], v[132:135]
	v_mfma_f32_16x16x32_bf16 v[128:131], v[178:181], v[188:191], v[128:131]
	v_mfma_f32_16x16x32_bf16 v[116:119], v[160:163], v[196:199], v[116:119]
	v_mfma_f32_16x16x32_bf16 v[112:115], v[178:181], v[196:199], v[112:115]
	v_mfma_f32_16x16x32_bf16 v[100:103], v[160:163], v[204:207], v[100:103]
	v_mfma_f32_16x16x32_bf16 v[88:91], v[178:181], v[204:207], v[88:91]
	v_mfma_f32_16x16x32_bf16 v[68:71], v[160:163], v[212:215], v[68:71]
	v_mfma_f32_16x16x32_bf16 v[64:67], v[178:181], v[212:215], v[64:67]
	s_setprio 0
	s_barrier
; #define PG8_STAGE(bufoff, gbase, voff) do { _Pragma("unroll") for (int _i = 0; _i < 2; ++_i) \
;         __builtin_amdgcn_global_load_lds((const unsigned*)((const char*)(gbase) + (voff)[_i]), (PG8_LAS unsigned*)(lds + (bufoff) + ldsw + _i * 8192), 16, 0, 0); } while (0)
; #define PG8_LDA(dst, b, h) do { _Pragma("unroll") for (int m = 0; m < 4; ++m) _Pragma("unroll") for (int k = 0; k < 2; ++k) dst[m][k] = *(const PG8_LAS bf16x8*)(lds + PG8_SA(b, h) + aoff + m * 2048 + k * 1024); } while (0)
; #define PG8_MMA(ai, bj, At, Bt) do { __builtin_amdgcn_s_setprio(1); _Pragma("unroll") for (int m = 0; m < 4; ++m) _Pragma("unroll") for (int n = 0; n < 2; ++n) _Pragma("unroll") for (int k = 0; k < 2; ++k) \
;         acc[ai][bj][m][n] = __builtin_amdgcn_mfma_f32_16x16x32_bf16(Bt[n][k], At[m][k], acc[ai][bj][m][n], 0, 0, 0); __builtin_amdgcn_s_setprio(0); } while (0)
; #define PG8_WAIT_V(n) asm volatile("s_waitcnt vmcnt(" #n ")" ::: "memory")
; #define PG8_WAIT_L(n) asm volatile("s_waitcnt lgkmcnt(" #n ")" ::: "memory")
; #define PG8_BAR __builtin_amdgcn_s_barrier()
; #define PG8_SCHED __builtin_amdgcn_sched_barrier(0)
; template <class Epi, class Sched, bool ALIGN_EPI = false, bool SP2 = false>
; __device__ __forceinline__ void gemm_phase(PG8_LAS unsigned char* lds, const Gemm g, const Sched& S, const Epi& E) {
;     ...
;         for (int t = 0; t < nt; t += 2) {
;             const bool last = (t == nt - 2);
;             const char* a1 = cA + (size_t)(t + 1) * kstep;
;             const char* a2 = last ? nA : cA + (size_t)(t + 2) * kstep; const char* b2 = last ? nB : cB + (size_t)(t + 2) * kstep;
;     ...
;             PG8_LDA(At, 1, 1); PG8_STAGE(PG8_SB(1, 0), b3, voffB); PG8_STAGE(PG8_SB(1, 1), b3 + hstep, voffB); PG8_STAGE(PG8_SA(1, 0), a3, voffA);
;             PG8_WAIT_V(8); PG8_WAIT_L(0); PG8_BAR; PG8_MMA(1, 0, At, B0); PG8_MMA(1, 1, At, B1); PG8_BAR; PG8_SCHED;
	s_add_i32 s42, s59, s33
	v_lshl_add_u64 v[164:165], v[164:165], 0, s[12:13]
	s_mov_b32 m0, s42
	ds_read_b128 v[182:185], v171 offset:49152
	ds_read_b128 v[188:191], v171 offset:50176
	ds_read_b128 v[192:195], v171 offset:51200
	ds_read_b128 v[196:199], v171 offset:52224
	ds_read_b128 v[200:203], v171 offset:53248
	ds_read_b128 v[204:207], v171 offset:54272
	ds_read_b128 v[208:211], v171 offset:55296
	ds_read_b128 v[212:215], v171 offset:56320
	global_load_lds_dwordx4 v[164:165], off
	s_add_i32 m0, s42, 0x2000
	s_add_u32 s40, s40, 0x80080
	v_lshl_add_u64 v[164:165], v[216:217], 0, s[12:13]
	s_addc_u32 s41, s41, 0
	s_add_i32 s42, s60, s33
	global_load_lds_dwordx4 v[164:165], off
	v_lshl_add_u64 v[164:165], s[40:41], 0, v[144:145]
	s_mov_b32 m0, s42
	s_nop 0
	global_load_lds_dwordx4 v[164:165], off
	v_lshl_add_u64 v[164:165], s[40:41], 0, v[146:147]
	s_add_i32 m0, s42, 0x2000
	s_nop 0
	global_load_lds_dwordx4 v[164:165], off
	v_lshl_add_u64 v[164:165], v[218:219], 0, s[12:13]
	s_mov_b32 m0, s50
	s_nop 0
	global_load_lds_dwordx4 v[164:165], off
	v_lshl_add_u64 v[164:165], v[220:221], 0, s[12:13]
	s_mov_b32 m0, s51
	s_nop 0
	global_load_lds_dwordx4 v[164:165], off
	s_waitcnt vmcnt(8)
	s_waitcnt lgkmcnt(0)
	s_barrier
	s_setprio 1
	s_waitcnt lgkmcnt(0)
	v_mfma_f32_16x16x32_bf16 v[60:63], v[72:75], v[182:185], v[60:63]
	v_mfma_f32_16x16x32_bf16 v[56:59], v[92:95], v[182:185], v[56:59]
	v_mfma_f32_16x16x32_bf16 v[44:47], v[72:75], v[192:195], v[44:47]
	v_mfma_f32_16x16x32_bf16 v[40:43], v[92:95], v[192:195], v[40:43]
	v_mfma_f32_16x16x32_bf16 v[28:31], v[72:75], v[200:203], v[28:31]
	v_mfma_f32_16x16x32_bf16 v[24:27], v[92:95], v[200:203], v[24:27]
	v_mfma_f32_16x16x32_bf16 v[12:15], v[72:75], v[208:211], v[12:15]
	v_mfma_f32_16x16x32_bf16 v[8:11], v[92:95], v[208:211], v[8:11]
	v_mfma_f32_16x16x32_bf16 v[60:63], v[84:87], v[188:191], v[60:63]
	v_mfma_f32_16x16x32_bf16 v[56:59], v[96:99], v[188:191], v[56:59]
	v_mfma_f32_16x16x32_bf16 v[44:47], v[84:87], v[196:199], v[44:47]
	v_mfma_f32_16x16x32_bf16 v[40:43], v[96:99], v[196:199], v[40:43]
	v_mfma_f32_16x16x32_bf16 v[28:31], v[84:87], v[204:207], v[28:31]
	v_mfma_f32_16x16x32_bf16 v[24:27], v[96:99], v[204:207], v[24:27]
	v_mfma_f32_16x16x32_bf16 v[12:15], v[84:87], v[212:215], v[12:15]
	v_mfma_f32_16x16x32_bf16 v[8:11], v[96:99], v[212:215], v[8:11]
	s_setprio 0
	s_setprio 1
	v_mfma_f32_16x16x32_bf16 v[52:55], v[156:159], v[182:185], v[52:55]
	v_mfma_f32_16x16x32_bf16 v[48:51], v[174:177], v[182:185], v[48:51]
	v_mfma_f32_16x16x32_bf16 v[36:39], v[156:159], v[192:195], v[36:39]
	v_mfma_f32_16x16x32_bf16 v[32:35], v[174:177], v[192:195], v[32:35]
	v_mfma_f32_16x16x32_bf16 v[20:23], v[156:159], v[200:203], v[20:23]
	v_mfma_f32_16x16x32_bf16 v[16:19], v[174:177], v[200:203], v[16:19]
	v_mfma_f32_16x16x32_bf16 v[4:7], v[156:159], v[208:211], v[4:7]
	v_mfma_f32_16x16x32_bf16 v[0:3], v[174:177], v[208:211], v[0:3]
	v_mfma_f32_16x16x32_bf16 v[52:55], v[160:163], v[188:191], v[52:55]
	v_mfma_f32_16x16x32_bf16 v[48:51], v[178:181], v[188:191], v[48:51]
	v_mfma_f32_16x16x32_bf16 v[36:39], v[160:163], v[196:199], v[36:39]
	v_mfma_f32_16x16x32_bf16 v[32:35], v[178:181], v[196:199], v[32:35]
	v_mfma_f32_16x16x32_bf16 v[20:23], v[160:163], v[204:207], v[20:23]
	v_mfma_f32_16x16x32_bf16 v[16:19], v[178:181], v[204:207], v[16:19]
	v_mfma_f32_16x16x32_bf16 v[4:7], v[160:163], v[212:215], v[4:7]
	v_mfma_f32_16x16x32_bf16 v[0:3], v[178:181], v[212:215], v[0:3]
	s_setprio 0
	s_add_i32 s58, s58, 2
	s_add_u32 s38, s38, 0x100
	s_addc_u32 s39, s39, 0
	s_add_u32 s56, s56, 0x100
	s_addc_u32 s57, s57, 0
	s_cmp_gt_u32 s58, 29

; #define PG8_STAGE(bufoff, gbase, voff) do { _Pragma("unroll") for (int _i = 0; _i < 2; ++_i) \
;         __builtin_amdgcn_global_load_lds((const unsigned*)((const char*)(gbase) + (voff)[_i]), (PG8_LAS unsigned*)(lds + (bufoff) + ldsw + _i * 8192), 16, 0, 0); } while (0)
; #define PG8_LDA(dst, b, h) do { _Pragma("unroll") for (int m = 0; m < 4; ++m) _Pragma("unroll") for (int k = 0; k < 2; ++k) dst[m][k] = *(const PG8_LAS bf16x8*)(lds + PG8_SA(b, h) + aoff + m * 2048 + k * 1024); } while (0)
; #define PG8_LDB(dst, b, h) do { _Pragma("unroll") for (int n = 0; n < 2; ++n) _Pragma("unroll") for (int k = 0; k < 2; ++k) dst[n][k] = *(const PG8_LAS bf16x8*)(lds + PG8_SB(b, h) + boff + n * 2048 + k * 1024); } while (0)
; #define PG8_MMA(ai, bj, At, Bt) do { __builtin_amdgcn_s_setprio(1); _Pragma("unroll") for (int m = 0; m < 4; ++m) _Pragma("unroll") for (int n = 0; n < 2; ++n) _Pragma("unroll") for (int k = 0; k < 2; ++k) \
;         acc[ai][bj][m][n] = __builtin_amdgcn_mfma_f32_16x16x32_bf16(Bt[n][k], At[m][k], acc[ai][bj][m][n], 0, 0, 0); __builtin_amdgcn_s_setprio(0); } while (0)
; #define PG8_WAIT_V(n) asm volatile("s_waitcnt vmcnt(" #n ")" ::: "memory")
; #define PG8_WAIT_L(n) asm volatile("s_waitcnt lgkmcnt(" #n ")" ::: "memory")
; #define PG8_BAR __builtin_amdgcn_s_barrier()
; #define PG8_SCHED __builtin_amdgcn_sched_barrier(0)
; template <class Epi, class Sched, bool ALIGN_EPI = false, bool SP2 = false>
; __device__ __forceinline__ void gemm_phase(PG8_LAS unsigned char* lds, const Gemm g, const Sched& S, const Epi& E) {
;     ...
;         for (int t = 0; t < nt; t += 2) {
;             const bool last = (t == nt - 2);
;             const char* a1 = cA + (size_t)(t + 1) * kstep;
;             const char* a2 = last ? nA : cA + (size_t)(t + 2) * kstep; const char* b2 = last ? nB : cB + (size_t)(t + 2) * kstep;
;             const char* a3 = a2 + kstep; const char* b3 = b2 + kstep;
;             if (last && has_next) S.a_ready(nxt);
;             if constexpr (SP2) {
;             PG8_LDB(B0, 0, 0); PG8_LDB(B1, 0, 1); PG8_SCHED; PG8_LDA(At, 0, 0); PG8_STAGE(PG8_SA(1, 1), a1 + hstep, voffA);
;             PG8_WAIT_V(8); PG8_WAIT_L(0); PG8_BAR; PG8_MMA(0, 0, At, B0); PG8_MMA(0, 1, At, B1); PG8_BAR; PG8_SCHED;
;             PG8_LDA(At, 0, 1); PG8_STAGE(PG8_SB(0, 0), b2, voffB); PG8_STAGE(PG8_SB(0, 1), b2 + hstep, voffB); PG8_STAGE(PG8_SA(0, 0), a2, voffA);
.LBB0_894:
	ds_read_b128 v[72:75], v169
	ds_read_b128 v[84:87], v169 offset:1024
	ds_read_b128 v[92:95], v169 offset:2048
	ds_read_b128 v[96:99], v169 offset:3072
	ds_read_b128 v[156:159], v170
	ds_read_b128 v[160:163], v170 offset:1024
	ds_read_b128 v[174:177], v170 offset:2048
	ds_read_b128 v[178:181], v170 offset:3072
	s_add_u32 s40, s38, 0xfff80080
	s_addc_u32 s41, s39, -1
	s_cmp_eq_u32 s58, 28
	s_cselect_b32 s43, s25, s41
	s_cselect_b32 s42, s35, s40
	s_cselect_b32 s41, s27, s57
	s_cselect_b32 s40, s55, s56
	v_lshl_add_u64 v[164:165], s[38:39], 0, v[148:149]
	s_add_i32 m0, s37, 0xc000
	ds_read_b128 v[182:185], v171
	ds_read_b128 v[188:191], v171 offset:1024
	ds_read_b128 v[192:195], v171 offset:2048
	ds_read_b128 v[196:199], v171 offset:3072
	ds_read_b128 v[200:203], v171 offset:4096
	ds_read_b128 v[204:207], v171 offset:5120
	ds_read_b128 v[208:211], v171 offset:6144
	ds_read_b128 v[212:215], v171 offset:7168
	global_load_lds_dwordx4 v[164:165], off
	v_lshl_add_u64 v[164:165], s[38:39], 0, v[150:151]
	s_add_i32 m0, s37, 0xe000
	s_nop 0
	global_load_lds_dwordx4 v[164:165], off
	s_waitcnt vmcnt(8)
	s_waitcnt lgkmcnt(0)
	s_barrier
	s_setprio 1
	s_waitcnt lgkmcnt(0)
	v_mfma_f32_16x16x32_bf16 v[140:143], v[72:75], v[182:185], v[140:143]
	v_mfma_f32_16x16x32_bf16 v[136:139], v[92:95], v[182:185], v[136:139]
	v_mfma_f32_16x16x32_bf16 v[124:127], v[72:75], v[192:195], v[124:127]
	v_mfma_f32_16x16x32_bf16 v[120:123], v[92:95], v[192:195], v[120:123]
	v_mfma_f32_16x16x32_bf16 v[108:111], v[72:75], v[200:203], v[108:111]
	v_mfma_f32_16x16x32_bf16 v[104:107], v[92:95], v[200:203], v[104:107]
	v_mfma_f32_16x16x32_bf16 v[80:83], v[72:75], v[208:211], v[80:83]
	v_mfma_f32_16x16x32_bf16 v[76:79], v[92:95], v[208:211], v[76:79]
	v_mfma_f32_16x16x32_bf16 v[140:143], v[84:87], v[188:191], v[140:143]
	v_mfma_f32_16x16x32_bf16 v[136:139], v[96:99], v[188:191], v[136:139]
	v_mfma_f32_16x16x32_bf16 v[124:127], v[84:87], v[196:199], v[124:127]
	v_mfma_f32_16x16x32_bf16 v[120:123], v[96:99], v[196:199], v[120:123]
	v_mfma_f32_16x16x32_bf16 v[108:111], v[84:87], v[204:207], v[108:111]
	v_mfma_f32_16x16x32_bf16 v[104:107], v[96:99], v[204:207], v[104:107]
	v_mfma_f32_16x16x32_bf16 v[80:83], v[84:87], v[212:215], v[80:83]
	v_mfma_f32_16x16x32_bf16 v[76:79], v[96:99], v[212:215], v[76:79]
	s_setprio 0
	s_setprio 1
	v_mfma_f32_16x16x32_bf16 v[132:135], v[156:159], v[182:185], v[132:135]
	v_mfma_f32_16x16x32_bf16 v[128:131], v[174:177], v[182:185], v[128:131]
	v_mfma_f32_16x16x32_bf16 v[116:119], v[156:159], v[192:195], v[116:119]
	v_mfma_f32_16x16x32_bf16 v[112:115], v[174:177], v[192:195], v[112:115]
	v_mfma_f32_16x16x32_bf16 v[100:103], v[156:159], v[200:203], v[100:103]
	v_mfma_f32_16x16x32_bf16 v[88:91], v[174:177], v[200:203], v[88:91]
	v_mfma_f32_16x16x32_bf16 v[68:71], v[156:159], v[208:211], v[68:71]
	v_mfma_f32_16x16x32_bf16 v[64:67], v[174:177], v[208:211], v[64:67]
	v_mfma_f32_16x16x32_bf16 v[132:135], v[160:163], v[188:191], v[132:135]
	v_mfma_f32_16x16x32_bf16 v[128:131], v[178:181], v[188:191], v[128:131]
	v_mfma_f32_16x16x32_bf16 v[116:119], v[160:163], v[196:199], v[116:119]
	v_mfma_f32_16x16x32_bf16 v[112:115], v[178:181], v[196:199], v[112:115]
	v_mfma_f32_16x16x32_bf16 v[100:103], v[160:163], v[204:207], v[100:103]
	v_mfma_f32_16x16x32_bf16 v[88:91], v[178:181], v[204:207], v[88:91]
	v_mfma_f32_16x16x32_bf16 v[68:71], v[160:163], v[212:215], v[68:71]
	v_mfma_f32_16x16x32_bf16 v[64:67], v[178:181], v[212:215], v[64:67]
	s_setprio 0
	s_barrier
	s_add_i32 s59, s53, s33
	v_lshl_add_u64 v[164:165], s[40:41], 0, v[144:145]
	s_mov_b32 m0, s59
	ds_read_b128 v[182:185], v171 offset:16384
	ds_read_b128 v[188:191], v171 offset:17408
	ds_read_b128 v[192:195], v171 offset:18432
	ds_read_b128 v[196:199], v171 offset:19456
	ds_read_b128 v[200:203], v171 offset:20480
	ds_read_b128 v[204:207], v171 offset:21504
	ds_read_b128 v[208:211], v171 offset:22528
	ds_read_b128 v[212:215], v171 offset:23552
	global_load_lds_dwordx4 v[164:165], off
	s_add_i32 m0, s59, 0x2000
	s_add_u32 s60, s40, 0x80000
	v_lshl_add_u64 v[216:217], s[40:41], 0, v[146:147]
	s_addc_u32 s61, s41, 0
	s_add_i32 s59, s54, s33
	global_load_lds_dwordx4 v[216:217], off
	v_lshl_add_u64 v[218:219], s[60:61], 0, v[144:145]
	s_mov_b32 m0, s59
	v_lshl_add_u64 v[220:221], s[42:43], 0, v[146:147]
	global_load_lds_dwordx4 v[218:219], off
	v_lshl_add_u64 v[218:219], s[60:61], 0, v[146:147]
	s_add_i32 m0, s59, 0x2000
	s_nop 0
	global_load_lds_dwordx4 v[218:219], off
	v_lshl_add_u64 v[218:219], s[42:43], 0, v[144:145]
	s_mov_b32 m0, s37
	s_nop 0
	global_load_lds_dwordx4 v[218:219], off
	s_mov_b32 m0, s44
	s_nop 0
	global_load_lds_dwordx4 v[220:221], off
	s_waitcnt vmcnt(8)
	s_waitcnt lgkmcnt(0)
	s_barrier
; #define PG8_STAGE(bufoff, gbase, voff) do { _Pragma("unroll") for (int _i = 0; _i < 2; ++_i) \
;         __builtin_amdgcn_global_load_lds((const unsigned*)((const char*)(gbase) + (voff)[_i]), (PG8_LAS unsigned*)(lds + (bufoff) + ldsw + _i * 8192), 16, 0, 0); } while (0)
; #define PG8_LDA(dst, b, h) do { _Pragma("unroll") for (int m = 0; m < 4; ++m) _Pragma("unroll") for (int k = 0; k < 2; ++k) dst[m][k] = *(const PG8_LAS bf16x8*)(lds + PG8_SA(b, h) + aoff + m * 2048 + k * 1024); } while (0)
; #define PG8_LDB(dst, b, h) do { _Pragma("unroll") for (int n = 0; n < 2; ++n) _Pragma("unroll") for (int k = 0; k < 2; ++k) dst[n][k] = *(const PG8_LAS bf16x8*)(lds + PG8_SB(b, h) + boff + n * 2048 + k * 1024); } while (0)
; #define PG8_MMA(ai, bj, At, Bt) do { __builtin_amdgcn_s_setprio(1); _Pragma("unroll") for (int m = 0; m < 4; ++m) _Pragma("unroll") for (int n = 0; n < 2; ++n) _Pragma("unroll") for (int k = 0; k < 2; ++k) \
;         acc[ai][bj][m][n] = __builtin_amdgcn_mfma_f32_16x16x32_bf16(Bt[n][k], At[m][k], acc[ai][bj][m][n], 0, 0, 0); __builtin_amdgcn_s_setprio(0); } while (0)
; #define PG8_WAIT_V(n) asm volatile("s_waitcnt vmcnt(" #n ")" ::: "memory")
; #define PG8_WAIT_L(n) asm volatile("s_waitcnt lgkmcnt(" #n ")" ::: "memory")
; #define PG8_BAR __builtin_amdgcn_s_barrier()
; #define PG8_SCHED __builtin_amdgcn_sched_barrier(0)
; template <class Epi, class Sched, bool ALIGN_EPI = false, bool SP2 = false>
; __device__ __forceinline__ void gemm_phase(PG8_LAS unsigned char* lds, const Gemm g, const Sched& S, const Epi& E) {
;     ...
;             PG8_WAIT_V(8); PG8_WAIT_L(0); PG8_BAR; PG8_MMA(1, 0, At, B0); PG8_MMA(1, 1, At, B1); PG8_BAR; PG8_SCHED;
;             PG8_LDB(B0, 1, 0); PG8_LDB(B1, 1, 1); PG8_SCHED; PG8_LDA(At, 1, 0); PG8_STAGE(PG8_SA(0, 1), a2 + hstep, voffA);
;             PG8_WAIT_V(8); PG8_WAIT_L(0); PG8_BAR; PG8_MMA(0, 0, At, B0); PG8_MMA(0, 1, At, B1); PG8_BAR; PG8_SCHED;
	s_setprio 1
	s_waitcnt lgkmcnt(0)
	v_mfma_f32_16x16x32_bf16 v[60:63], v[72:75], v[182:185], v[60:63]
	v_mfma_f32_16x16x32_bf16 v[56:59], v[92:95], v[182:185], v[56:59]
	v_mfma_f32_16x16x32_bf16 v[44:47], v[72:75], v[192:195], v[44:47]
	v_mfma_f32_16x16x32_bf16 v[40:43], v[92:95], v[192:195], v[40:43]
	v_mfma_f32_16x16x32_bf16 v[28:31], v[72:75], v[200:203], v[28:31]
	v_mfma_f32_16x16x32_bf16 v[24:27], v[92:95], v[200:203], v[24:27]
	v_mfma_f32_16x16x32_bf16 v[12:15], v[72:75], v[208:211], v[12:15]
	v_mfma_f32_16x16x32_bf16 v[8:11], v[92:95], v[208:211], v[8:11]
	v_mfma_f32_16x16x32_bf16 v[60:63], v[84:87], v[188:191], v[60:63]
	v_mfma_f32_16x16x32_bf16 v[56:59], v[96:99], v[188:191], v[56:59]
	v_mfma_f32_16x16x32_bf16 v[44:47], v[84:87], v[196:199], v[44:47]
	v_mfma_f32_16x16x32_bf16 v[40:43], v[96:99], v[196:199], v[40:43]
	v_mfma_f32_16x16x32_bf16 v[28:31], v[84:87], v[204:207], v[28:31]
	v_mfma_f32_16x16x32_bf16 v[24:27], v[96:99], v[204:207], v[24:27]
	v_mfma_f32_16x16x32_bf16 v[12:15], v[84:87], v[212:215], v[12:15]
	v_mfma_f32_16x16x32_bf16 v[8:11], v[96:99], v[212:215], v[8:11]
	s_setprio 0
	s_setprio 1
	v_mfma_f32_16x16x32_bf16 v[52:55], v[156:159], v[182:185], v[52:55]
	v_mfma_f32_16x16x32_bf16 v[48:51], v[174:177], v[182:185], v[48:51]
	v_mfma_f32_16x16x32_bf16 v[36:39], v[156:159], v[192:195], v[36:39]
	v_mfma_f32_16x16x32_bf16 v[32:35], v[174:177], v[192:195], v[32:35]
	v_mfma_f32_16x16x32_bf16 v[20:23], v[156:159], v[200:203], v[20:23]
	v_mfma_f32_16x16x32_bf16 v[16:19], v[174:177], v[200:203], v[16:19]
	v_mfma_f32_16x16x32_bf16 v[4:7], v[156:159], v[208:211], v[4:7]
	v_mfma_f32_16x16x32_bf16 v[0:3], v[174:177], v[208:211], v[0:3]
	v_mfma_f32_16x16x32_bf16 v[52:55], v[160:163], v[188:191], v[52:55]
	v_mfma_f32_16x16x32_bf16 v[48:51], v[178:181], v[188:191], v[48:51]
	v_mfma_f32_16x16x32_bf16 v[36:39], v[160:163], v[196:199], v[36:39]
	v_mfma_f32_16x16x32_bf16 v[32:35], v[178:181], v[196:199], v[32:35]
	v_mfma_f32_16x16x32_bf16 v[20:23], v[160:163], v[204:207], v[20:23]
	v_mfma_f32_16x16x32_bf16 v[16:19], v[178:181], v[204:207], v[16:19]
	v_mfma_f32_16x16x32_bf16 v[4:7], v[160:163], v[212:215], v[4:7]
	v_mfma_f32_16x16x32_bf16 v[0:3], v[178:181], v[212:215], v[0:3]
	s_setprio 0
	s_barrier
	s_add_i32 s59, 0, 0x18000
	s_add_i32 s60, 0, 0x1c000
	v_add_u32_e32 v96, s59, v167
	v_add_u32_e32 v173, s60, v167
	ds_read_b128 v[72:75], v96
	ds_read_b128 v[84:87], v96 offset:1024
	ds_read_b128 v[92:95], v96 offset:2048
	ds_read_b128 v[96:99], v96 offset:3072
	ds_read_b128 v[156:159], v173
	ds_read_b128 v[160:163], v173 offset:1024
	ds_read_b128 v[174:177], v173 offset:2048
	ds_read_b128 v[178:181], v173 offset:3072
	s_add_u32 s42, s42, 0x80000
	s_addc_u32 s43, s43, 0
	s_mov_b32 m0, s45
	v_lshl_add_u64 v[222:223], s[42:43], 0, v[144:145]
	ds_read_b128 v[182:185], v171 offset:32768
	ds_read_b128 v[188:191], v171 offset:33792
	ds_read_b128 v[192:195], v171 offset:34816
	ds_read_b128 v[196:199], v171 offset:35840
	ds_read_b128 v[200:203], v171 offset:36864
	ds_read_b128 v[204:207], v171 offset:37888
	ds_read_b128 v[208:211], v171 offset:38912
	ds_read_b128 v[212:215], v171 offset:39936
	global_load_lds_dwordx4 v[222:223], off
	v_lshl_add_u64 v[222:223], s[42:43], 0, v[146:147]
	s_mov_b32 m0, s46
	s_nop 0
	global_load_lds_dwordx4 v[222:223], off
	s_waitcnt vmcnt(8)
	s_waitcnt lgkmcnt(0)
	s_barrier
	s_setprio 1
	s_waitcnt lgkmcnt(0)
	v_mfma_f32_16x16x32_bf16 v[140:143], v[72:75], v[182:185], v[140:143]
	v_mfma_f32_16x16x32_bf16 v[136:139], v[92:95], v[182:185], v[136:139]
	v_mfma_f32_16x16x32_bf16 v[124:127], v[72:75], v[192:195], v[124:127]
	v_mfma_f32_16x16x32_bf16 v[120:123], v[92:95], v[192:195], v[120:123]
	v_mfma_f32_16x16x32_bf16 v[108:111], v[72:75], v[200:203], v[108:111]
	v_mfma_f32_16x16x32_bf16 v[104:107], v[92:95], v[200:203], v[104:107]
	v_mfma_f32_16x16x32_bf16 v[80:83], v[72:75], v[208:211], v[80:83]
	v_mfma_f32_16x16x32_bf16 v[76:79], v[92:95], v[208:211], v[76:79]
	v_mfma_f32_16x16x32_bf16 v[140:143], v[84:87], v[188:191], v[140:143]
	v_mfma_f32_16x16x32_bf16 v[136:139], v[96:99], v[188:191], v[136:139]
	v_mfma_f32_16x16x32_bf16 v[124:127], v[84:87], v[196:199], v[124:127]
	v_mfma_f32_16x16x32_bf16 v[120:123], v[96:99], v[196:199], v[120:123]
	v_mfma_f32_16x16x32_bf16 v[108:111], v[84:87], v[204:207], v[108:111]
	v_mfma_f32_16x16x32_bf16 v[104:107], v[96:99], v[204:207], v[104:107]
	v_mfma_f32_16x16x32_bf16 v[80:83], v[84:87], v[212:215], v[80:83]
	v_mfma_f32_16x16x32_bf16 v[76:79], v[96:99], v[212:215], v[76:79]
	s_setprio 0
	s_setprio 1
	v_mfma_f32_16x16x32_bf16 v[132:135], v[156:159], v[182:185], v[132:135]
	v_mfma_f32_16x16x32_bf16 v[128:131], v[174:177], v[182:185], v[128:131]
	v_mfma_f32_16x16x32_bf16 v[116:119], v[156:159], v[192:195], v[116:119]
	v_mfma_f32_16x16x32_bf16 v[112:115], v[174:177], v[192:195], v[112:115]
	v_mfma_f32_16x16x32_bf16 v[100:103], v[156:159], v[200:203], v[100:103]
	v_mfma_f32_16x16x32_bf16 v[88:91], v[174:177], v[200:203], v[88:91]
	v_mfma_f32_16x16x32_bf16 v[68:71], v[156:159], v[208:211], v[68:71]
	v_mfma_f32_16x16x32_bf16 v[64:67], v[174:177], v[208:211], v[64:67]
	v_mfma_f32_16x16x32_bf16 v[132:135], v[160:163], v[188:191], v[132:135]
	v_mfma_f32_16x16x32_bf16 v[128:131], v[178:181], v[188:191], v[128:131]
	v_mfma_f32_16x16x32_bf16 v[116:119], v[160:163], v[196:199], v[116:119]
	v_mfma_f32_16x16x32_bf16 v[112:115], v[178:181], v[196:199], v[112:115]
	v_mfma_f32_16x16x32_bf16 v[100:103], v[160:163], v[204:207], v[100:103]
	v_mfma_f32_16x16x32_bf16 v[88:91], v[178:181], v[204:207], v[88:91]
	v_mfma_f32_16x16x32_bf16 v[68:71], v[160:163], v[212:215], v[68:71]
	v_mfma_f32_16x16x32_bf16 v[64:67], v[178:181], v[212:215], v[64:67]
	s_setprio 0
	s_barrier
; #define PG8_STAGE(bufoff, gbase, voff) do { _Pragma("unroll") for (int _i = 0; _i < 2; ++_i) \
;         __builtin_amdgcn_global_load_lds((const unsigned*)((const char*)(gbase) + (voff)[_i]), (PG8_LAS unsigned*)(lds + (bufoff) + ldsw + _i * 8192), 16, 0, 0); } while (0)
; #define PG8_LDA(dst, b, h) do { _Pragma("unroll") for (int m = 0; m < 4; ++m) _Pragma("unroll") for (int k = 0; k < 2; ++k) dst[m][k] = *(const PG8_LAS bf16x8*)(lds + PG8_SA(b, h) + aoff + m * 2048 + k * 1024); } while (0)
; #define PG8_MMA(ai, bj, At, Bt) do { __builtin_amdgcn_s_setprio(1); _Pragma("unroll") for (int m = 0; m < 4; ++m) _Pragma("unroll") for (int n = 0; n < 2; ++n) _Pragma("unroll") for (int k = 0; k < 2; ++k) \
;         acc[ai][bj][m][n] = __builtin_amdgcn_mfma_f32_16x16x32_bf16(Bt[n][k], At[m][k], acc[ai][bj][m][n], 0, 0, 0); __builtin_amdgcn_s_setprio(0); } while (0)
; #define PG8_WAIT_V(n) asm volatile("s_waitcnt vmcnt(" #n ")" ::: "memory")
; #define PG8_WAIT_L(n) asm volatile("s_waitcnt lgkmcnt(" #n ")" ::: "memory")
; #define PG8_BAR __builtin_amdgcn_s_barrier()
; #define PG8_SCHED __builtin_amdgcn_sched_barrier(0)
; template <class Epi, class Sched, bool ALIGN_EPI = false, bool SP2 = false>
; __device__ __forceinline__ void gemm_phase(PG8_LAS unsigned char* lds, const Gemm g, const Sched& S, const Epi& E) {
;     ...
;         for (int t = 0; t < nt; t += 2) {
;     ...
;             PG8_LDA(At, 1, 1); PG8_STAGE(PG8_SB(1, 0), b3, voffB); PG8_STAGE(PG8_SB(1, 1), b3 + hstep, voffB); PG8_STAGE(PG8_SA(1, 0), a3, voffA);
;             PG8_WAIT_V(8); PG8_WAIT_L(0); PG8_BAR; PG8_MMA(1, 0, At, B0); PG8_MMA(1, 1, At, B1); PG8_BAR; PG8_SCHED;
;     ...
;         if constexpr (ALIGN_EPI) { if (wr == 0) PG8_BAR; }
	s_add_i32 s42, s59, s33
	v_lshl_add_u64 v[164:165], v[164:165], 0, s[12:13]
	s_mov_b32 m0, s42
	ds_read_b128 v[182:185], v171 offset:49152
	ds_read_b128 v[188:191], v171 offset:50176
	ds_read_b128 v[192:195], v171 offset:51200
	ds_read_b128 v[196:199], v171 offset:52224
	ds_read_b128 v[200:203], v171 offset:53248
	ds_read_b128 v[204:207], v171 offset:54272
	ds_read_b128 v[208:211], v171 offset:55296
	ds_read_b128 v[212:215], v171 offset:56320
	global_load_lds_dwordx4 v[164:165], off
	s_add_i32 m0, s42, 0x2000
	s_add_u32 s40, s40, 0x80080
	v_lshl_add_u64 v[164:165], v[216:217], 0, s[12:13]
	s_addc_u32 s41, s41, 0
	s_add_i32 s42, s60, s33
	global_load_lds_dwordx4 v[164:165], off
	v_lshl_add_u64 v[164:165], s[40:41], 0, v[144:145]
	s_mov_b32 m0, s42
	s_nop 0
	global_load_lds_dwordx4 v[164:165], off
	v_lshl_add_u64 v[164:165], s[40:41], 0, v[146:147]
	s_add_i32 m0, s42, 0x2000
	s_nop 0
	global_load_lds_dwordx4 v[164:165], off
	v_lshl_add_u64 v[164:165], v[218:219], 0, s[12:13]
	s_mov_b32 m0, s50
	s_nop 0
	global_load_lds_dwordx4 v[164:165], off
	v_lshl_add_u64 v[164:165], v[220:221], 0, s[12:13]
	s_mov_b32 m0, s51
	s_nop 0
	global_load_lds_dwordx4 v[164:165], off
	s_waitcnt vmcnt(8)
	s_waitcnt lgkmcnt(0)
	s_barrier
	s_setprio 1
	s_waitcnt lgkmcnt(0)
	v_mfma_f32_16x16x32_bf16 v[60:63], v[72:75], v[182:185], v[60:63]
	v_mfma_f32_16x16x32_bf16 v[56:59], v[92:95], v[182:185], v[56:59]
	v_mfma_f32_16x16x32_bf16 v[44:47], v[72:75], v[192:195], v[44:47]
	v_mfma_f32_16x16x32_bf16 v[40:43], v[92:95], v[192:195], v[40:43]
	v_mfma_f32_16x16x32_bf16 v[28:31], v[72:75], v[200:203], v[28:31]
	v_mfma_f32_16x16x32_bf16 v[24:27], v[92:95], v[200:203], v[24:27]
	v_mfma_f32_16x16x32_bf16 v[12:15], v[72:75], v[208:211], v[12:15]
	v_mfma_f32_16x16x32_bf16 v[8:11], v[92:95], v[208:211], v[8:11]
	v_mfma_f32_16x16x32_bf16 v[60:63], v[84:87], v[188:191], v[60:63]
	v_mfma_f32_16x16x32_bf16 v[56:59], v[96:99], v[188:191], v[56:59]
	v_mfma_f32_16x16x32_bf16 v[44:47], v[84:87], v[196:199], v[44:47]
	v_mfma_f32_16x16x32_bf16 v[40:43], v[96:99], v[196:199], v[40:43]
	v_mfma_f32_16x16x32_bf16 v[28:31], v[84:87], v[204:207], v[28:31]
	v_mfma_f32_16x16x32_bf16 v[24:27], v[96:99], v[204:207], v[24:27]
	v_mfma_f32_16x16x32_bf16 v[12:15], v[84:87], v[212:215], v[12:15]
	v_mfma_f32_16x16x32_bf16 v[8:11], v[96:99], v[212:215], v[8:11]
	s_setprio 0
	s_setprio 1
	v_mfma_f32_16x16x32_bf16 v[52:55], v[156:159], v[182:185], v[52:55]
	v_mfma_f32_16x16x32_bf16 v[48:51], v[174:177], v[182:185], v[48:51]
	v_mfma_f32_16x16x32_bf16 v[36:39], v[156:159], v[192:195], v[36:39]
	v_mfma_f32_16x16x32_bf16 v[32:35], v[174:177], v[192:195], v[32:35]
	v_mfma_f32_16x16x32_bf16 v[20:23], v[156:159], v[200:203], v[20:23]
	v_mfma_f32_16x16x32_bf16 v[16:19], v[174:177], v[200:203], v[16:19]
	v_mfma_f32_16x16x32_bf16 v[4:7], v[156:159], v[208:211], v[4:7]
	v_mfma_f32_16x16x32_bf16 v[0:3], v[174:177], v[208:211], v[0:3]
	v_mfma_f32_16x16x32_bf16 v[52:55], v[160:163], v[188:191], v[52:55]
	v_mfma_f32_16x16x32_bf16 v[48:51], v[178:181], v[188:191], v[48:51]
	v_mfma_f32_16x16x32_bf16 v[36:39], v[160:163], v[196:199], v[36:39]
	v_mfma_f32_16x16x32_bf16 v[32:35], v[178:181], v[196:199], v[32:35]
	v_mfma_f32_16x16x32_bf16 v[20:23], v[160:163], v[204:207], v[20:23]
	v_mfma_f32_16x16x32_bf16 v[16:19], v[178:181], v[204:207], v[16:19]
	v_mfma_f32_16x16x32_bf16 v[4:7], v[160:163], v[212:215], v[4:7]
	v_mfma_f32_16x16x32_bf16 v[0:3], v[178:181], v[212:215], v[0:3]
	s_setprio 0
	s_add_i32 s58, s58, 2
	s_add_u32 s38, s38, 0x100
	s_addc_u32 s39, s39, 0
	s_add_u32 s56, s56, 0x100
	s_addc_u32 s57, s57, 0
	s_cmp_gt_u32 s58, 29
	s_cbranch_scc0 .Lrot_894
	s_barrier
	s_and_b64 vcc, exec, s[14:15]
	s_cbranch_vccz .LBB0_897
	s_barrier

;     __device__ __forceinline__ bool next(int i, Unit& u) const { if (!base.next(i >> 1, u)) return false; if (i & 1) { u.pm += 64; u.pn += 8; } return true; }
; #define PG8_STAGE(bufoff, gbase, voff) do { _Pragma("unroll") for (int _i = 0; _i < 2; ++_i) \
;         __builtin_amdgcn_global_load_lds((const unsigned*)((const char*)(gbase) + (voff)[_i]), (PG8_LAS unsigned*)(lds + (bufoff) + ldsw + _i * 8192), 16, 0, 0); } while (0)
; #define PG8_LDA(dst, b, h) do { _Pragma("unroll") for (int m = 0; m < 4; ++m) _Pragma("unroll") for (int k = 0; k < 2; ++k) dst[m][k] = *(const PG8_LAS bf16x8*)(lds + PG8_SA(b, h) + aoff + m * 2048 + k * 1024); } while (0)
; #define PG8_LDB(dst, b, h) do { _Pragma("unroll") for (int n = 0; n < 2; ++n) _Pragma("unroll") for (int k = 0; k < 2; ++k) dst[n][k] = *(const PG8_LAS bf16x8*)(lds + PG8_SB(b, h) + boff + n * 2048 + k * 1024); } while (0)
; #define PG8_WAIT_V(n) asm volatile("s_waitcnt vmcnt(" #n ")" ::: "memory")
; #define PG8_WAIT_L(n) asm volatile("s_waitcnt lgkmcnt(" #n ")" ::: "memory")
; #define PG8_BAR __builtin_amdgcn_s_barrier()
; #define PG8_SCHED __builtin_amdgcn_sched_barrier(0)
; template <class Epi, class Sched, bool ALIGN_EPI = false, bool SP2 = false>
; __device__ __forceinline__ void gemm_phase(PG8_LAS unsigned char* lds, const Gemm g, const Sched& S, const Epi& E) {
;     ...
;         const bool has_next = S.next(ui + 1, nxt);
;         const char* nA = has_next ? (const char*)g.A + (size_t)nxt.pm * tstep : cA; const char* nB = has_next ? (const char*)g.Bt + (size_t)nxt.pn * tstep : cB;
;         for (int t = 0; t < nt; t += 2) {
;             const bool last = (t == nt - 2);
;             const char* a1 = cA + (size_t)(t + 1) * kstep;
;             const char* a2 = last ? nA : cA + (size_t)(t + 2) * kstep; const char* b2 = last ? nB : cB + (size_t)(t + 2) * kstep;
;             const char* a3 = a2 + kstep; const char* b3 = b2 + kstep;
;             if (last && has_next) S.a_ready(nxt);
;             if constexpr (SP2) {
;             PG8_LDB(B0, 0, 0); PG8_LDB(B1, 0, 1); PG8_SCHED; PG8_LDA(At, 0, 0); PG8_STAGE(PG8_SA(1, 1), a1 + hstep, voffA);
;             PG8_WAIT_V(8); PG8_WAIT_L(0); PG8_BAR; PG8_MMA(0, 0, At, B0); PG8_MMA(0, 1, At, B1); PG8_BAR; PG8_SCHED;
;             PG8_LDA(At, 0, 1); PG8_STAGE(PG8_SB(0, 0), b2, voffB); PG8_STAGE(PG8_SB(0, 1), b2 + hstep, voffB); PG8_STAGE(PG8_SA(0, 0), a2, voffA);
.LBB0_993:
	s_ashr_i32 s15, s14, 31
	s_lshl_b64 s[18:19], s[14:15], 20
	s_add_u32 s18, s8, s18
	s_addc_u32 s19, s9, s19
	s_and_b64 s[20:21], s[4:5], exec
	s_cselect_b32 s15, s19, s25
	s_cselect_b32 s43, s18, s24
	s_ashr_i32 s17, s16, 31
	s_lshl_b64 s[20:21], s[16:17], 20
	v_readlane_b32 s28, v236, 52
	v_readlane_b32 s29, v236, 53
	s_add_u32 s20, s28, s20
	s_addc_u32 s21, s29, s21
	s_and_b64 s[28:29], s[4:5], exec
	s_cselect_b32 s17, s21, s27
	s_cselect_b32 s44, s20, s26
	s_add_u32 s24, s24, 0x80080
	s_addc_u32 s25, s25, 0
	s_add_u32 s45, s26, 0x100
	s_addc_u32 s46, s27, 0
	s_mov_b32 s47, -2
	ds_read_b128 v[128:131], v173
	ds_read_b128 v[132:135], v173 offset:1024
	ds_read_b128 v[136:139], v173 offset:2048
	ds_read_b128 v[140:143], v173 offset:3072
	ds_read_b128 v[176:179], v174
	ds_read_b128 v[180:183], v174 offset:1024
	ds_read_b128 v[188:191], v174 offset:2048
	ds_read_b128 v[192:195], v174 offset:3072
	s_add_u32 s26, s24, 0xfff80080
	s_addc_u32 s27, s25, -1
	s_cmp_eq_u32 s47, 28
	s_cselect_b32 s29, s15, s27
	s_cselect_b32 s28, s43, s26
	s_cselect_b32 s27, s17, s46
	s_cselect_b32 s26, s44, s45
	v_lshl_add_u64 v[160:161], s[24:25], 0, v[152:153]
	s_add_i32 m0, s23, 0xc000
	ds_read_b128 v[196:199], v175
	ds_read_b128 v[200:203], v175 offset:1024
	ds_read_b128 v[204:207], v175 offset:2048
	ds_read_b128 v[208:211], v175 offset:3072
	ds_read_b128 v[212:215], v175 offset:4096
	ds_read_b128 v[216:219], v175 offset:5120
	ds_read_b128 v[220:223], v175 offset:6144
	ds_read_b128 v[224:227], v175 offset:7168
	global_load_lds_dwordx4 v[160:161], off
	v_lshl_add_u64 v[160:161], s[24:25], 0, v[154:155]
	s_add_i32 m0, s23, 0xe000
	s_nop 0
	global_load_lds_dwordx4 v[160:161], off
	s_waitcnt vmcnt(8)
	s_waitcnt lgkmcnt(0)
	s_barrier
	s_setprio 1
	s_waitcnt lgkmcnt(0)
	v_mfma_f32_16x16x32_bf16 v[124:127], v[128:131], v[196:199], 0
	v_mfma_f32_16x16x32_bf16 v[120:123], v[136:139], v[196:199], 0
	v_mfma_f32_16x16x32_bf16 v[108:111], v[128:131], v[204:207], 0
	v_mfma_f32_16x16x32_bf16 v[104:107], v[136:139], v[204:207], 0
	v_mfma_f32_16x16x32_bf16 v[92:95], v[128:131], v[212:215], 0
	v_mfma_f32_16x16x32_bf16 v[88:91], v[136:139], v[212:215], 0
	v_mfma_f32_16x16x32_bf16 v[76:79], v[128:131], v[220:223], 0
	v_mfma_f32_16x16x32_bf16 v[72:75], v[136:139], v[220:223], 0
	v_mfma_f32_16x16x32_bf16 v[124:127], v[132:135], v[200:203], v[124:127]
	v_mfma_f32_16x16x32_bf16 v[120:123], v[140:143], v[200:203], v[120:123]
	v_mfma_f32_16x16x32_bf16 v[108:111], v[132:135], v[208:211], v[108:111]
	v_mfma_f32_16x16x32_bf16 v[104:107], v[140:143], v[208:211], v[104:107]
	v_mfma_f32_16x16x32_bf16 v[92:95], v[132:135], v[216:219], v[92:95]
	v_mfma_f32_16x16x32_bf16 v[88:91], v[140:143], v[216:219], v[88:91]
	v_mfma_f32_16x16x32_bf16 v[76:79], v[132:135], v[224:227], v[76:79]
	v_mfma_f32_16x16x32_bf16 v[72:75], v[140:143], v[224:227], v[72:75]
	s_setprio 0
	s_setprio 1
	v_mfma_f32_16x16x32_bf16 v[116:119], v[176:179], v[196:199], 0
	v_mfma_f32_16x16x32_bf16 v[112:115], v[188:191], v[196:199], 0
	v_mfma_f32_16x16x32_bf16 v[100:103], v[176:179], v[204:207], 0
	v_mfma_f32_16x16x32_bf16 v[96:99], v[188:191], v[204:207], 0
	v_mfma_f32_16x16x32_bf16 v[84:87], v[176:179], v[212:215], 0
	v_mfma_f32_16x16x32_bf16 v[80:83], v[188:191], v[212:215], 0
	v_mfma_f32_16x16x32_bf16 v[68:71], v[176:179], v[220:223], 0
	v_mfma_f32_16x16x32_bf16 v[64:67], v[188:191], v[220:223], 0
	v_mfma_f32_16x16x32_bf16 v[116:119], v[180:183], v[200:203], v[116:119]
	v_mfma_f32_16x16x32_bf16 v[112:115], v[192:195], v[200:203], v[112:115]
	v_mfma_f32_16x16x32_bf16 v[100:103], v[180:183], v[208:211], v[100:103]
	v_mfma_f32_16x16x32_bf16 v[96:99], v[192:195], v[208:211], v[96:99]
	v_mfma_f32_16x16x32_bf16 v[84:87], v[180:183], v[216:219], v[84:87]
	v_mfma_f32_16x16x32_bf16 v[80:83], v[192:195], v[216:219], v[80:83]
	v_mfma_f32_16x16x32_bf16 v[68:71], v[180:183], v[224:227], v[68:71]
	v_mfma_f32_16x16x32_bf16 v[64:67], v[192:195], v[224:227], v[64:67]
	s_setprio 0
	s_barrier
	s_add_i32 s48, s40, s31
	v_lshl_add_u64 v[160:161], s[26:27], 0, v[146:147]
	s_mov_b32 m0, s48
	ds_read_b128 v[196:199], v175 offset:16384
	ds_read_b128 v[200:203], v175 offset:17408
	ds_read_b128 v[204:207], v175 offset:18432
	ds_read_b128 v[208:211], v175 offset:19456
	ds_read_b128 v[212:215], v175 offset:20480
	ds_read_b128 v[216:219], v175 offset:21504
	ds_read_b128 v[220:223], v175 offset:22528
	ds_read_b128 v[224:227], v175 offset:23552
	global_load_lds_dwordx4 v[160:161], off
	s_add_i32 m0, s48, 0x2000
	s_add_u32 s48, s26, 0x80000
	v_lshl_add_u64 v[184:185], s[26:27], 0, v[150:151]
	s_addc_u32 s49, s27, 0
	s_add_i32 s50, s41, s31
	global_load_lds_dwordx4 v[184:185], off
	v_lshl_add_u64 v[228:229], s[48:49], 0, v[146:147]
	s_mov_b32 m0, s50
	v_lshl_add_u64 v[230:231], s[28:29], 0, v[148:149]
	global_load_lds_dwordx4 v[228:229], off
	v_lshl_add_u64 v[228:229], s[48:49], 0, v[150:151]
	s_add_i32 m0, s50, 0x2000
	s_nop 0
	global_load_lds_dwordx4 v[228:229], off
	v_lshl_add_u64 v[228:229], s[28:29], 0, v[144:145]
	s_mov_b32 m0, s23
	s_nop 0
	global_load_lds_dwordx4 v[228:229], off
	s_mov_b32 m0, s33
	s_nop 0
	global_load_lds_dwordx4 v[230:231], off
	s_waitcnt vmcnt(8)
	s_waitcnt lgkmcnt(0)
	s_barrier
; #define PG8_STAGE(bufoff, gbase, voff) do { _Pragma("unroll") for (int _i = 0; _i < 2; ++_i) \
;         __builtin_amdgcn_global_load_lds((const unsigned*)((const char*)(gbase) + (voff)[_i]), (PG8_LAS unsigned*)(lds + (bufoff) + ldsw + _i * 8192), 16, 0, 0); } while (0)
; #define PG8_LDA(dst, b, h) do { _Pragma("unroll") for (int m = 0; m < 4; ++m) _Pragma("unroll") for (int k = 0; k < 2; ++k) dst[m][k] = *(const PG8_LAS bf16x8*)(lds + PG8_SA(b, h) + aoff + m * 2048 + k * 1024); } while (0)
; #define PG8_LDB(dst, b, h) do { _Pragma("unroll") for (int n = 0; n < 2; ++n) _Pragma("unroll") for (int k = 0; k < 2; ++k) dst[n][k] = *(const PG8_LAS bf16x8*)(lds + PG8_SB(b, h) + boff + n * 2048 + k * 1024); } while (0)
; #define PG8_MMA(ai, bj, At, Bt) do { __builtin_amdgcn_s_setprio(1); _Pragma("unroll") for (int m = 0; m < 4; ++m) _Pragma("unroll") for (int n = 0; n < 2; ++n) _Pragma("unroll") for (int k = 0; k < 2; ++k) \
;         acc[ai][bj][m][n] = __builtin_amdgcn_mfma_f32_16x16x32_bf16(Bt[n][k], At[m][k], acc[ai][bj][m][n], 0, 0, 0); __builtin_amdgcn_s_setprio(0); } while (0)
; #define PG8_WAIT_V(n) asm volatile("s_waitcnt vmcnt(" #n ")" ::: "memory")
; #define PG8_WAIT_L(n) asm volatile("s_waitcnt lgkmcnt(" #n ")" ::: "memory")
; #define PG8_BAR __builtin_amdgcn_s_barrier()
; #define PG8_SCHED __builtin_amdgcn_sched_barrier(0)
; template <class Epi, class Sched, bool ALIGN_EPI = false, bool SP2 = false>
; __device__ __forceinline__ void gemm_phase(PG8_LAS unsigned char* lds, const Gemm g, const Sched& S, const Epi& E) {
;     ...
;             PG8_WAIT_V(8); PG8_WAIT_L(0); PG8_BAR; PG8_MMA(1, 0, At, B0); PG8_MMA(1, 1, At, B1); PG8_BAR; PG8_SCHED;
;             PG8_LDB(B0, 1, 0); PG8_LDB(B1, 1, 1); PG8_SCHED; PG8_LDA(At, 1, 0); PG8_STAGE(PG8_SA(0, 1), a2 + hstep, voffA);
;             PG8_WAIT_V(8); PG8_WAIT_L(0); PG8_BAR; PG8_MMA(0, 0, At, B0); PG8_MMA(0, 1, At, B1); PG8_BAR; PG8_SCHED;
	s_setprio 1
	s_waitcnt lgkmcnt(0)
	v_mfma_f32_16x16x32_bf16 v[60:63], v[128:131], v[196:199], 0
	v_mfma_f32_16x16x32_bf16 v[56:59], v[136:139], v[196:199], 0
	v_mfma_f32_16x16x32_bf16 v[44:47], v[128:131], v[204:207], 0
	v_mfma_f32_16x16x32_bf16 v[40:43], v[136:139], v[204:207], 0
	v_mfma_f32_16x16x32_bf16 v[28:31], v[128:131], v[212:215], 0
	v_mfma_f32_16x16x32_bf16 v[24:27], v[136:139], v[212:215], 0
	v_mfma_f32_16x16x32_bf16 v[12:15], v[128:131], v[220:223], 0
	v_mfma_f32_16x16x32_bf16 v[8:11], v[136:139], v[220:223], 0
	v_mfma_f32_16x16x32_bf16 v[60:63], v[132:135], v[200:203], v[60:63]
	v_mfma_f32_16x16x32_bf16 v[56:59], v[140:143], v[200:203], v[56:59]
	v_mfma_f32_16x16x32_bf16 v[44:47], v[132:135], v[208:211], v[44:47]
	v_mfma_f32_16x16x32_bf16 v[40:43], v[140:143], v[208:211], v[40:43]
	v_mfma_f32_16x16x32_bf16 v[28:31], v[132:135], v[216:219], v[28:31]
	v_mfma_f32_16x16x32_bf16 v[24:27], v[140:143], v[216:219], v[24:27]
	v_mfma_f32_16x16x32_bf16 v[12:15], v[132:135], v[224:227], v[12:15]
	v_mfma_f32_16x16x32_bf16 v[8:11], v[140:143], v[224:227], v[8:11]
	s_setprio 0
	s_setprio 1
	v_mfma_f32_16x16x32_bf16 v[52:55], v[176:179], v[196:199], 0
	v_mfma_f32_16x16x32_bf16 v[48:51], v[188:191], v[196:199], 0
	v_mfma_f32_16x16x32_bf16 v[36:39], v[176:179], v[204:207], 0
	v_mfma_f32_16x16x32_bf16 v[32:35], v[188:191], v[204:207], 0
	v_mfma_f32_16x16x32_bf16 v[20:23], v[176:179], v[212:215], 0
	v_mfma_f32_16x16x32_bf16 v[16:19], v[188:191], v[212:215], 0
	v_mfma_f32_16x16x32_bf16 v[4:7], v[176:179], v[220:223], 0
	v_mfma_f32_16x16x32_bf16 v[0:3], v[188:191], v[220:223], 0
	v_mfma_f32_16x16x32_bf16 v[52:55], v[180:183], v[200:203], v[52:55]
	v_mfma_f32_16x16x32_bf16 v[48:51], v[192:195], v[200:203], v[48:51]
	v_mfma_f32_16x16x32_bf16 v[36:39], v[180:183], v[208:211], v[36:39]
	v_mfma_f32_16x16x32_bf16 v[32:35], v[192:195], v[208:211], v[32:35]
	v_mfma_f32_16x16x32_bf16 v[20:23], v[180:183], v[216:219], v[20:23]
	v_mfma_f32_16x16x32_bf16 v[16:19], v[192:195], v[216:219], v[16:19]
	v_mfma_f32_16x16x32_bf16 v[4:7], v[180:183], v[224:227], v[4:7]
	v_mfma_f32_16x16x32_bf16 v[0:3], v[192:195], v[224:227], v[0:3]
	s_setprio 0
	s_barrier
	s_add_i32 s48, 0, 0x18000
	s_add_i32 s49, 0, 0x1c000
	v_add_u32_e32 v140, s48, v163
	v_add_u32_e32 v187, s49, v163
	ds_read_b128 v[128:131], v140
	ds_read_b128 v[132:135], v140 offset:1024
	ds_read_b128 v[136:139], v140 offset:2048
	ds_read_b128 v[140:143], v140 offset:3072
	ds_read_b128 v[176:179], v187
	ds_read_b128 v[180:183], v187 offset:1024
	ds_read_b128 v[188:191], v187 offset:2048
	ds_read_b128 v[192:195], v187 offset:3072
	s_add_u32 s28, s28, 0x80000
	s_addc_u32 s29, s29, 0
	s_mov_b32 m0, s34
	v_lshl_add_u64 v[232:233], s[28:29], 0, v[144:145]
	ds_read_b128 v[196:199], v175 offset:32768
	ds_read_b128 v[200:203], v175 offset:33792
	ds_read_b128 v[204:207], v175 offset:34816
	ds_read_b128 v[208:211], v175 offset:35840
	ds_read_b128 v[212:215], v175 offset:36864
	ds_read_b128 v[216:219], v175 offset:37888
	ds_read_b128 v[220:223], v175 offset:38912
	ds_read_b128 v[224:227], v175 offset:39936
	global_load_lds_dwordx4 v[232:233], off
	v_lshl_add_u64 v[232:233], s[28:29], 0, v[148:149]
	s_mov_b32 m0, s35
	s_nop 0
	global_load_lds_dwordx4 v[232:233], off
	s_waitcnt vmcnt(8)
	s_waitcnt lgkmcnt(0)
	s_barrier
	s_setprio 1
	s_waitcnt lgkmcnt(0)
	v_mfma_f32_16x16x32_bf16 v[124:127], v[128:131], v[196:199], v[124:127]
	v_mfma_f32_16x16x32_bf16 v[120:123], v[136:139], v[196:199], v[120:123]
	v_mfma_f32_16x16x32_bf16 v[108:111], v[128:131], v[204:207], v[108:111]
	v_mfma_f32_16x16x32_bf16 v[104:107], v[136:139], v[204:207], v[104:107]
	v_mfma_f32_16x16x32_bf16 v[92:95], v[128:131], v[212:215], v[92:95]
	v_mfma_f32_16x16x32_bf16 v[88:91], v[136:139], v[212:215], v[88:91]
	v_mfma_f32_16x16x32_bf16 v[76:79], v[128:131], v[220:223], v[76:79]
	v_mfma_f32_16x16x32_bf16 v[72:75], v[136:139], v[220:223], v[72:75]
	v_mfma_f32_16x16x32_bf16 v[124:127], v[132:135], v[200:203], v[124:127]
	v_mfma_f32_16x16x32_bf16 v[120:123], v[140:143], v[200:203], v[120:123]
	v_mfma_f32_16x16x32_bf16 v[108:111], v[132:135], v[208:211], v[108:111]
	v_mfma_f32_16x16x32_bf16 v[104:107], v[140:143], v[208:211], v[104:107]
	v_mfma_f32_16x16x32_bf16 v[92:95], v[132:135], v[216:219], v[92:95]
	v_mfma_f32_16x16x32_bf16 v[88:91], v[140:143], v[216:219], v[88:91]
	v_mfma_f32_16x16x32_bf16 v[76:79], v[132:135], v[224:227], v[76:79]
	v_mfma_f32_16x16x32_bf16 v[72:75], v[140:143], v[224:227], v[72:75]
	s_setprio 0
	s_setprio 1
	v_mfma_f32_16x16x32_bf16 v[116:119], v[176:179], v[196:199], v[116:119]
	v_mfma_f32_16x16x32_bf16 v[112:115], v[188:191], v[196:199], v[112:115]
	v_mfma_f32_16x16x32_bf16 v[100:103], v[176:179], v[204:207], v[100:103]
	v_mfma_f32_16x16x32_bf16 v[96:99], v[188:191], v[204:207], v[96:99]
	v_mfma_f32_16x16x32_bf16 v[84:87], v[176:179], v[212:215], v[84:87]
	v_mfma_f32_16x16x32_bf16 v[80:83], v[188:191], v[212:215], v[80:83]
	v_mfma_f32_16x16x32_bf16 v[68:71], v[176:179], v[220:223], v[68:71]
	v_mfma_f32_16x16x32_bf16 v[64:67], v[188:191], v[220:223], v[64:67]
	v_mfma_f32_16x16x32_bf16 v[116:119], v[180:183], v[200:203], v[116:119]
	v_mfma_f32_16x16x32_bf16 v[112:115], v[192:195], v[200:203], v[112:115]
	v_mfma_f32_16x16x32_bf16 v[100:103], v[180:183], v[208:211], v[100:103]
	v_mfma_f32_16x16x32_bf16 v[96:99], v[192:195], v[208:211], v[96:99]
	v_mfma_f32_16x16x32_bf16 v[84:87], v[180:183], v[216:219], v[84:87]
	v_mfma_f32_16x16x32_bf16 v[80:83], v[192:195], v[216:219], v[80:83]
	v_mfma_f32_16x16x32_bf16 v[68:71], v[180:183], v[224:227], v[68:71]
	v_mfma_f32_16x16x32_bf16 v[64:67], v[192:195], v[224:227], v[64:67]
	s_setprio 0
	s_barrier
; #define PG8_STAGE(bufoff, gbase, voff) do { _Pragma("unroll") for (int _i = 0; _i < 2; ++_i) \
;         __builtin_amdgcn_global_load_lds((const unsigned*)((const char*)(gbase) + (voff)[_i]), (PG8_LAS unsigned*)(lds + (bufoff) + ldsw + _i * 8192), 16, 0, 0); } while (0)
; #define PG8_LDA(dst, b, h) do { _Pragma("unroll") for (int m = 0; m < 4; ++m) _Pragma("unroll") for (int k = 0; k < 2; ++k) dst[m][k] = *(const PG8_LAS bf16x8*)(lds + PG8_SA(b, h) + aoff + m * 2048 + k * 1024); } while (0)
; #define PG8_MMA(ai, bj, At, Bt) do { __builtin_amdgcn_s_setprio(1); _Pragma("unroll") for (int m = 0; m < 4; ++m) _Pragma("unroll") for (int n = 0; n < 2; ++n) _Pragma("unroll") for (int k = 0; k < 2; ++k) \
;         acc[ai][bj][m][n] = __builtin_amdgcn_mfma_f32_16x16x32_bf16(Bt[n][k], At[m][k], acc[ai][bj][m][n], 0, 0, 0); __builtin_amdgcn_s_setprio(0); } while (0)
; #define PG8_WAIT_V(n) asm volatile("s_waitcnt vmcnt(" #n ")" ::: "memory")
; #define PG8_WAIT_L(n) asm volatile("s_waitcnt lgkmcnt(" #n ")" ::: "memory")
; #define PG8_BAR __builtin_amdgcn_s_barrier()
; #define PG8_SCHED __builtin_amdgcn_sched_barrier(0)
; template <class Epi, class Sched, bool ALIGN_EPI = false, bool SP2 = false>
; __device__ __forceinline__ void gemm_phase(PG8_LAS unsigned char* lds, const Gemm g, const Sched& S, const Epi& E) {
;     ...
;         for (int t = 0; t < nt; t += 2) {
;             const bool last = (t == nt - 2);
;             const char* a1 = cA + (size_t)(t + 1) * kstep;
;             const char* a2 = last ? nA : cA + (size_t)(t + 2) * kstep; const char* b2 = last ? nB : cB + (size_t)(t + 2) * kstep;
;     ...
;             PG8_LDA(At, 1, 1); PG8_STAGE(PG8_SB(1, 0), b3, voffB); PG8_STAGE(PG8_SB(1, 1), b3 + hstep, voffB); PG8_STAGE(PG8_SA(1, 0), a3, voffA);
;             PG8_WAIT_V(8); PG8_WAIT_L(0); PG8_BAR; PG8_MMA(1, 0, At, B0); PG8_MMA(1, 1, At, B1); PG8_BAR; PG8_SCHED;
	s_add_i32 s28, s48, s31
	v_lshl_add_u64 v[160:161], v[160:161], 0, s[10:11]
	s_mov_b32 m0, s28
	ds_read_b128 v[196:199], v175 offset:49152
	ds_read_b128 v[200:203], v175 offset:50176
	ds_read_b128 v[204:207], v175 offset:51200
	ds_read_b128 v[208:211], v175 offset:52224
	ds_read_b128 v[212:215], v175 offset:53248
	ds_read_b128 v[216:219], v175 offset:54272
	ds_read_b128 v[220:223], v175 offset:55296
	ds_read_b128 v[224:227], v175 offset:56320
	global_load_lds_dwordx4 v[160:161], off
	s_add_i32 m0, s28, 0x2000
	s_add_u32 s26, s26, 0x80080
	v_lshl_add_u64 v[160:161], v[184:185], 0, s[10:11]
	s_addc_u32 s27, s27, 0
	s_add_i32 s28, s49, s31
	global_load_lds_dwordx4 v[160:161], off
	v_lshl_add_u64 v[160:161], s[26:27], 0, v[146:147]
	s_mov_b32 m0, s28
	s_nop 0
	global_load_lds_dwordx4 v[160:161], off
	v_lshl_add_u64 v[160:161], s[26:27], 0, v[150:151]
	s_add_i32 m0, s28, 0x2000
	s_nop 0
	global_load_lds_dwordx4 v[160:161], off
	v_lshl_add_u64 v[160:161], v[228:229], 0, s[10:11]
	s_mov_b32 m0, s38
	s_nop 0
	global_load_lds_dwordx4 v[160:161], off
	v_lshl_add_u64 v[160:161], v[230:231], 0, s[10:11]
	s_mov_b32 m0, s39
	s_nop 0
	global_load_lds_dwordx4 v[160:161], off
	s_waitcnt vmcnt(8)
	s_waitcnt lgkmcnt(0)
	s_barrier
	s_setprio 1
	s_waitcnt lgkmcnt(0)
	v_mfma_f32_16x16x32_bf16 v[60:63], v[128:131], v[196:199], v[60:63]
	v_mfma_f32_16x16x32_bf16 v[56:59], v[136:139], v[196:199], v[56:59]
	v_mfma_f32_16x16x32_bf16 v[44:47], v[128:131], v[204:207], v[44:47]
	v_mfma_f32_16x16x32_bf16 v[40:43], v[136:139], v[204:207], v[40:43]
	v_mfma_f32_16x16x32_bf16 v[28:31], v[128:131], v[212:215], v[28:31]
	v_mfma_f32_16x16x32_bf16 v[24:27], v[136:139], v[212:215], v[24:27]
	v_mfma_f32_16x16x32_bf16 v[12:15], v[128:131], v[220:223], v[12:15]
	v_mfma_f32_16x16x32_bf16 v[8:11], v[136:139], v[220:223], v[8:11]
	v_mfma_f32_16x16x32_bf16 v[60:63], v[132:135], v[200:203], v[60:63]
	v_mfma_f32_16x16x32_bf16 v[56:59], v[140:143], v[200:203], v[56:59]
	v_mfma_f32_16x16x32_bf16 v[44:47], v[132:135], v[208:211], v[44:47]
	v_mfma_f32_16x16x32_bf16 v[40:43], v[140:143], v[208:211], v[40:43]
	v_mfma_f32_16x16x32_bf16 v[28:31], v[132:135], v[216:219], v[28:31]
	v_mfma_f32_16x16x32_bf16 v[24:27], v[140:143], v[216:219], v[24:27]
	v_mfma_f32_16x16x32_bf16 v[12:15], v[132:135], v[224:227], v[12:15]
	v_mfma_f32_16x16x32_bf16 v[8:11], v[140:143], v[224:227], v[8:11]
	s_setprio 0
	s_setprio 1
	v_mfma_f32_16x16x32_bf16 v[52:55], v[176:179], v[196:199], v[52:55]
	v_mfma_f32_16x16x32_bf16 v[48:51], v[188:191], v[196:199], v[48:51]
	v_mfma_f32_16x16x32_bf16 v[36:39], v[176:179], v[204:207], v[36:39]
	v_mfma_f32_16x16x32_bf16 v[32:35], v[188:191], v[204:207], v[32:35]
	v_mfma_f32_16x16x32_bf16 v[20:23], v[176:179], v[212:215], v[20:23]
	v_mfma_f32_16x16x32_bf16 v[16:19], v[188:191], v[212:215], v[16:19]
	v_mfma_f32_16x16x32_bf16 v[4:7], v[176:179], v[220:223], v[4:7]
	v_mfma_f32_16x16x32_bf16 v[0:3], v[188:191], v[220:223], v[0:3]
	v_mfma_f32_16x16x32_bf16 v[52:55], v[180:183], v[200:203], v[52:55]
	v_mfma_f32_16x16x32_bf16 v[48:51], v[192:195], v[200:203], v[48:51]
	v_mfma_f32_16x16x32_bf16 v[36:39], v[180:183], v[208:211], v[36:39]
	v_mfma_f32_16x16x32_bf16 v[32:35], v[192:195], v[208:211], v[32:35]
	v_mfma_f32_16x16x32_bf16 v[20:23], v[180:183], v[216:219], v[20:23]
	v_mfma_f32_16x16x32_bf16 v[16:19], v[192:195], v[216:219], v[16:19]
	v_mfma_f32_16x16x32_bf16 v[4:7], v[180:183], v[224:227], v[4:7]
	v_mfma_f32_16x16x32_bf16 v[0:3], v[192:195], v[224:227], v[0:3]
	s_setprio 0
	s_add_i32 s47, s47, 2
	s_add_u32 s24, s24, 0x100
	s_addc_u32 s25, s25, 0
	s_add_u32 s45, s45, 0x100
	s_addc_u32 s46, s46, 0
	s_cmp_gt_u32 s47, 29

; #define PG8_STAGE(bufoff, gbase, voff) do { _Pragma("unroll") for (int _i = 0; _i < 2; ++_i) \
;         __builtin_amdgcn_global_load_lds((const unsigned*)((const char*)(gbase) + (voff)[_i]), (PG8_LAS unsigned*)(lds + (bufoff) + ldsw + _i * 8192), 16, 0, 0); } while (0)
; #define PG8_LDA(dst, b, h) do { _Pragma("unroll") for (int m = 0; m < 4; ++m) _Pragma("unroll") for (int k = 0; k < 2; ++k) dst[m][k] = *(const PG8_LAS bf16x8*)(lds + PG8_SA(b, h) + aoff + m * 2048 + k * 1024); } while (0)
; #define PG8_LDB(dst, b, h) do { _Pragma("unroll") for (int n = 0; n < 2; ++n) _Pragma("unroll") for (int k = 0; k < 2; ++k) dst[n][k] = *(const PG8_LAS bf16x8*)(lds + PG8_SB(b, h) + boff + n * 2048 + k * 1024); } while (0)
; #define PG8_MMA(ai, bj, At, Bt) do { __builtin_amdgcn_s_setprio(1); _Pragma("unroll") for (int m = 0; m < 4; ++m) _Pragma("unroll") for (int n = 0; n < 2; ++n) _Pragma("unroll") for (int k = 0; k < 2; ++k) \
;         acc[ai][bj][m][n] = __builtin_amdgcn_mfma_f32_16x16x32_bf16(Bt[n][k], At[m][k], acc[ai][bj][m][n], 0, 0, 0); __builtin_amdgcn_s_setprio(0); } while (0)
; #define PG8_WAIT_V(n) asm volatile("s_waitcnt vmcnt(" #n ")" ::: "memory")
; #define PG8_WAIT_L(n) asm volatile("s_waitcnt lgkmcnt(" #n ")" ::: "memory")
; #define PG8_BAR __builtin_amdgcn_s_barrier()
; #define PG8_SCHED __builtin_amdgcn_sched_barrier(0)
; template <class Epi, class Sched, bool ALIGN_EPI = false, bool SP2 = false>
; __device__ __forceinline__ void gemm_phase(PG8_LAS unsigned char* lds, const Gemm g, const Sched& S, const Epi& E) {
;     ...
;         for (int t = 0; t < nt; t += 2) {
;             const bool last = (t == nt - 2);
;             const char* a1 = cA + (size_t)(t + 1) * kstep;
;             const char* a2 = last ? nA : cA + (size_t)(t + 2) * kstep; const char* b2 = last ? nB : cB + (size_t)(t + 2) * kstep;
;             const char* a3 = a2 + kstep; const char* b3 = b2 + kstep;
;             if (last && has_next) S.a_ready(nxt);
;             if constexpr (SP2) {
;             PG8_LDB(B0, 0, 0); PG8_LDB(B1, 0, 1); PG8_SCHED; PG8_LDA(At, 0, 0); PG8_STAGE(PG8_SA(1, 1), a1 + hstep, voffA);
;             PG8_WAIT_V(8); PG8_WAIT_L(0); PG8_BAR; PG8_MMA(0, 0, At, B0); PG8_MMA(0, 1, At, B1); PG8_BAR; PG8_SCHED;
;             PG8_LDA(At, 0, 1); PG8_STAGE(PG8_SB(0, 0), b2, voffB); PG8_STAGE(PG8_SB(0, 1), b2 + hstep, voffB); PG8_STAGE(PG8_SA(0, 0), a2, voffA);
.LBB0_994:
	ds_read_b128 v[128:131], v173
	ds_read_b128 v[132:135], v173 offset:1024
	ds_read_b128 v[136:139], v173 offset:2048
	ds_read_b128 v[140:143], v173 offset:3072
	ds_read_b128 v[176:179], v174
	ds_read_b128 v[180:183], v174 offset:1024
	ds_read_b128 v[188:191], v174 offset:2048
	ds_read_b128 v[192:195], v174 offset:3072
	s_add_u32 s26, s24, 0xfff80080
	s_addc_u32 s27, s25, -1
	s_cmp_eq_u32 s47, 28
	s_cselect_b32 s29, s15, s27
	s_cselect_b32 s28, s43, s26
	s_cselect_b32 s27, s17, s46
	s_cselect_b32 s26, s44, s45
	v_lshl_add_u64 v[160:161], s[24:25], 0, v[152:153]
	s_add_i32 m0, s23, 0xc000
	ds_read_b128 v[196:199], v175
	ds_read_b128 v[200:203], v175 offset:1024
	ds_read_b128 v[204:207], v175 offset:2048
	ds_read_b128 v[208:211], v175 offset:3072
	ds_read_b128 v[212:215], v175 offset:4096
	ds_read_b128 v[216:219], v175 offset:5120
	ds_read_b128 v[220:223], v175 offset:6144
	ds_read_b128 v[224:227], v175 offset:7168
	global_load_lds_dwordx4 v[160:161], off
	v_lshl_add_u64 v[160:161], s[24:25], 0, v[154:155]
	s_add_i32 m0, s23, 0xe000
	s_nop 0
	global_load_lds_dwordx4 v[160:161], off
	s_waitcnt vmcnt(8)
	s_waitcnt lgkmcnt(0)
	s_barrier
	s_setprio 1
	s_waitcnt lgkmcnt(0)
	v_mfma_f32_16x16x32_bf16 v[124:127], v[128:131], v[196:199], v[124:127]
	v_mfma_f32_16x16x32_bf16 v[120:123], v[136:139], v[196:199], v[120:123]
	v_mfma_f32_16x16x32_bf16 v[108:111], v[128:131], v[204:207], v[108:111]
	v_mfma_f32_16x16x32_bf16 v[104:107], v[136:139], v[204:207], v[104:107]
	v_mfma_f32_16x16x32_bf16 v[92:95], v[128:131], v[212:215], v[92:95]
	v_mfma_f32_16x16x32_bf16 v[88:91], v[136:139], v[212:215], v[88:91]
	v_mfma_f32_16x16x32_bf16 v[76:79], v[128:131], v[220:223], v[76:79]
	v_mfma_f32_16x16x32_bf16 v[72:75], v[136:139], v[220:223], v[72:75]
	v_mfma_f32_16x16x32_bf16 v[124:127], v[132:135], v[200:203], v[124:127]
	v_mfma_f32_16x16x32_bf16 v[120:123], v[140:143], v[200:203], v[120:123]
	v_mfma_f32_16x16x32_bf16 v[108:111], v[132:135], v[208:211], v[108:111]
	v_mfma_f32_16x16x32_bf16 v[104:107], v[140:143], v[208:211], v[104:107]
	v_mfma_f32_16x16x32_bf16 v[92:95], v[132:135], v[216:219], v[92:95]
	v_mfma_f32_16x16x32_bf16 v[88:91], v[140:143], v[216:219], v[88:91]
	v_mfma_f32_16x16x32_bf16 v[76:79], v[132:135], v[224:227], v[76:79]
	v_mfma_f32_16x16x32_bf16 v[72:75], v[140:143], v[224:227], v[72:75]
	s_setprio 0
	s_setprio 1
	v_mfma_f32_16x16x32_bf16 v[116:119], v[176:179], v[196:199], v[116:119]
	v_mfma_f32_16x16x32_bf16 v[112:115], v[188:191], v[196:199], v[112:115]
	v_mfma_f32_16x16x32_bf16 v[100:103], v[176:179], v[204:207], v[100:103]
	v_mfma_f32_16x16x32_bf16 v[96:99], v[188:191], v[204:207], v[96:99]
	v_mfma_f32_16x16x32_bf16 v[84:87], v[176:179], v[212:215], v[84:87]
	v_mfma_f32_16x16x32_bf16 v[80:83], v[188:191], v[212:215], v[80:83]
	v_mfma_f32_16x16x32_bf16 v[68:71], v[176:179], v[220:223], v[68:71]
	v_mfma_f32_16x16x32_bf16 v[64:67], v[188:191], v[220:223], v[64:67]
	v_mfma_f32_16x16x32_bf16 v[116:119], v[180:183], v[200:203], v[116:119]
	v_mfma_f32_16x16x32_bf16 v[112:115], v[192:195], v[200:203], v[112:115]
	v_mfma_f32_16x16x32_bf16 v[100:103], v[180:183], v[208:211], v[100:103]
	v_mfma_f32_16x16x32_bf16 v[96:99], v[192:195], v[208:211], v[96:99]
	v_mfma_f32_16x16x32_bf16 v[84:87], v[180:183], v[216:219], v[84:87]
	v_mfma_f32_16x16x32_bf16 v[80:83], v[192:195], v[216:219], v[80:83]
	v_mfma_f32_16x16x32_bf16 v[68:71], v[180:183], v[224:227], v[68:71]
	v_mfma_f32_16x16x32_bf16 v[64:67], v[192:195], v[224:227], v[64:67]
	s_setprio 0
	s_barrier
	s_add_i32 s48, s40, s31
	v_lshl_add_u64 v[160:161], s[26:27], 0, v[146:147]
	s_mov_b32 m0, s48
	ds_read_b128 v[196:199], v175 offset:16384
	ds_read_b128 v[200:203], v175 offset:17408
	ds_read_b128 v[204:207], v175 offset:18432
	ds_read_b128 v[208:211], v175 offset:19456
	ds_read_b128 v[212:215], v175 offset:20480
	ds_read_b128 v[216:219], v175 offset:21504
	ds_read_b128 v[220:223], v175 offset:22528
	ds_read_b128 v[224:227], v175 offset:23552
	global_load_lds_dwordx4 v[160:161], off
	s_add_i32 m0, s48, 0x2000
	s_add_u32 s48, s26, 0x80000
	v_lshl_add_u64 v[184:185], s[26:27], 0, v[150:151]
	s_addc_u32 s49, s27, 0
	s_add_i32 s50, s41, s31
	global_load_lds_dwordx4 v[184:185], off
	v_lshl_add_u64 v[228:229], s[48:49], 0, v[146:147]
	s_mov_b32 m0, s50
	v_lshl_add_u64 v[230:231], s[28:29], 0, v[148:149]
	global_load_lds_dwordx4 v[228:229], off
	v_lshl_add_u64 v[228:229], s[48:49], 0, v[150:151]
	s_add_i32 m0, s50, 0x2000
	s_nop 0
	global_load_lds_dwordx4 v[228:229], off
	v_lshl_add_u64 v[228:229], s[28:29], 0, v[144:145]
	s_mov_b32 m0, s23
	s_nop 0
	global_load_lds_dwordx4 v[228:229], off
	s_mov_b32 m0, s33
	s_nop 0
	global_load_lds_dwordx4 v[230:231], off
	s_waitcnt vmcnt(8)
	s_waitcnt lgkmcnt(0)
	s_barrier
; #define PG8_STAGE(bufoff, gbase, voff) do { _Pragma("unroll") for (int _i = 0; _i < 2; ++_i) \
;         __builtin_amdgcn_global_load_lds((const unsigned*)((const char*)(gbase) + (voff)[_i]), (PG8_LAS unsigned*)(lds + (bufoff) + ldsw + _i * 8192), 16, 0, 0); } while (0)
; #define PG8_LDA(dst, b, h) do { _Pragma("unroll") for (int m = 0; m < 4; ++m) _Pragma("unroll") for (int k = 0; k < 2; ++k) dst[m][k] = *(const PG8_LAS bf16x8*)(lds + PG8_SA(b, h) + aoff + m * 2048 + k * 1024); } while (0)
; #define PG8_LDB(dst, b, h) do { _Pragma("unroll") for (int n = 0; n < 2; ++n) _Pragma("unroll") for (int k = 0; k < 2; ++k) dst[n][k] = *(const PG8_LAS bf16x8*)(lds + PG8_SB(b, h) + boff + n * 2048 + k * 1024); } while (0)
; #define PG8_MMA(ai, bj, At, Bt) do { __builtin_amdgcn_s_setprio(1); _Pragma("unroll") for (int m = 0; m < 4; ++m) _Pragma("unroll") for (int n = 0; n < 2; ++n) _Pragma("unroll") for (int k = 0; k < 2; ++k) \
;         acc[ai][bj][m][n] = __builtin_amdgcn_mfma_f32_16x16x32_bf16(Bt[n][k], At[m][k], acc[ai][bj][m][n], 0, 0, 0); __builtin_amdgcn_s_setprio(0); } while (0)
; #define PG8_WAIT_V(n) asm volatile("s_waitcnt vmcnt(" #n ")" ::: "memory")
; #define PG8_WAIT_L(n) asm volatile("s_waitcnt lgkmcnt(" #n ")" ::: "memory")
; #define PG8_BAR __builtin_amdgcn_s_barrier()
; #define PG8_SCHED __builtin_amdgcn_sched_barrier(0)
; template <class Epi, class Sched, bool ALIGN_EPI = false, bool SP2 = false>
; __device__ __forceinline__ void gemm_phase(PG8_LAS unsigned char* lds, const Gemm g, const Sched& S, const Epi& E) {
;     ...
;             PG8_WAIT_V(8); PG8_WAIT_L(0); PG8_BAR; PG8_MMA(1, 0, At, B0); PG8_MMA(1, 1, At, B1); PG8_BAR; PG8_SCHED;
;             PG8_LDB(B0, 1, 0); PG8_LDB(B1, 1, 1); PG8_SCHED; PG8_LDA(At, 1, 0); PG8_STAGE(PG8_SA(0, 1), a2 + hstep, voffA);
;             PG8_WAIT_V(8); PG8_WAIT_L(0); PG8_BAR; PG8_MMA(0, 0, At, B0); PG8_MMA(0, 1, At, B1); PG8_BAR; PG8_SCHED;
	s_setprio 1
	s_waitcnt lgkmcnt(0)
	v_mfma_f32_16x16x32_bf16 v[60:63], v[128:131], v[196:199], v[60:63]
	v_mfma_f32_16x16x32_bf16 v[56:59], v[136:139], v[196:199], v[56:59]
	v_mfma_f32_16x16x32_bf16 v[44:47], v[128:131], v[204:207], v[44:47]
	v_mfma_f32_16x16x32_bf16 v[40:43], v[136:139], v[204:207], v[40:43]
	v_mfma_f32_16x16x32_bf16 v[28:31], v[128:131], v[212:215], v[28:31]
	v_mfma_f32_16x16x32_bf16 v[24:27], v[136:139], v[212:215], v[24:27]
	v_mfma_f32_16x16x32_bf16 v[12:15], v[128:131], v[220:223], v[12:15]
	v_mfma_f32_16x16x32_bf16 v[8:11], v[136:139], v[220:223], v[8:11]
	v_mfma_f32_16x16x32_bf16 v[60:63], v[132:135], v[200:203], v[60:63]
	v_mfma_f32_16x16x32_bf16 v[56:59], v[140:143], v[200:203], v[56:59]
	v_mfma_f32_16x16x32_bf16 v[44:47], v[132:135], v[208:211], v[44:47]
	v_mfma_f32_16x16x32_bf16 v[40:43], v[140:143], v[208:211], v[40:43]
	v_mfma_f32_16x16x32_bf16 v[28:31], v[132:135], v[216:219], v[28:31]
	v_mfma_f32_16x16x32_bf16 v[24:27], v[140:143], v[216:219], v[24:27]
	v_mfma_f32_16x16x32_bf16 v[12:15], v[132:135], v[224:227], v[12:15]
	v_mfma_f32_16x16x32_bf16 v[8:11], v[140:143], v[224:227], v[8:11]
	s_setprio 0
	s_setprio 1
	v_mfma_f32_16x16x32_bf16 v[52:55], v[176:179], v[196:199], v[52:55]
	v_mfma_f32_16x16x32_bf16 v[48:51], v[188:191], v[196:199], v[48:51]
	v_mfma_f32_16x16x32_bf16 v[36:39], v[176:179], v[204:207], v[36:39]
	v_mfma_f32_16x16x32_bf16 v[32:35], v[188:191], v[204:207], v[32:35]
	v_mfma_f32_16x16x32_bf16 v[20:23], v[176:179], v[212:215], v[20:23]
	v_mfma_f32_16x16x32_bf16 v[16:19], v[188:191], v[212:215], v[16:19]
	v_mfma_f32_16x16x32_bf16 v[4:7], v[176:179], v[220:223], v[4:7]
	v_mfma_f32_16x16x32_bf16 v[0:3], v[188:191], v[220:223], v[0:3]
	v_mfma_f32_16x16x32_bf16 v[52:55], v[180:183], v[200:203], v[52:55]
	v_mfma_f32_16x16x32_bf16 v[48:51], v[192:195], v[200:203], v[48:51]
	v_mfma_f32_16x16x32_bf16 v[36:39], v[180:183], v[208:211], v[36:39]
	v_mfma_f32_16x16x32_bf16 v[32:35], v[192:195], v[208:211], v[32:35]
	v_mfma_f32_16x16x32_bf16 v[20:23], v[180:183], v[216:219], v[20:23]
	v_mfma_f32_16x16x32_bf16 v[16:19], v[192:195], v[216:219], v[16:19]
	v_mfma_f32_16x16x32_bf16 v[4:7], v[180:183], v[224:227], v[4:7]
	v_mfma_f32_16x16x32_bf16 v[0:3], v[192:195], v[224:227], v[0:3]
	s_setprio 0
	s_barrier
	s_add_i32 s48, 0, 0x18000
	s_add_i32 s49, 0, 0x1c000
	v_add_u32_e32 v140, s48, v163
	v_add_u32_e32 v187, s49, v163
	ds_read_b128 v[128:131], v140
	ds_read_b128 v[132:135], v140 offset:1024
	ds_read_b128 v[136:139], v140 offset:2048
	ds_read_b128 v[140:143], v140 offset:3072
	ds_read_b128 v[176:179], v187
	ds_read_b128 v[180:183], v187 offset:1024
	ds_read_b128 v[188:191], v187 offset:2048
	ds_read_b128 v[192:195], v187 offset:3072
	s_add_u32 s28, s28, 0x80000
	s_addc_u32 s29, s29, 0
	s_mov_b32 m0, s34
	v_lshl_add_u64 v[232:233], s[28:29], 0, v[144:145]
	ds_read_b128 v[196:199], v175 offset:32768
	ds_read_b128 v[200:203], v175 offset:33792
	ds_read_b128 v[204:207], v175 offset:34816
	ds_read_b128 v[208:211], v175 offset:35840
	ds_read_b128 v[212:215], v175 offset:36864
	ds_read_b128 v[216:219], v175 offset:37888
	ds_read_b128 v[220:223], v175 offset:38912
	ds_read_b128 v[224:227], v175 offset:39936
	global_load_lds_dwordx4 v[232:233], off
	v_lshl_add_u64 v[232:233], s[28:29], 0, v[148:149]
	s_mov_b32 m0, s35
	s_nop 0
	global_load_lds_dwordx4 v[232:233], off
	s_waitcnt vmcnt(8)
	s_waitcnt lgkmcnt(0)
	s_barrier
	s_setprio 1
	s_waitcnt lgkmcnt(0)
	v_mfma_f32_16x16x32_bf16 v[124:127], v[128:131], v[196:199], v[124:127]
	v_mfma_f32_16x16x32_bf16 v[120:123], v[136:139], v[196:199], v[120:123]
	v_mfma_f32_16x16x32_bf16 v[108:111], v[128:131], v[204:207], v[108:111]
	v_mfma_f32_16x16x32_bf16 v[104:107], v[136:139], v[204:207], v[104:107]
	v_mfma_f32_16x16x32_bf16 v[92:95], v[128:131], v[212:215], v[92:95]
	v_mfma_f32_16x16x32_bf16 v[88:91], v[136:139], v[212:215], v[88:91]
	v_mfma_f32_16x16x32_bf16 v[76:79], v[128:131], v[220:223], v[76:79]
	v_mfma_f32_16x16x32_bf16 v[72:75], v[136:139], v[220:223], v[72:75]
	v_mfma_f32_16x16x32_bf16 v[124:127], v[132:135], v[200:203], v[124:127]
	v_mfma_f32_16x16x32_bf16 v[120:123], v[140:143], v[200:203], v[120:123]
	v_mfma_f32_16x16x32_bf16 v[108:111], v[132:135], v[208:211], v[108:111]
	v_mfma_f32_16x16x32_bf16 v[104:107], v[140:143], v[208:211], v[104:107]
	v_mfma_f32_16x16x32_bf16 v[92:95], v[132:135], v[216:219], v[92:95]
	v_mfma_f32_16x16x32_bf16 v[88:91], v[140:143], v[216:219], v[88:91]
	v_mfma_f32_16x16x32_bf16 v[76:79], v[132:135], v[224:227], v[76:79]
	v_mfma_f32_16x16x32_bf16 v[72:75], v[140:143], v[224:227], v[72:75]
	s_setprio 0
	s_setprio 1
	v_mfma_f32_16x16x32_bf16 v[116:119], v[176:179], v[196:199], v[116:119]
	v_mfma_f32_16x16x32_bf16 v[112:115], v[188:191], v[196:199], v[112:115]
	v_mfma_f32_16x16x32_bf16 v[100:103], v[176:179], v[204:207], v[100:103]
	v_mfma_f32_16x16x32_bf16 v[96:99], v[188:191], v[204:207], v[96:99]
	v_mfma_f32_16x16x32_bf16 v[84:87], v[176:179], v[212:215], v[84:87]
	v_mfma_f32_16x16x32_bf16 v[80:83], v[188:191], v[212:215], v[80:83]
	v_mfma_f32_16x16x32_bf16 v[68:71], v[176:179], v[220:223], v[68:71]
	v_mfma_f32_16x16x32_bf16 v[64:67], v[188:191], v[220:223], v[64:67]
	v_mfma_f32_16x16x32_bf16 v[116:119], v[180:183], v[200:203], v[116:119]
	v_mfma_f32_16x16x32_bf16 v[112:115], v[192:195], v[200:203], v[112:115]
	v_mfma_f32_16x16x32_bf16 v[100:103], v[180:183], v[208:211], v[100:103]
	v_mfma_f32_16x16x32_bf16 v[96:99], v[192:195], v[208:211], v[96:99]
	v_mfma_f32_16x16x32_bf16 v[84:87], v[180:183], v[216:219], v[84:87]
	v_mfma_f32_16x16x32_bf16 v[80:83], v[192:195], v[216:219], v[80:83]
	v_mfma_f32_16x16x32_bf16 v[68:71], v[180:183], v[224:227], v[68:71]
	v_mfma_f32_16x16x32_bf16 v[64:67], v[192:195], v[224:227], v[64:67]
	s_setprio 0
	s_barrier
; #define PG8_STAGE(bufoff, gbase, voff) do { _Pragma("unroll") for (int _i = 0; _i < 2; ++_i) \
;         __builtin_amdgcn_global_load_lds((const unsigned*)((const char*)(gbase) + (voff)[_i]), (PG8_LAS unsigned*)(lds + (bufoff) + ldsw + _i * 8192), 16, 0, 0); } while (0)
; #define PG8_LDA(dst, b, h) do { _Pragma("unroll") for (int m = 0; m < 4; ++m) _Pragma("unroll") for (int k = 0; k < 2; ++k) dst[m][k] = *(const PG8_LAS bf16x8*)(lds + PG8_SA(b, h) + aoff + m * 2048 + k * 1024); } while (0)
; #define PG8_MMA(ai, bj, At, Bt) do { __builtin_amdgcn_s_setprio(1); _Pragma("unroll") for (int m = 0; m < 4; ++m) _Pragma("unroll") for (int n = 0; n < 2; ++n) _Pragma("unroll") for (int k = 0; k < 2; ++k) \
;         acc[ai][bj][m][n] = __builtin_amdgcn_mfma_f32_16x16x32_bf16(Bt[n][k], At[m][k], acc[ai][bj][m][n], 0, 0, 0); __builtin_amdgcn_s_setprio(0); } while (0)
; #define PG8_WAIT_V(n) asm volatile("s_waitcnt vmcnt(" #n ")" ::: "memory")
; #define PG8_WAIT_L(n) asm volatile("s_waitcnt lgkmcnt(" #n ")" ::: "memory")
; #define PG8_BAR __builtin_amdgcn_s_barrier()
; #define PG8_SCHED __builtin_amdgcn_sched_barrier(0)
; template <class Epi, class Sched, bool ALIGN_EPI = false, bool SP2 = false>
; __device__ __forceinline__ void gemm_phase(PG8_LAS unsigned char* lds, const Gemm g, const Sched& S, const Epi& E) {
;     ...
;         for (int t = 0; t < nt; t += 2) {
;     ...
;             PG8_LDA(At, 1, 1); PG8_STAGE(PG8_SB(1, 0), b3, voffB); PG8_STAGE(PG8_SB(1, 1), b3 + hstep, voffB); PG8_STAGE(PG8_SA(1, 0), a3, voffA);
;             PG8_WAIT_V(8); PG8_WAIT_L(0); PG8_BAR; PG8_MMA(1, 0, At, B0); PG8_MMA(1, 1, At, B1); PG8_BAR; PG8_SCHED;
;     ...
;         if constexpr (ALIGN_EPI) { if (wr == 0) PG8_BAR; }
	s_add_i32 s28, s48, s31
	v_lshl_add_u64 v[160:161], v[160:161], 0, s[10:11]
	s_mov_b32 m0, s28
	ds_read_b128 v[196:199], v175 offset:49152
	ds_read_b128 v[200:203], v175 offset:50176
	ds_read_b128 v[204:207], v175 offset:51200
	ds_read_b128 v[208:211], v175 offset:52224
	ds_read_b128 v[212:215], v175 offset:53248
	ds_read_b128 v[216:219], v175 offset:54272
	ds_read_b128 v[220:223], v175 offset:55296
	ds_read_b128 v[224:227], v175 offset:56320
	global_load_lds_dwordx4 v[160:161], off
	s_add_i32 m0, s28, 0x2000
	s_add_u32 s26, s26, 0x80080
	v_lshl_add_u64 v[160:161], v[184:185], 0, s[10:11]
	s_addc_u32 s27, s27, 0
	s_add_i32 s28, s49, s31
	global_load_lds_dwordx4 v[160:161], off
	v_lshl_add_u64 v[160:161], s[26:27], 0, v[146:147]
	s_mov_b32 m0, s28
	s_nop 0
	global_load_lds_dwordx4 v[160:161], off
	v_lshl_add_u64 v[160:161], s[26:27], 0, v[150:151]
	s_add_i32 m0, s28, 0x2000
	s_nop 0
	global_load_lds_dwordx4 v[160:161], off
	v_lshl_add_u64 v[160:161], v[228:229], 0, s[10:11]
	s_mov_b32 m0, s38
	s_nop 0
	global_load_lds_dwordx4 v[160:161], off
	v_lshl_add_u64 v[160:161], v[230:231], 0, s[10:11]
	s_mov_b32 m0, s39
	s_nop 0
	global_load_lds_dwordx4 v[160:161], off
	s_waitcnt vmcnt(8)
	s_waitcnt lgkmcnt(0)
	s_barrier
	s_setprio 1
	s_waitcnt lgkmcnt(0)
	v_mfma_f32_16x16x32_bf16 v[60:63], v[128:131], v[196:199], v[60:63]
	v_mfma_f32_16x16x32_bf16 v[56:59], v[136:139], v[196:199], v[56:59]
	v_mfma_f32_16x16x32_bf16 v[44:47], v[128:131], v[204:207], v[44:47]
	v_mfma_f32_16x16x32_bf16 v[40:43], v[136:139], v[204:207], v[40:43]
	v_mfma_f32_16x16x32_bf16 v[28:31], v[128:131], v[212:215], v[28:31]
	v_mfma_f32_16x16x32_bf16 v[24:27], v[136:139], v[212:215], v[24:27]
	v_mfma_f32_16x16x32_bf16 v[12:15], v[128:131], v[220:223], v[12:15]
	v_mfma_f32_16x16x32_bf16 v[8:11], v[136:139], v[220:223], v[8:11]
	v_mfma_f32_16x16x32_bf16 v[60:63], v[132:135], v[200:203], v[60:63]
	v_mfma_f32_16x16x32_bf16 v[56:59], v[140:143], v[200:203], v[56:59]
	v_mfma_f32_16x16x32_bf16 v[44:47], v[132:135], v[208:211], v[44:47]
	v_mfma_f32_16x16x32_bf16 v[40:43], v[140:143], v[208:211], v[40:43]
	v_mfma_f32_16x16x32_bf16 v[28:31], v[132:135], v[216:219], v[28:31]
	v_mfma_f32_16x16x32_bf16 v[24:27], v[140:143], v[216:219], v[24:27]
	v_mfma_f32_16x16x32_bf16 v[12:15], v[132:135], v[224:227], v[12:15]
	v_mfma_f32_16x16x32_bf16 v[8:11], v[140:143], v[224:227], v[8:11]
	s_setprio 0
	s_setprio 1
	v_mfma_f32_16x16x32_bf16 v[52:55], v[176:179], v[196:199], v[52:55]
	v_mfma_f32_16x16x32_bf16 v[48:51], v[188:191], v[196:199], v[48:51]
	v_mfma_f32_16x16x32_bf16 v[36:39], v[176:179], v[204:207], v[36:39]
	v_mfma_f32_16x16x32_bf16 v[32:35], v[188:191], v[204:207], v[32:35]
	v_mfma_f32_16x16x32_bf16 v[20:23], v[176:179], v[212:215], v[20:23]
	v_mfma_f32_16x16x32_bf16 v[16:19], v[188:191], v[212:215], v[16:19]
	v_mfma_f32_16x16x32_bf16 v[4:7], v[176:179], v[220:223], v[4:7]
	v_mfma_f32_16x16x32_bf16 v[0:3], v[188:191], v[220:223], v[0:3]
	v_mfma_f32_16x16x32_bf16 v[52:55], v[180:183], v[200:203], v[52:55]
	v_mfma_f32_16x16x32_bf16 v[48:51], v[192:195], v[200:203], v[48:51]
	v_mfma_f32_16x16x32_bf16 v[36:39], v[180:183], v[208:211], v[36:39]
	v_mfma_f32_16x16x32_bf16 v[32:35], v[192:195], v[208:211], v[32:35]
	v_mfma_f32_16x16x32_bf16 v[20:23], v[180:183], v[216:219], v[20:23]
	v_mfma_f32_16x16x32_bf16 v[16:19], v[192:195], v[216:219], v[16:19]
	v_mfma_f32_16x16x32_bf16 v[4:7], v[180:183], v[224:227], v[4:7]
	v_mfma_f32_16x16x32_bf16 v[0:3], v[192:195], v[224:227], v[0:3]
	s_setprio 0
	s_add_i32 s47, s47, 2
	s_add_u32 s24, s24, 0x100
	s_addc_u32 s25, s25, 0
	s_add_u32 s45, s45, 0x100
	s_addc_u32 s46, s46, 0
	s_cmp_gt_u32 s47, 29
	s_cbranch_scc0 .Lrot_994
	s_barrier
	s_and_b64 vcc, exec, s[12:13]
	s_cbranch_vccz .LBB0_997
	s_barrier

;     __device__ __forceinline__ bool next(int i, Unit& u) const { if (!base.next(i >> 1, u)) return false; if (i & 1) { u.pm += 64; u.pn += 8; } return true; }
; #define PG8_STAGE(bufoff, gbase, voff) do { _Pragma("unroll") for (int _i = 0; _i < 2; ++_i) \
;         __builtin_amdgcn_global_load_lds((const unsigned*)((const char*)(gbase) + (voff)[_i]), (PG8_LAS unsigned*)(lds + (bufoff) + ldsw + _i * 8192), 16, 0, 0); } while (0)
; #define PG8_LDA(dst, b, h) do { _Pragma("unroll") for (int m = 0; m < 4; ++m) _Pragma("unroll") for (int k = 0; k < 2; ++k) dst[m][k] = *(const PG8_LAS bf16x8*)(lds + PG8_SA(b, h) + aoff + m * 2048 + k * 1024); } while (0)
; #define PG8_LDB(dst, b, h) do { _Pragma("unroll") for (int n = 0; n < 2; ++n) _Pragma("unroll") for (int k = 0; k < 2; ++k) dst[n][k] = *(const PG8_LAS bf16x8*)(lds + PG8_SB(b, h) + boff + n * 2048 + k * 1024); } while (0)
; #define PG8_WAIT_V(n) asm volatile("s_waitcnt vmcnt(" #n ")" ::: "memory")
; #define PG8_WAIT_L(n) asm volatile("s_waitcnt lgkmcnt(" #n ")" ::: "memory")
; #define PG8_BAR __builtin_amdgcn_s_barrier()
; #define PG8_SCHED __builtin_amdgcn_sched_barrier(0)
; template <class Epi, class Sched, bool ALIGN_EPI = false, bool SP2 = false>
; __device__ __forceinline__ void gemm_phase(PG8_LAS unsigned char* lds, const Gemm g, const Sched& S, const Epi& E) {
;     ...
;         const bool has_next = S.next(ui + 1, nxt);
;         const char* nA = has_next ? (const char*)g.A + (size_t)nxt.pm * tstep : cA; const char* nB = has_next ? (const char*)g.Bt + (size_t)nxt.pn * tstep : cB;
;         for (int t = 0; t < nt; t += 2) {
;             const bool last = (t == nt - 2);
;             const char* a1 = cA + (size_t)(t + 1) * kstep;
;             const char* a2 = last ? nA : cA + (size_t)(t + 2) * kstep; const char* b2 = last ? nB : cB + (size_t)(t + 2) * kstep;
;             const char* a3 = a2 + kstep; const char* b3 = b2 + kstep;
;             if (last && has_next) S.a_ready(nxt);
;             if constexpr (SP2) {
;             PG8_LDB(B0, 0, 0); PG8_LDB(B1, 0, 1); PG8_SCHED; PG8_LDA(At, 0, 0); PG8_STAGE(PG8_SA(1, 1), a1 + hstep, voffA);
;             PG8_WAIT_V(8); PG8_WAIT_L(0); PG8_BAR; PG8_MMA(0, 0, At, B0); PG8_MMA(0, 1, At, B1); PG8_BAR; PG8_SCHED;
;             PG8_LDA(At, 0, 1); PG8_STAGE(PG8_SB(0, 0), b2, voffB); PG8_STAGE(PG8_SB(0, 1), b2 + hstep, voffB); PG8_STAGE(PG8_SA(0, 0), a2, voffA);
.LBB0_1070:
	s_ashr_i32 s19, s18, 31
	s_lshl_b64 s[20:21], s[18:19], 22
	s_add_u32 s20, s72, s20
	s_addc_u32 s21, s73, s21
	s_and_b64 s[22:23], s[0:1], exec
	s_cselect_b32 s19, s21, s27
	s_cselect_b32 s51, s20, s26
	s_ashr_i32 s17, s16, 31
	s_lshl_b64 s[22:23], s[16:17], 22
	v_readlane_b32 s30, v236, 54
	v_readlane_b32 s31, v236, 55
	s_add_u32 s22, s30, s22
	s_addc_u32 s23, s31, s23
	s_and_b64 s[30:31], s[0:1], exec
	s_cselect_b32 s17, s23, s29
	s_cselect_b32 s52, s22, s28
	s_add_u32 s26, s26, 0x200080
	s_addc_u32 s27, s27, 0
	s_add_u32 s53, s28, 0x100
	s_addc_u32 s54, s29, 0
	s_mov_b32 s55, -2
	ds_read_b128 v[64:67], v165
	ds_read_b128 v[108:111], v165 offset:1024
	ds_read_b128 v[116:119], v165 offset:2048
	ds_read_b128 v[128:131], v165 offset:3072
	ds_read_b128 v[156:159], v166
	ds_read_b128 v[168:171], v166 offset:1024
	ds_read_b128 v[172:175], v166 offset:2048
	ds_read_b128 v[176:179], v166 offset:3072
	s_add_u32 s28, s26, 0xffe00080
	s_addc_u32 s29, s27, -1
	s_cmpk_eq_i32 s55, 0x7c
	s_cselect_b32 s31, s19, s29
	s_cselect_b32 s30, s51, s28
	s_cselect_b32 s29, s17, s54
	s_cselect_b32 s28, s52, s53
	v_lshl_add_u64 v[160:161], s[26:27], 0, v[148:149]
	s_add_i32 m0, s35, 0xc000
	ds_read_b128 v[180:183], v167
	ds_read_b128 v[184:187], v167 offset:1024
	ds_read_b128 v[188:191], v167 offset:2048
	ds_read_b128 v[192:195], v167 offset:3072
	ds_read_b128 v[196:199], v167 offset:4096
	ds_read_b128 v[200:203], v167 offset:5120
	ds_read_b128 v[204:207], v167 offset:6144
	ds_read_b128 v[208:211], v167 offset:7168
	global_load_lds_dwordx4 v[160:161], off
	v_lshl_add_u64 v[160:161], s[26:27], 0, v[150:151]
	s_add_i32 m0, s35, 0xe000
	s_nop 0
	global_load_lds_dwordx4 v[160:161], off
	s_waitcnt vmcnt(8)
	s_waitcnt lgkmcnt(0)
	s_barrier
	s_setprio 1
	s_waitcnt lgkmcnt(0)
	v_mfma_f32_16x16x32_bf16 v[140:143], v[64:67], v[180:183], 0
	v_mfma_f32_16x16x32_bf16 v[136:139], v[116:119], v[180:183], 0
	v_mfma_f32_16x16x32_bf16 v[120:123], v[64:67], v[188:191], 0
	v_mfma_f32_16x16x32_bf16 v[112:115], v[116:119], v[188:191], 0
	v_mfma_f32_16x16x32_bf16 v[96:99], v[64:67], v[196:199], 0
	v_mfma_f32_16x16x32_bf16 v[92:95], v[116:119], v[196:199], 0
	v_mfma_f32_16x16x32_bf16 v[80:83], v[64:67], v[204:207], 0
	v_mfma_f32_16x16x32_bf16 v[76:79], v[116:119], v[204:207], 0
	v_mfma_f32_16x16x32_bf16 v[140:143], v[108:111], v[184:187], v[140:143]
	v_mfma_f32_16x16x32_bf16 v[136:139], v[128:131], v[184:187], v[136:139]
	v_mfma_f32_16x16x32_bf16 v[120:123], v[108:111], v[192:195], v[120:123]
	v_mfma_f32_16x16x32_bf16 v[112:115], v[128:131], v[192:195], v[112:115]
	v_mfma_f32_16x16x32_bf16 v[96:99], v[108:111], v[200:203], v[96:99]
	v_mfma_f32_16x16x32_bf16 v[92:95], v[128:131], v[200:203], v[92:95]
	v_mfma_f32_16x16x32_bf16 v[80:83], v[108:111], v[208:211], v[80:83]
	v_mfma_f32_16x16x32_bf16 v[76:79], v[128:131], v[208:211], v[76:79]
	s_setprio 0
	s_setprio 1
	v_mfma_f32_16x16x32_bf16 v[132:135], v[156:159], v[180:183], 0
	v_mfma_f32_16x16x32_bf16 v[124:127], v[172:175], v[180:183], 0
	v_mfma_f32_16x16x32_bf16 v[104:107], v[156:159], v[188:191], 0
	v_mfma_f32_16x16x32_bf16 v[100:103], v[172:175], v[188:191], 0
	v_mfma_f32_16x16x32_bf16 v[88:91], v[156:159], v[196:199], 0
	v_mfma_f32_16x16x32_bf16 v[84:87], v[172:175], v[196:199], 0
	v_mfma_f32_16x16x32_bf16 v[72:75], v[156:159], v[204:207], 0
	v_mfma_f32_16x16x32_bf16 v[68:71], v[172:175], v[204:207], 0
	v_mfma_f32_16x16x32_bf16 v[132:135], v[168:171], v[184:187], v[132:135]
	v_mfma_f32_16x16x32_bf16 v[124:127], v[176:179], v[184:187], v[124:127]
	v_mfma_f32_16x16x32_bf16 v[104:107], v[168:171], v[192:195], v[104:107]
	v_mfma_f32_16x16x32_bf16 v[100:103], v[176:179], v[192:195], v[100:103]
	v_mfma_f32_16x16x32_bf16 v[88:91], v[168:171], v[200:203], v[88:91]
	v_mfma_f32_16x16x32_bf16 v[84:87], v[176:179], v[200:203], v[84:87]
	v_mfma_f32_16x16x32_bf16 v[72:75], v[168:171], v[208:211], v[72:75]
	v_mfma_f32_16x16x32_bf16 v[68:71], v[176:179], v[208:211], v[68:71]
	s_setprio 0
	s_barrier
	s_add_i32 s56, s45, s34
	v_lshl_add_u64 v[160:161], s[28:29], 0, v[144:145]
	s_mov_b32 m0, s56
	ds_read_b128 v[180:183], v167 offset:16384
	ds_read_b128 v[184:187], v167 offset:17408
	ds_read_b128 v[188:191], v167 offset:18432
	ds_read_b128 v[192:195], v167 offset:19456
	ds_read_b128 v[196:199], v167 offset:20480
	ds_read_b128 v[200:203], v167 offset:21504
	ds_read_b128 v[204:207], v167 offset:22528
	ds_read_b128 v[208:211], v167 offset:23552
	global_load_lds_dwordx4 v[160:161], off
	s_add_i32 m0, s56, 0x2000
	s_add_u32 s56, s28, 0x200000
	v_lshl_add_u64 v[212:213], s[28:29], 0, v[146:147]
	s_addc_u32 s57, s29, 0
	s_add_i32 s58, s46, s34
	global_load_lds_dwordx4 v[212:213], off
	v_lshl_add_u64 v[214:215], s[56:57], 0, v[144:145]
	s_mov_b32 m0, s58
	v_lshl_add_u64 v[216:217], s[30:31], 0, v[146:147]
	global_load_lds_dwordx4 v[214:215], off
	v_lshl_add_u64 v[214:215], s[56:57], 0, v[146:147]
	s_add_i32 m0, s58, 0x2000
	s_nop 0
	global_load_lds_dwordx4 v[214:215], off
	v_lshl_add_u64 v[214:215], s[30:31], 0, v[144:145]
	s_mov_b32 m0, s35
	s_nop 0
	global_load_lds_dwordx4 v[214:215], off
	s_mov_b32 m0, s36
	s_nop 0
	global_load_lds_dwordx4 v[216:217], off
	s_waitcnt vmcnt(8)
	s_waitcnt lgkmcnt(0)
	s_barrier
; #define PG8_STAGE(bufoff, gbase, voff) do { _Pragma("unroll") for (int _i = 0; _i < 2; ++_i) \
;         __builtin_amdgcn_global_load_lds((const unsigned*)((const char*)(gbase) + (voff)[_i]), (PG8_LAS unsigned*)(lds + (bufoff) + ldsw + _i * 8192), 16, 0, 0); } while (0)
; #define PG8_LDA(dst, b, h) do { _Pragma("unroll") for (int m = 0; m < 4; ++m) _Pragma("unroll") for (int k = 0; k < 2; ++k) dst[m][k] = *(const PG8_LAS bf16x8*)(lds + PG8_SA(b, h) + aoff + m * 2048 + k * 1024); } while (0)
; #define PG8_LDB(dst, b, h) do { _Pragma("unroll") for (int n = 0; n < 2; ++n) _Pragma("unroll") for (int k = 0; k < 2; ++k) dst[n][k] = *(const PG8_LAS bf16x8*)(lds + PG8_SB(b, h) + boff + n * 2048 + k * 1024); } while (0)
; #define PG8_MMA(ai, bj, At, Bt) do { __builtin_amdgcn_s_setprio(1); _Pragma("unroll") for (int m = 0; m < 4; ++m) _Pragma("unroll") for (int n = 0; n < 2; ++n) _Pragma("unroll") for (int k = 0; k < 2; ++k) \
;         acc[ai][bj][m][n] = __builtin_amdgcn_mfma_f32_16x16x32_bf16(Bt[n][k], At[m][k], acc[ai][bj][m][n], 0, 0, 0); __builtin_amdgcn_s_setprio(0); } while (0)
; #define PG8_WAIT_V(n) asm volatile("s_waitcnt vmcnt(" #n ")" ::: "memory")
; #define PG8_WAIT_L(n) asm volatile("s_waitcnt lgkmcnt(" #n ")" ::: "memory")
; #define PG8_BAR __builtin_amdgcn_s_barrier()
; #define PG8_SCHED __builtin_amdgcn_sched_barrier(0)
; template <class Epi, class Sched, bool ALIGN_EPI = false, bool SP2 = false>
; __device__ __forceinline__ void gemm_phase(PG8_LAS unsigned char* lds, const Gemm g, const Sched& S, const Epi& E) {
;     ...
;             PG8_WAIT_V(8); PG8_WAIT_L(0); PG8_BAR; PG8_MMA(1, 0, At, B0); PG8_MMA(1, 1, At, B1); PG8_BAR; PG8_SCHED;
;             PG8_LDB(B0, 1, 0); PG8_LDB(B1, 1, 1); PG8_SCHED; PG8_LDA(At, 1, 0); PG8_STAGE(PG8_SA(0, 1), a2 + hstep, voffA);
;             PG8_WAIT_V(8); PG8_WAIT_L(0); PG8_BAR; PG8_MMA(0, 0, At, B0); PG8_MMA(0, 1, At, B1); PG8_BAR; PG8_SCHED;
	s_setprio 1
	s_waitcnt lgkmcnt(0)
	v_mfma_f32_16x16x32_bf16 v[60:63], v[64:67], v[180:183], 0
	v_mfma_f32_16x16x32_bf16 v[56:59], v[116:119], v[180:183], 0
	v_mfma_f32_16x16x32_bf16 v[44:47], v[64:67], v[188:191], 0
	v_mfma_f32_16x16x32_bf16 v[40:43], v[116:119], v[188:191], 0
	v_mfma_f32_16x16x32_bf16 v[28:31], v[64:67], v[196:199], 0
	v_mfma_f32_16x16x32_bf16 v[24:27], v[116:119], v[196:199], 0
	v_mfma_f32_16x16x32_bf16 v[12:15], v[64:67], v[204:207], 0
	v_mfma_f32_16x16x32_bf16 v[8:11], v[116:119], v[204:207], 0
	v_mfma_f32_16x16x32_bf16 v[60:63], v[108:111], v[184:187], v[60:63]
	v_mfma_f32_16x16x32_bf16 v[56:59], v[128:131], v[184:187], v[56:59]
	v_mfma_f32_16x16x32_bf16 v[44:47], v[108:111], v[192:195], v[44:47]
	v_mfma_f32_16x16x32_bf16 v[40:43], v[128:131], v[192:195], v[40:43]
	v_mfma_f32_16x16x32_bf16 v[28:31], v[108:111], v[200:203], v[28:31]
	v_mfma_f32_16x16x32_bf16 v[24:27], v[128:131], v[200:203], v[24:27]
	v_mfma_f32_16x16x32_bf16 v[12:15], v[108:111], v[208:211], v[12:15]
	v_mfma_f32_16x16x32_bf16 v[8:11], v[128:131], v[208:211], v[8:11]
	s_setprio 0
	s_setprio 1
	v_mfma_f32_16x16x32_bf16 v[52:55], v[156:159], v[180:183], 0
	v_mfma_f32_16x16x32_bf16 v[48:51], v[172:175], v[180:183], 0
	v_mfma_f32_16x16x32_bf16 v[36:39], v[156:159], v[188:191], 0
	v_mfma_f32_16x16x32_bf16 v[32:35], v[172:175], v[188:191], 0
	v_mfma_f32_16x16x32_bf16 v[20:23], v[156:159], v[196:199], 0
	v_mfma_f32_16x16x32_bf16 v[16:19], v[172:175], v[196:199], 0
	v_mfma_f32_16x16x32_bf16 v[4:7], v[156:159], v[204:207], 0
	v_mfma_f32_16x16x32_bf16 v[0:3], v[172:175], v[204:207], 0
	v_mfma_f32_16x16x32_bf16 v[52:55], v[168:171], v[184:187], v[52:55]
	v_mfma_f32_16x16x32_bf16 v[48:51], v[176:179], v[184:187], v[48:51]
	v_mfma_f32_16x16x32_bf16 v[36:39], v[168:171], v[192:195], v[36:39]
	v_mfma_f32_16x16x32_bf16 v[32:35], v[176:179], v[192:195], v[32:35]
	v_mfma_f32_16x16x32_bf16 v[20:23], v[168:171], v[200:203], v[20:23]
	v_mfma_f32_16x16x32_bf16 v[16:19], v[176:179], v[200:203], v[16:19]
	v_mfma_f32_16x16x32_bf16 v[4:7], v[168:171], v[208:211], v[4:7]
	v_mfma_f32_16x16x32_bf16 v[0:3], v[176:179], v[208:211], v[0:3]
	s_setprio 0
	s_barrier
	s_add_i32 s56, 0, 0x18000
	s_add_i32 s57, 0, 0x1c000
	v_add_u32_e32 v128, s56, v163
	v_add_u32_e32 v176, s57, v163
	ds_read_b128 v[64:67], v128
	ds_read_b128 v[108:111], v128 offset:1024
	ds_read_b128 v[116:119], v128 offset:2048
	ds_read_b128 v[128:131], v128 offset:3072
	ds_read_b128 v[156:159], v176
	ds_read_b128 v[168:171], v176 offset:1024
	ds_read_b128 v[172:175], v176 offset:2048
	ds_read_b128 v[176:179], v176 offset:3072
	s_add_u32 s30, s30, 0x200000
	s_addc_u32 s31, s31, 0
	s_mov_b32 m0, s37
	v_lshl_add_u64 v[218:219], s[30:31], 0, v[144:145]
	ds_read_b128 v[180:183], v167 offset:32768
	ds_read_b128 v[184:187], v167 offset:33792
	ds_read_b128 v[188:191], v167 offset:34816
	ds_read_b128 v[192:195], v167 offset:35840
	ds_read_b128 v[196:199], v167 offset:36864
	ds_read_b128 v[200:203], v167 offset:37888
	ds_read_b128 v[204:207], v167 offset:38912
	ds_read_b128 v[208:211], v167 offset:39936
	global_load_lds_dwordx4 v[218:219], off
	v_lshl_add_u64 v[218:219], s[30:31], 0, v[146:147]
	s_mov_b32 m0, s38
	s_nop 0
	global_load_lds_dwordx4 v[218:219], off
	s_waitcnt vmcnt(8)
	s_waitcnt lgkmcnt(0)
	s_barrier
	s_setprio 1
	s_waitcnt lgkmcnt(0)
	v_mfma_f32_16x16x32_bf16 v[140:143], v[64:67], v[180:183], v[140:143]
	v_mfma_f32_16x16x32_bf16 v[136:139], v[116:119], v[180:183], v[136:139]
	v_mfma_f32_16x16x32_bf16 v[120:123], v[64:67], v[188:191], v[120:123]
	v_mfma_f32_16x16x32_bf16 v[112:115], v[116:119], v[188:191], v[112:115]
	v_mfma_f32_16x16x32_bf16 v[96:99], v[64:67], v[196:199], v[96:99]
	v_mfma_f32_16x16x32_bf16 v[92:95], v[116:119], v[196:199], v[92:95]
	v_mfma_f32_16x16x32_bf16 v[80:83], v[64:67], v[204:207], v[80:83]
	v_mfma_f32_16x16x32_bf16 v[76:79], v[116:119], v[204:207], v[76:79]
	v_mfma_f32_16x16x32_bf16 v[140:143], v[108:111], v[184:187], v[140:143]
	v_mfma_f32_16x16x32_bf16 v[136:139], v[128:131], v[184:187], v[136:139]
	v_mfma_f32_16x16x32_bf16 v[120:123], v[108:111], v[192:195], v[120:123]
	v_mfma_f32_16x16x32_bf16 v[112:115], v[128:131], v[192:195], v[112:115]
	v_mfma_f32_16x16x32_bf16 v[96:99], v[108:111], v[200:203], v[96:99]
	v_mfma_f32_16x16x32_bf16 v[92:95], v[128:131], v[200:203], v[92:95]
	v_mfma_f32_16x16x32_bf16 v[80:83], v[108:111], v[208:211], v[80:83]
	v_mfma_f32_16x16x32_bf16 v[76:79], v[128:131], v[208:211], v[76:79]
	s_setprio 0
	s_setprio 1
	v_mfma_f32_16x16x32_bf16 v[132:135], v[156:159], v[180:183], v[132:135]
	v_mfma_f32_16x16x32_bf16 v[124:127], v[172:175], v[180:183], v[124:127]
	v_mfma_f32_16x16x32_bf16 v[104:107], v[156:159], v[188:191], v[104:107]
	v_mfma_f32_16x16x32_bf16 v[100:103], v[172:175], v[188:191], v[100:103]
	v_mfma_f32_16x16x32_bf16 v[88:91], v[156:159], v[196:199], v[88:91]
	v_mfma_f32_16x16x32_bf16 v[84:87], v[172:175], v[196:199], v[84:87]
	v_mfma_f32_16x16x32_bf16 v[72:75], v[156:159], v[204:207], v[72:75]
	v_mfma_f32_16x16x32_bf16 v[68:71], v[172:175], v[204:207], v[68:71]
	v_mfma_f32_16x16x32_bf16 v[132:135], v[168:171], v[184:187], v[132:135]
	v_mfma_f32_16x16x32_bf16 v[124:127], v[176:179], v[184:187], v[124:127]
	v_mfma_f32_16x16x32_bf16 v[104:107], v[168:171], v[192:195], v[104:107]
	v_mfma_f32_16x16x32_bf16 v[100:103], v[176:179], v[192:195], v[100:103]
	v_mfma_f32_16x16x32_bf16 v[88:91], v[168:171], v[200:203], v[88:91]
	v_mfma_f32_16x16x32_bf16 v[84:87], v[176:179], v[200:203], v[84:87]
	v_mfma_f32_16x16x32_bf16 v[72:75], v[168:171], v[208:211], v[72:75]
	v_mfma_f32_16x16x32_bf16 v[68:71], v[176:179], v[208:211], v[68:71]
	s_setprio 0
	s_barrier
; #define PG8_STAGE(bufoff, gbase, voff) do { _Pragma("unroll") for (int _i = 0; _i < 2; ++_i) \
;         __builtin_amdgcn_global_load_lds((const unsigned*)((const char*)(gbase) + (voff)[_i]), (PG8_LAS unsigned*)(lds + (bufoff) + ldsw + _i * 8192), 16, 0, 0); } while (0)
; #define PG8_LDA(dst, b, h) do { _Pragma("unroll") for (int m = 0; m < 4; ++m) _Pragma("unroll") for (int k = 0; k < 2; ++k) dst[m][k] = *(const PG8_LAS bf16x8*)(lds + PG8_SA(b, h) + aoff + m * 2048 + k * 1024); } while (0)
; #define PG8_MMA(ai, bj, At, Bt) do { __builtin_amdgcn_s_setprio(1); _Pragma("unroll") for (int m = 0; m < 4; ++m) _Pragma("unroll") for (int n = 0; n < 2; ++n) _Pragma("unroll") for (int k = 0; k < 2; ++k) \
;         acc[ai][bj][m][n] = __builtin_amdgcn_mfma_f32_16x16x32_bf16(Bt[n][k], At[m][k], acc[ai][bj][m][n], 0, 0, 0); __builtin_amdgcn_s_setprio(0); } while (0)
; #define PG8_WAIT_V(n) asm volatile("s_waitcnt vmcnt(" #n ")" ::: "memory")
; #define PG8_WAIT_L(n) asm volatile("s_waitcnt lgkmcnt(" #n ")" ::: "memory")
; #define PG8_BAR __builtin_amdgcn_s_barrier()
; #define PG8_SCHED __builtin_amdgcn_sched_barrier(0)
; template <class Epi, class Sched, bool ALIGN_EPI = false, bool SP2 = false>
; __device__ __forceinline__ void gemm_phase(PG8_LAS unsigned char* lds, const Gemm g, const Sched& S, const Epi& E) {
;     ...
;         for (int t = 0; t < nt; t += 2) {
;     ...
;             PG8_LDA(At, 1, 1); PG8_STAGE(PG8_SB(1, 0), b3, voffB); PG8_STAGE(PG8_SB(1, 1), b3 + hstep, voffB); PG8_STAGE(PG8_SA(1, 0), a3, voffA);
;             PG8_WAIT_V(8); PG8_WAIT_L(0); PG8_BAR; PG8_MMA(1, 0, At, B0); PG8_MMA(1, 1, At, B1); PG8_BAR; PG8_SCHED;
	s_add_i32 s30, s56, s34
	v_lshl_add_u64 v[160:161], v[160:161], 0, s[4:5]
	s_mov_b32 m0, s30
	ds_read_b128 v[180:183], v167 offset:49152
	ds_read_b128 v[184:187], v167 offset:50176
	ds_read_b128 v[188:191], v167 offset:51200
	ds_read_b128 v[192:195], v167 offset:52224
	ds_read_b128 v[196:199], v167 offset:53248
	ds_read_b128 v[200:203], v167 offset:54272
	ds_read_b128 v[204:207], v167 offset:55296
	ds_read_b128 v[208:211], v167 offset:56320
	global_load_lds_dwordx4 v[160:161], off
	s_add_i32 m0, s30, 0x2000
	s_add_u32 s28, s28, 0x200080
	v_lshl_add_u64 v[160:161], v[212:213], 0, s[4:5]
	s_addc_u32 s29, s29, 0
	s_add_i32 s30, s57, s34
	global_load_lds_dwordx4 v[160:161], off
	v_lshl_add_u64 v[160:161], s[28:29], 0, v[144:145]
	s_mov_b32 m0, s30
	s_nop 0
	global_load_lds_dwordx4 v[160:161], off
	v_lshl_add_u64 v[160:161], s[28:29], 0, v[146:147]
	s_add_i32 m0, s30, 0x2000
	s_nop 0
	global_load_lds_dwordx4 v[160:161], off
	v_lshl_add_u64 v[160:161], v[214:215], 0, s[4:5]
	s_mov_b32 m0, s42
	s_nop 0
	global_load_lds_dwordx4 v[160:161], off
	v_lshl_add_u64 v[160:161], v[216:217], 0, s[4:5]
	s_mov_b32 m0, s43
	s_nop 0
	global_load_lds_dwordx4 v[160:161], off
	s_waitcnt vmcnt(8)
	s_waitcnt lgkmcnt(0)
	s_barrier
	s_setprio 1
	s_waitcnt lgkmcnt(0)
	v_mfma_f32_16x16x32_bf16 v[60:63], v[64:67], v[180:183], v[60:63]
	v_mfma_f32_16x16x32_bf16 v[56:59], v[116:119], v[180:183], v[56:59]
	v_mfma_f32_16x16x32_bf16 v[44:47], v[64:67], v[188:191], v[44:47]
	v_mfma_f32_16x16x32_bf16 v[40:43], v[116:119], v[188:191], v[40:43]
	v_mfma_f32_16x16x32_bf16 v[28:31], v[64:67], v[196:199], v[28:31]
	v_mfma_f32_16x16x32_bf16 v[24:27], v[116:119], v[196:199], v[24:27]
	v_mfma_f32_16x16x32_bf16 v[12:15], v[64:67], v[204:207], v[12:15]
	v_mfma_f32_16x16x32_bf16 v[8:11], v[116:119], v[204:207], v[8:11]
	v_mfma_f32_16x16x32_bf16 v[60:63], v[108:111], v[184:187], v[60:63]
	v_mfma_f32_16x16x32_bf16 v[56:59], v[128:131], v[184:187], v[56:59]
	v_mfma_f32_16x16x32_bf16 v[44:47], v[108:111], v[192:195], v[44:47]
	v_mfma_f32_16x16x32_bf16 v[40:43], v[128:131], v[192:195], v[40:43]
	v_mfma_f32_16x16x32_bf16 v[28:31], v[108:111], v[200:203], v[28:31]
	v_mfma_f32_16x16x32_bf16 v[24:27], v[128:131], v[200:203], v[24:27]
	v_mfma_f32_16x16x32_bf16 v[12:15], v[108:111], v[208:211], v[12:15]
	v_mfma_f32_16x16x32_bf16 v[8:11], v[128:131], v[208:211], v[8:11]
	s_setprio 0
	s_setprio 1
	v_mfma_f32_16x16x32_bf16 v[52:55], v[156:159], v[180:183], v[52:55]
	v_mfma_f32_16x16x32_bf16 v[48:51], v[172:175], v[180:183], v[48:51]
	v_mfma_f32_16x16x32_bf16 v[36:39], v[156:159], v[188:191], v[36:39]
	v_mfma_f32_16x16x32_bf16 v[32:35], v[172:175], v[188:191], v[32:35]
	v_mfma_f32_16x16x32_bf16 v[20:23], v[156:159], v[196:199], v[20:23]
	v_mfma_f32_16x16x32_bf16 v[16:19], v[172:175], v[196:199], v[16:19]
	v_mfma_f32_16x16x32_bf16 v[4:7], v[156:159], v[204:207], v[4:7]
	v_mfma_f32_16x16x32_bf16 v[0:3], v[172:175], v[204:207], v[0:3]
	v_mfma_f32_16x16x32_bf16 v[52:55], v[168:171], v[184:187], v[52:55]
	v_mfma_f32_16x16x32_bf16 v[48:51], v[176:179], v[184:187], v[48:51]
	v_mfma_f32_16x16x32_bf16 v[36:39], v[168:171], v[192:195], v[36:39]
	v_mfma_f32_16x16x32_bf16 v[32:35], v[176:179], v[192:195], v[32:35]
	v_mfma_f32_16x16x32_bf16 v[20:23], v[168:171], v[200:203], v[20:23]
	v_mfma_f32_16x16x32_bf16 v[16:19], v[176:179], v[200:203], v[16:19]
	v_mfma_f32_16x16x32_bf16 v[4:7], v[168:171], v[208:211], v[4:7]
	v_mfma_f32_16x16x32_bf16 v[0:3], v[176:179], v[208:211], v[0:3]
	s_setprio 0
	s_add_i32 s55, s55, 2
	s_add_u32 s26, s26, 0x100
	s_addc_u32 s27, s27, 0
	s_add_u32 s53, s53, 0x100
	s_addc_u32 s54, s54, 0
	s_cmpk_gt_u32 s55, 0x7d

; #define PG8_STAGE(bufoff, gbase, voff) do { _Pragma("unroll") for (int _i = 0; _i < 2; ++_i) \
;         __builtin_amdgcn_global_load_lds((const unsigned*)((const char*)(gbase) + (voff)[_i]), (PG8_LAS unsigned*)(lds + (bufoff) + ldsw + _i * 8192), 16, 0, 0); } while (0)
; #define PG8_LDA(dst, b, h) do { _Pragma("unroll") for (int m = 0; m < 4; ++m) _Pragma("unroll") for (int k = 0; k < 2; ++k) dst[m][k] = *(const PG8_LAS bf16x8*)(lds + PG8_SA(b, h) + aoff + m * 2048 + k * 1024); } while (0)
; #define PG8_LDB(dst, b, h) do { _Pragma("unroll") for (int n = 0; n < 2; ++n) _Pragma("unroll") for (int k = 0; k < 2; ++k) dst[n][k] = *(const PG8_LAS bf16x8*)(lds + PG8_SB(b, h) + boff + n * 2048 + k * 1024); } while (0)
; #define PG8_MMA(ai, bj, At, Bt) do { __builtin_amdgcn_s_setprio(1); _Pragma("unroll") for (int m = 0; m < 4; ++m) _Pragma("unroll") for (int n = 0; n < 2; ++n) _Pragma("unroll") for (int k = 0; k < 2; ++k) \
;         acc[ai][bj][m][n] = __builtin_amdgcn_mfma_f32_16x16x32_bf16(Bt[n][k], At[m][k], acc[ai][bj][m][n], 0, 0, 0); __builtin_amdgcn_s_setprio(0); } while (0)
; #define PG8_WAIT_V(n) asm volatile("s_waitcnt vmcnt(" #n ")" ::: "memory")
; #define PG8_WAIT_L(n) asm volatile("s_waitcnt lgkmcnt(" #n ")" ::: "memory")
; #define PG8_BAR __builtin_amdgcn_s_barrier()
; #define PG8_SCHED __builtin_amdgcn_sched_barrier(0)
; template <class Epi, class Sched, bool ALIGN_EPI = false, bool SP2 = false>
; __device__ __forceinline__ void gemm_phase(PG8_LAS unsigned char* lds, const Gemm g, const Sched& S, const Epi& E) {
;     ...
;             PG8_LDB(B0, 0, 0); PG8_LDB(B1, 0, 1); PG8_SCHED; PG8_LDA(At, 0, 0); PG8_STAGE(PG8_SA(1, 1), a1 + hstep, voffA);
;             PG8_WAIT_V(8); PG8_WAIT_L(0); PG8_BAR; PG8_MMA(0, 0, At, B0); PG8_MMA(0, 1, At, B1); PG8_BAR; PG8_SCHED;
;             PG8_LDA(At, 0, 1); PG8_STAGE(PG8_SB(0, 0), b2, voffB); PG8_STAGE(PG8_SB(0, 1), b2 + hstep, voffB); PG8_STAGE(PG8_SA(0, 0), a2, voffA);
;             PG8_WAIT_V(8); PG8_WAIT_L(0); PG8_BAR; PG8_MMA(1, 0, At, B0); PG8_MMA(1, 1, At, B1); PG8_BAR; PG8_SCHED;
.LBB0_1071:
	ds_read_b128 v[64:67], v165
	ds_read_b128 v[108:111], v165 offset:1024
	ds_read_b128 v[116:119], v165 offset:2048
	ds_read_b128 v[128:131], v165 offset:3072
	ds_read_b128 v[156:159], v166
	ds_read_b128 v[168:171], v166 offset:1024
	ds_read_b128 v[172:175], v166 offset:2048
	ds_read_b128 v[176:179], v166 offset:3072
	s_add_u32 s28, s26, 0xffe00080
	s_addc_u32 s29, s27, -1
	s_cmpk_eq_i32 s55, 0x7c
	s_cselect_b32 s31, s19, s29
	s_cselect_b32 s30, s51, s28
	s_cselect_b32 s29, s17, s54
	s_cselect_b32 s28, s52, s53
	v_lshl_add_u64 v[160:161], s[26:27], 0, v[148:149]
	s_add_i32 m0, s35, 0xc000
	ds_read_b128 v[180:183], v167
	ds_read_b128 v[184:187], v167 offset:1024
	ds_read_b128 v[188:191], v167 offset:2048
	ds_read_b128 v[192:195], v167 offset:3072
	ds_read_b128 v[196:199], v167 offset:4096
	ds_read_b128 v[200:203], v167 offset:5120
	ds_read_b128 v[204:207], v167 offset:6144
	ds_read_b128 v[208:211], v167 offset:7168
	global_load_lds_dwordx4 v[160:161], off
	v_lshl_add_u64 v[160:161], s[26:27], 0, v[150:151]
	s_add_i32 m0, s35, 0xe000
	s_nop 0
	global_load_lds_dwordx4 v[160:161], off
	s_waitcnt vmcnt(8)
	s_waitcnt lgkmcnt(0)
	s_barrier
	s_setprio 1
	s_waitcnt lgkmcnt(0)
	v_mfma_f32_16x16x32_bf16 v[140:143], v[64:67], v[180:183], v[140:143]
	v_mfma_f32_16x16x32_bf16 v[136:139], v[116:119], v[180:183], v[136:139]
	v_mfma_f32_16x16x32_bf16 v[120:123], v[64:67], v[188:191], v[120:123]
	v_mfma_f32_16x16x32_bf16 v[112:115], v[116:119], v[188:191], v[112:115]
	v_mfma_f32_16x16x32_bf16 v[96:99], v[64:67], v[196:199], v[96:99]
	v_mfma_f32_16x16x32_bf16 v[92:95], v[116:119], v[196:199], v[92:95]
	v_mfma_f32_16x16x32_bf16 v[80:83], v[64:67], v[204:207], v[80:83]
	v_mfma_f32_16x16x32_bf16 v[76:79], v[116:119], v[204:207], v[76:79]
	v_mfma_f32_16x16x32_bf16 v[140:143], v[108:111], v[184:187], v[140:143]
	v_mfma_f32_16x16x32_bf16 v[136:139], v[128:131], v[184:187], v[136:139]
	v_mfma_f32_16x16x32_bf16 v[120:123], v[108:111], v[192:195], v[120:123]
	v_mfma_f32_16x16x32_bf16 v[112:115], v[128:131], v[192:195], v[112:115]
	v_mfma_f32_16x16x32_bf16 v[96:99], v[108:111], v[200:203], v[96:99]
	v_mfma_f32_16x16x32_bf16 v[92:95], v[128:131], v[200:203], v[92:95]
	v_mfma_f32_16x16x32_bf16 v[80:83], v[108:111], v[208:211], v[80:83]
	v_mfma_f32_16x16x32_bf16 v[76:79], v[128:131], v[208:211], v[76:79]
	s_setprio 0
	s_setprio 1
	v_mfma_f32_16x16x32_bf16 v[132:135], v[156:159], v[180:183], v[132:135]
	v_mfma_f32_16x16x32_bf16 v[124:127], v[172:175], v[180:183], v[124:127]
	v_mfma_f32_16x16x32_bf16 v[104:107], v[156:159], v[188:191], v[104:107]
	v_mfma_f32_16x16x32_bf16 v[100:103], v[172:175], v[188:191], v[100:103]
	v_mfma_f32_16x16x32_bf16 v[88:91], v[156:159], v[196:199], v[88:91]
	v_mfma_f32_16x16x32_bf16 v[84:87], v[172:175], v[196:199], v[84:87]
	v_mfma_f32_16x16x32_bf16 v[72:75], v[156:159], v[204:207], v[72:75]
	v_mfma_f32_16x16x32_bf16 v[68:71], v[172:175], v[204:207], v[68:71]
	v_mfma_f32_16x16x32_bf16 v[132:135], v[168:171], v[184:187], v[132:135]
	v_mfma_f32_16x16x32_bf16 v[124:127], v[176:179], v[184:187], v[124:127]
	v_mfma_f32_16x16x32_bf16 v[104:107], v[168:171], v[192:195], v[104:107]
	v_mfma_f32_16x16x32_bf16 v[100:103], v[176:179], v[192:195], v[100:103]
	v_mfma_f32_16x16x32_bf16 v[88:91], v[168:171], v[200:203], v[88:91]
	v_mfma_f32_16x16x32_bf16 v[84:87], v[176:179], v[200:203], v[84:87]
	v_mfma_f32_16x16x32_bf16 v[72:75], v[168:171], v[208:211], v[72:75]
	v_mfma_f32_16x16x32_bf16 v[68:71], v[176:179], v[208:211], v[68:71]
	s_setprio 0
	s_barrier
	s_add_i32 s56, s45, s34
	v_lshl_add_u64 v[160:161], s[28:29], 0, v[144:145]
	s_mov_b32 m0, s56
	ds_read_b128 v[180:183], v167 offset:16384
	ds_read_b128 v[184:187], v167 offset:17408
	ds_read_b128 v[188:191], v167 offset:18432
	ds_read_b128 v[192:195], v167 offset:19456
	ds_read_b128 v[196:199], v167 offset:20480
	ds_read_b128 v[200:203], v167 offset:21504
	ds_read_b128 v[204:207], v167 offset:22528
	ds_read_b128 v[208:211], v167 offset:23552
	global_load_lds_dwordx4 v[160:161], off
	s_add_i32 m0, s56, 0x2000
	s_add_u32 s56, s28, 0x200000
	v_lshl_add_u64 v[212:213], s[28:29], 0, v[146:147]
	s_addc_u32 s57, s29, 0
	s_add_i32 s58, s46, s34
	global_load_lds_dwordx4 v[212:213], off
	v_lshl_add_u64 v[214:215], s[56:57], 0, v[144:145]
	s_mov_b32 m0, s58
	v_lshl_add_u64 v[216:217], s[30:31], 0, v[146:147]
	global_load_lds_dwordx4 v[214:215], off
	v_lshl_add_u64 v[214:215], s[56:57], 0, v[146:147]
	s_add_i32 m0, s58, 0x2000
	s_nop 0
	global_load_lds_dwordx4 v[214:215], off
	v_lshl_add_u64 v[214:215], s[30:31], 0, v[144:145]
	s_mov_b32 m0, s35
	s_nop 0
	global_load_lds_dwordx4 v[214:215], off
	s_mov_b32 m0, s36
	s_nop 0
	global_load_lds_dwordx4 v[216:217], off
	s_waitcnt vmcnt(8)
	s_waitcnt lgkmcnt(0)
	s_barrier
; #define PG8_STAGE(bufoff, gbase, voff) do { _Pragma("unroll") for (int _i = 0; _i < 2; ++_i) \
;         __builtin_amdgcn_global_load_lds((const unsigned*)((const char*)(gbase) + (voff)[_i]), (PG8_LAS unsigned*)(lds + (bufoff) + ldsw + _i * 8192), 16, 0, 0); } while (0)
; #define PG8_LDA(dst, b, h) do { _Pragma("unroll") for (int m = 0; m < 4; ++m) _Pragma("unroll") for (int k = 0; k < 2; ++k) dst[m][k] = *(const PG8_LAS bf16x8*)(lds + PG8_SA(b, h) + aoff + m * 2048 + k * 1024); } while (0)
; #define PG8_LDB(dst, b, h) do { _Pragma("unroll") for (int n = 0; n < 2; ++n) _Pragma("unroll") for (int k = 0; k < 2; ++k) dst[n][k] = *(const PG8_LAS bf16x8*)(lds + PG8_SB(b, h) + boff + n * 2048 + k * 1024); } while (0)
; #define PG8_MMA(ai, bj, At, Bt) do { __builtin_amdgcn_s_setprio(1); _Pragma("unroll") for (int m = 0; m < 4; ++m) _Pragma("unroll") for (int n = 0; n < 2; ++n) _Pragma("unroll") for (int k = 0; k < 2; ++k) \
;         acc[ai][bj][m][n] = __builtin_amdgcn_mfma_f32_16x16x32_bf16(Bt[n][k], At[m][k], acc[ai][bj][m][n], 0, 0, 0); __builtin_amdgcn_s_setprio(0); } while (0)
; #define PG8_WAIT_V(n) asm volatile("s_waitcnt vmcnt(" #n ")" ::: "memory")
; #define PG8_WAIT_L(n) asm volatile("s_waitcnt lgkmcnt(" #n ")" ::: "memory")
; #define PG8_BAR __builtin_amdgcn_s_barrier()
; #define PG8_SCHED __builtin_amdgcn_sched_barrier(0)
; template <class Epi, class Sched, bool ALIGN_EPI = false, bool SP2 = false>
; __device__ __forceinline__ void gemm_phase(PG8_LAS unsigned char* lds, const Gemm g, const Sched& S, const Epi& E) {
;     ...
;             PG8_WAIT_V(8); PG8_WAIT_L(0); PG8_BAR; PG8_MMA(1, 0, At, B0); PG8_MMA(1, 1, At, B1); PG8_BAR; PG8_SCHED;
;             PG8_LDB(B0, 1, 0); PG8_LDB(B1, 1, 1); PG8_SCHED; PG8_LDA(At, 1, 0); PG8_STAGE(PG8_SA(0, 1), a2 + hstep, voffA);
;             PG8_WAIT_V(8); PG8_WAIT_L(0); PG8_BAR; PG8_MMA(0, 0, At, B0); PG8_MMA(0, 1, At, B1); PG8_BAR; PG8_SCHED;
	s_setprio 1
	s_waitcnt lgkmcnt(0)
	v_mfma_f32_16x16x32_bf16 v[60:63], v[64:67], v[180:183], v[60:63]
	v_mfma_f32_16x16x32_bf16 v[56:59], v[116:119], v[180:183], v[56:59]
	v_mfma_f32_16x16x32_bf16 v[44:47], v[64:67], v[188:191], v[44:47]
	v_mfma_f32_16x16x32_bf16 v[40:43], v[116:119], v[188:191], v[40:43]
	v_mfma_f32_16x16x32_bf16 v[28:31], v[64:67], v[196:199], v[28:31]
	v_mfma_f32_16x16x32_bf16 v[24:27], v[116:119], v[196:199], v[24:27]
	v_mfma_f32_16x16x32_bf16 v[12:15], v[64:67], v[204:207], v[12:15]
	v_mfma_f32_16x16x32_bf16 v[8:11], v[116:119], v[204:207], v[8:11]
	v_mfma_f32_16x16x32_bf16 v[60:63], v[108:111], v[184:187], v[60:63]
	v_mfma_f32_16x16x32_bf16 v[56:59], v[128:131], v[184:187], v[56:59]
	v_mfma_f32_16x16x32_bf16 v[44:47], v[108:111], v[192:195], v[44:47]
	v_mfma_f32_16x16x32_bf16 v[40:43], v[128:131], v[192:195], v[40:43]
	v_mfma_f32_16x16x32_bf16 v[28:31], v[108:111], v[200:203], v[28:31]
	v_mfma_f32_16x16x32_bf16 v[24:27], v[128:131], v[200:203], v[24:27]
	v_mfma_f32_16x16x32_bf16 v[12:15], v[108:111], v[208:211], v[12:15]
	v_mfma_f32_16x16x32_bf16 v[8:11], v[128:131], v[208:211], v[8:11]
	s_setprio 0
	s_setprio 1
	v_mfma_f32_16x16x32_bf16 v[52:55], v[156:159], v[180:183], v[52:55]
	v_mfma_f32_16x16x32_bf16 v[48:51], v[172:175], v[180:183], v[48:51]
	v_mfma_f32_16x16x32_bf16 v[36:39], v[156:159], v[188:191], v[36:39]
	v_mfma_f32_16x16x32_bf16 v[32:35], v[172:175], v[188:191], v[32:35]
	v_mfma_f32_16x16x32_bf16 v[20:23], v[156:159], v[196:199], v[20:23]
	v_mfma_f32_16x16x32_bf16 v[16:19], v[172:175], v[196:199], v[16:19]
	v_mfma_f32_16x16x32_bf16 v[4:7], v[156:159], v[204:207], v[4:7]
	v_mfma_f32_16x16x32_bf16 v[0:3], v[172:175], v[204:207], v[0:3]
	v_mfma_f32_16x16x32_bf16 v[52:55], v[168:171], v[184:187], v[52:55]
	v_mfma_f32_16x16x32_bf16 v[48:51], v[176:179], v[184:187], v[48:51]
	v_mfma_f32_16x16x32_bf16 v[36:39], v[168:171], v[192:195], v[36:39]
	v_mfma_f32_16x16x32_bf16 v[32:35], v[176:179], v[192:195], v[32:35]
	v_mfma_f32_16x16x32_bf16 v[20:23], v[168:171], v[200:203], v[20:23]
	v_mfma_f32_16x16x32_bf16 v[16:19], v[176:179], v[200:203], v[16:19]
	v_mfma_f32_16x16x32_bf16 v[4:7], v[168:171], v[208:211], v[4:7]
	v_mfma_f32_16x16x32_bf16 v[0:3], v[176:179], v[208:211], v[0:3]
	s_setprio 0
	s_barrier
	s_add_i32 s56, 0, 0x18000
	s_add_i32 s57, 0, 0x1c000
	v_add_u32_e32 v128, s56, v163
	v_add_u32_e32 v176, s57, v163
	ds_read_b128 v[64:67], v128
	ds_read_b128 v[108:111], v128 offset:1024
	ds_read_b128 v[116:119], v128 offset:2048
	ds_read_b128 v[128:131], v128 offset:3072
	ds_read_b128 v[156:159], v176
	ds_read_b128 v[168:171], v176 offset:1024
	ds_read_b128 v[172:175], v176 offset:2048
	ds_read_b128 v[176:179], v176 offset:3072
	s_add_u32 s30, s30, 0x200000
	s_addc_u32 s31, s31, 0
	s_mov_b32 m0, s37
	v_lshl_add_u64 v[218:219], s[30:31], 0, v[144:145]
	ds_read_b128 v[180:183], v167 offset:32768
	ds_read_b128 v[184:187], v167 offset:33792
	ds_read_b128 v[188:191], v167 offset:34816
	ds_read_b128 v[192:195], v167 offset:35840
	ds_read_b128 v[196:199], v167 offset:36864
	ds_read_b128 v[200:203], v167 offset:37888
	ds_read_b128 v[204:207], v167 offset:38912
	ds_read_b128 v[208:211], v167 offset:39936
	global_load_lds_dwordx4 v[218:219], off
	v_lshl_add_u64 v[218:219], s[30:31], 0, v[146:147]
	s_mov_b32 m0, s38
	s_nop 0
	global_load_lds_dwordx4 v[218:219], off
	s_waitcnt vmcnt(8)
	s_waitcnt lgkmcnt(0)
	s_barrier
	s_setprio 1
	s_waitcnt lgkmcnt(0)
	v_mfma_f32_16x16x32_bf16 v[140:143], v[64:67], v[180:183], v[140:143]
	v_mfma_f32_16x16x32_bf16 v[136:139], v[116:119], v[180:183], v[136:139]
	v_mfma_f32_16x16x32_bf16 v[120:123], v[64:67], v[188:191], v[120:123]
	v_mfma_f32_16x16x32_bf16 v[112:115], v[116:119], v[188:191], v[112:115]
	v_mfma_f32_16x16x32_bf16 v[96:99], v[64:67], v[196:199], v[96:99]
	v_mfma_f32_16x16x32_bf16 v[92:95], v[116:119], v[196:199], v[92:95]
	v_mfma_f32_16x16x32_bf16 v[80:83], v[64:67], v[204:207], v[80:83]
	v_mfma_f32_16x16x32_bf16 v[76:79], v[116:119], v[204:207], v[76:79]
	v_mfma_f32_16x16x32_bf16 v[140:143], v[108:111], v[184:187], v[140:143]
	v_mfma_f32_16x16x32_bf16 v[136:139], v[128:131], v[184:187], v[136:139]
	v_mfma_f32_16x16x32_bf16 v[120:123], v[108:111], v[192:195], v[120:123]
	v_mfma_f32_16x16x32_bf16 v[112:115], v[128:131], v[192:195], v[112:115]
	v_mfma_f32_16x16x32_bf16 v[96:99], v[108:111], v[200:203], v[96:99]
	v_mfma_f32_16x16x32_bf16 v[92:95], v[128:131], v[200:203], v[92:95]
	v_mfma_f32_16x16x32_bf16 v[80:83], v[108:111], v[208:211], v[80:83]
	v_mfma_f32_16x16x32_bf16 v[76:79], v[128:131], v[208:211], v[76:79]
	s_setprio 0
	s_setprio 1
	v_mfma_f32_16x16x32_bf16 v[132:135], v[156:159], v[180:183], v[132:135]
	v_mfma_f32_16x16x32_bf16 v[124:127], v[172:175], v[180:183], v[124:127]
	v_mfma_f32_16x16x32_bf16 v[104:107], v[156:159], v[188:191], v[104:107]
	v_mfma_f32_16x16x32_bf16 v[100:103], v[172:175], v[188:191], v[100:103]
	v_mfma_f32_16x16x32_bf16 v[88:91], v[156:159], v[196:199], v[88:91]
	v_mfma_f32_16x16x32_bf16 v[84:87], v[172:175], v[196:199], v[84:87]
	v_mfma_f32_16x16x32_bf16 v[72:75], v[156:159], v[204:207], v[72:75]
	v_mfma_f32_16x16x32_bf16 v[68:71], v[172:175], v[204:207], v[68:71]
	v_mfma_f32_16x16x32_bf16 v[132:135], v[168:171], v[184:187], v[132:135]
	v_mfma_f32_16x16x32_bf16 v[124:127], v[176:179], v[184:187], v[124:127]
	v_mfma_f32_16x16x32_bf16 v[104:107], v[168:171], v[192:195], v[104:107]
	v_mfma_f32_16x16x32_bf16 v[100:103], v[176:179], v[192:195], v[100:103]
	v_mfma_f32_16x16x32_bf16 v[88:91], v[168:171], v[200:203], v[88:91]
	v_mfma_f32_16x16x32_bf16 v[84:87], v[176:179], v[200:203], v[84:87]
	v_mfma_f32_16x16x32_bf16 v[72:75], v[168:171], v[208:211], v[72:75]
	v_mfma_f32_16x16x32_bf16 v[68:71], v[176:179], v[208:211], v[68:71]
	s_setprio 0
	s_barrier
; #define PG8_STAGE(bufoff, gbase, voff) do { _Pragma("unroll") for (int _i = 0; _i < 2; ++_i) \
;         __builtin_amdgcn_global_load_lds((const unsigned*)((const char*)(gbase) + (voff)[_i]), (PG8_LAS unsigned*)(lds + (bufoff) + ldsw + _i * 8192), 16, 0, 0); } while (0)
; #define PG8_LDA(dst, b, h) do { _Pragma("unroll") for (int m = 0; m < 4; ++m) _Pragma("unroll") for (int k = 0; k < 2; ++k) dst[m][k] = *(const PG8_LAS bf16x8*)(lds + PG8_SA(b, h) + aoff + m * 2048 + k * 1024); } while (0)
; #define PG8_MMA(ai, bj, At, Bt) do { __builtin_amdgcn_s_setprio(1); _Pragma("unroll") for (int m = 0; m < 4; ++m) _Pragma("unroll") for (int n = 0; n < 2; ++n) _Pragma("unroll") for (int k = 0; k < 2; ++k) \
;         acc[ai][bj][m][n] = __builtin_amdgcn_mfma_f32_16x16x32_bf16(Bt[n][k], At[m][k], acc[ai][bj][m][n], 0, 0, 0); __builtin_amdgcn_s_setprio(0); } while (0)
; #define PG8_WAIT_V(n) asm volatile("s_waitcnt vmcnt(" #n ")" ::: "memory")
; #define PG8_WAIT_L(n) asm volatile("s_waitcnt lgkmcnt(" #n ")" ::: "memory")
; #define PG8_BAR __builtin_amdgcn_s_barrier()
; #define PG8_SCHED __builtin_amdgcn_sched_barrier(0)
; template <class Epi, class Sched, bool ALIGN_EPI = false, bool SP2 = false>
; __device__ __forceinline__ void gemm_phase(PG8_LAS unsigned char* lds, const Gemm g, const Sched& S, const Epi& E) {
;     ...
;         for (int t = 0; t < nt; t += 2) {
;     ...
;             PG8_LDA(At, 1, 1); PG8_STAGE(PG8_SB(1, 0), b3, voffB); PG8_STAGE(PG8_SB(1, 1), b3 + hstep, voffB); PG8_STAGE(PG8_SA(1, 0), a3, voffA);
;             PG8_WAIT_V(8); PG8_WAIT_L(0); PG8_BAR; PG8_MMA(1, 0, At, B0); PG8_MMA(1, 1, At, B1); PG8_BAR; PG8_SCHED;
;     ...
;         if constexpr (ALIGN_EPI) { if (wr == 0) PG8_BAR; }
	s_add_i32 s30, s56, s34
	v_lshl_add_u64 v[160:161], v[160:161], 0, s[4:5]
	s_mov_b32 m0, s30
	ds_read_b128 v[180:183], v167 offset:49152
	ds_read_b128 v[184:187], v167 offset:50176
	ds_read_b128 v[188:191], v167 offset:51200
	ds_read_b128 v[192:195], v167 offset:52224
	ds_read_b128 v[196:199], v167 offset:53248
	ds_read_b128 v[200:203], v167 offset:54272
	ds_read_b128 v[204:207], v167 offset:55296
	ds_read_b128 v[208:211], v167 offset:56320
	global_load_lds_dwordx4 v[160:161], off
	s_add_i32 m0, s30, 0x2000
	s_add_u32 s28, s28, 0x200080
	v_lshl_add_u64 v[160:161], v[212:213], 0, s[4:5]
	s_addc_u32 s29, s29, 0
	s_add_i32 s30, s57, s34
	global_load_lds_dwordx4 v[160:161], off
	v_lshl_add_u64 v[160:161], s[28:29], 0, v[144:145]
	s_mov_b32 m0, s30
	s_nop 0
	global_load_lds_dwordx4 v[160:161], off
	v_lshl_add_u64 v[160:161], s[28:29], 0, v[146:147]
	s_add_i32 m0, s30, 0x2000
	s_nop 0
	global_load_lds_dwordx4 v[160:161], off
	v_lshl_add_u64 v[160:161], v[214:215], 0, s[4:5]
	s_mov_b32 m0, s42
	s_nop 0
	global_load_lds_dwordx4 v[160:161], off
	v_lshl_add_u64 v[160:161], v[216:217], 0, s[4:5]
	s_mov_b32 m0, s43
	s_nop 0
	global_load_lds_dwordx4 v[160:161], off
	s_waitcnt vmcnt(8)
	s_waitcnt lgkmcnt(0)
	s_barrier
	s_setprio 1
	s_waitcnt lgkmcnt(0)
	v_mfma_f32_16x16x32_bf16 v[60:63], v[64:67], v[180:183], v[60:63]
	v_mfma_f32_16x16x32_bf16 v[56:59], v[116:119], v[180:183], v[56:59]
	v_mfma_f32_16x16x32_bf16 v[44:47], v[64:67], v[188:191], v[44:47]
	v_mfma_f32_16x16x32_bf16 v[40:43], v[116:119], v[188:191], v[40:43]
	v_mfma_f32_16x16x32_bf16 v[28:31], v[64:67], v[196:199], v[28:31]
	v_mfma_f32_16x16x32_bf16 v[24:27], v[116:119], v[196:199], v[24:27]
	v_mfma_f32_16x16x32_bf16 v[12:15], v[64:67], v[204:207], v[12:15]
	v_mfma_f32_16x16x32_bf16 v[8:11], v[116:119], v[204:207], v[8:11]
	v_mfma_f32_16x16x32_bf16 v[60:63], v[108:111], v[184:187], v[60:63]
	v_mfma_f32_16x16x32_bf16 v[56:59], v[128:131], v[184:187], v[56:59]
	v_mfma_f32_16x16x32_bf16 v[44:47], v[108:111], v[192:195], v[44:47]
	v_mfma_f32_16x16x32_bf16 v[40:43], v[128:131], v[192:195], v[40:43]
	v_mfma_f32_16x16x32_bf16 v[28:31], v[108:111], v[200:203], v[28:31]
	v_mfma_f32_16x16x32_bf16 v[24:27], v[128:131], v[200:203], v[24:27]
	v_mfma_f32_16x16x32_bf16 v[12:15], v[108:111], v[208:211], v[12:15]
	v_mfma_f32_16x16x32_bf16 v[8:11], v[128:131], v[208:211], v[8:11]
	s_setprio 0
	s_setprio 1
	v_mfma_f32_16x16x32_bf16 v[52:55], v[156:159], v[180:183], v[52:55]
	v_mfma_f32_16x16x32_bf16 v[48:51], v[172:175], v[180:183], v[48:51]
	v_mfma_f32_16x16x32_bf16 v[36:39], v[156:159], v[188:191], v[36:39]
	v_mfma_f32_16x16x32_bf16 v[32:35], v[172:175], v[188:191], v[32:35]
	v_mfma_f32_16x16x32_bf16 v[20:23], v[156:159], v[196:199], v[20:23]
	v_mfma_f32_16x16x32_bf16 v[16:19], v[172:175], v[196:199], v[16:19]
	v_mfma_f32_16x16x32_bf16 v[4:7], v[156:159], v[204:207], v[4:7]
	v_mfma_f32_16x16x32_bf16 v[0:3], v[172:175], v[204:207], v[0:3]
	v_mfma_f32_16x16x32_bf16 v[52:55], v[168:171], v[184:187], v[52:55]
	v_mfma_f32_16x16x32_bf16 v[48:51], v[176:179], v[184:187], v[48:51]
	v_mfma_f32_16x16x32_bf16 v[36:39], v[168:171], v[192:195], v[36:39]
	v_mfma_f32_16x16x32_bf16 v[32:35], v[176:179], v[192:195], v[32:35]
	v_mfma_f32_16x16x32_bf16 v[20:23], v[168:171], v[200:203], v[20:23]
	v_mfma_f32_16x16x32_bf16 v[16:19], v[176:179], v[200:203], v[16:19]
	v_mfma_f32_16x16x32_bf16 v[4:7], v[168:171], v[208:211], v[4:7]
	v_mfma_f32_16x16x32_bf16 v[0:3], v[176:179], v[208:211], v[0:3]
	s_setprio 0
	s_add_i32 s55, s55, 2
	s_add_u32 s26, s26, 0x100
	s_addc_u32 s27, s27, 0
	s_add_u32 s53, s53, 0x100
	s_addc_u32 s54, s54, 0
	s_cmpk_gt_u32 s55, 0x7d
	s_cbranch_scc0 .Lrot_1071
	s_barrier
	s_and_b64 vcc, exec, s[6:7]
	s_cbranch_vccz .LBB0_1074
	s_barrier
